# O9S with every s_setprio removed from the 10 K-loops (80 instructions)
# baseline (speedup 1.0000x reference)
.LBB0_170:
	ds_read_b128 v[136:139], v191
	ds_read_b128 v[158:161], v191 offset:1024
	ds_read_b128 v[162:165], v191 offset:2048
	ds_read_b128 v[166:169], v191 offset:3072
	ds_read_b128 v[170:173], v192
	ds_read_b128 v[174:177], v192 offset:1024
	ds_read_b128 v[178:181], v192 offset:2048
	ds_read_b128 v[194:197], v192 offset:3072
	s_add_u32 s0, s42, 0xfff00080
	s_addc_u32 s50, s43, -1
	s_cmp_eq_u32 s70, 60
	s_cselect_b32 s53, s23, s50
	s_cselect_b32 s52, s41, s0
	s_cselect_b32 s51, s21, s68
	s_cselect_b32 s50, s66, s67
	s_add_i32 m0, s31, 0xc000
	ds_read_b128 v[198:201], v193
	ds_read_b128 v[202:205], v193 offset:1024
	ds_read_b128 v[206:209], v193 offset:2048
	ds_read_b128 v[210:213], v193 offset:3072
	ds_read_b128 v[214:217], v193 offset:4096
	ds_read_b128 v[218:221], v193 offset:5120
	ds_read_b128 v[222:225], v193 offset:6144
	ds_read_b128 v[226:229], v193 offset:7168
	global_load_lds_dwordx4 v152, s[42:43]
	s_add_i32 m0, s31, 0xe000
	s_nop 0
	global_load_lds_dwordx4 v154, s[42:43]
	s_waitcnt vmcnt(8)
	s_waitcnt lgkmcnt(0)
	s_barrier
	v_mfma_f32_16x16x32_bf16 v[132:135], v[136:139], v[198:201], v[132:135]
	v_mfma_f32_16x16x32_bf16 v[132:135], v[158:161], v[202:205], v[132:135]
	v_mfma_f32_16x16x32_bf16 v[128:131], v[162:165], v[198:201], v[128:131]
	v_mfma_f32_16x16x32_bf16 v[128:131], v[166:169], v[202:205], v[128:131]
	v_mfma_f32_16x16x32_bf16 v[124:127], v[170:173], v[198:201], v[124:127]
	v_mfma_f32_16x16x32_bf16 v[124:127], v[174:177], v[202:205], v[124:127]
	v_mfma_f32_16x16x32_bf16 v[120:123], v[178:181], v[198:201], v[120:123]
	v_mfma_f32_16x16x32_bf16 v[120:123], v[194:197], v[202:205], v[120:123]
	v_mfma_f32_16x16x32_bf16 v[104:107], v[178:181], v[206:209], v[104:107]
	v_mfma_f32_16x16x32_bf16 v[104:107], v[194:197], v[210:213], v[104:107]
	v_mfma_f32_16x16x32_bf16 v[108:111], v[170:173], v[206:209], v[108:111]
	v_mfma_f32_16x16x32_bf16 v[108:111], v[174:177], v[210:213], v[108:111]
	v_mfma_f32_16x16x32_bf16 v[112:115], v[162:165], v[206:209], v[112:115]
	v_mfma_f32_16x16x32_bf16 v[112:115], v[166:169], v[210:213], v[112:115]
	v_mfma_f32_16x16x32_bf16 v[116:119], v[136:139], v[206:209], v[116:119]
	v_mfma_f32_16x16x32_bf16 v[116:119], v[158:161], v[210:213], v[116:119]
	v_mfma_f32_16x16x32_bf16 v[100:103], v[136:139], v[214:217], v[100:103]
	v_mfma_f32_16x16x32_bf16 v[100:103], v[158:161], v[218:221], v[100:103]
	v_mfma_f32_16x16x32_bf16 v[96:99], v[162:165], v[214:217], v[96:99]
	v_mfma_f32_16x16x32_bf16 v[96:99], v[166:169], v[218:221], v[96:99]
	v_mfma_f32_16x16x32_bf16 v[92:95], v[170:173], v[214:217], v[92:95]
	v_mfma_f32_16x16x32_bf16 v[92:95], v[174:177], v[218:221], v[92:95]
	v_mfma_f32_16x16x32_bf16 v[88:91], v[178:181], v[214:217], v[88:91]
	v_mfma_f32_16x16x32_bf16 v[88:91], v[194:197], v[218:221], v[88:91]
	v_mfma_f32_16x16x32_bf16 v[72:75], v[178:181], v[222:225], v[72:75]
	v_mfma_f32_16x16x32_bf16 v[72:75], v[194:197], v[226:229], v[72:75]
	v_mfma_f32_16x16x32_bf16 v[76:79], v[170:173], v[222:225], v[76:79]
	v_mfma_f32_16x16x32_bf16 v[76:79], v[174:177], v[226:229], v[76:79]
	v_mfma_f32_16x16x32_bf16 v[80:83], v[162:165], v[222:225], v[80:83]
	v_mfma_f32_16x16x32_bf16 v[80:83], v[166:169], v[226:229], v[80:83]
	v_mfma_f32_16x16x32_bf16 v[84:87], v[136:139], v[222:225], v[84:87]
	v_mfma_f32_16x16x32_bf16 v[84:87], v[158:161], v[226:229], v[84:87]
	s_barrier
	s_add_i32 s0, s61, s19
	s_mov_b32 m0, s0
	ds_read_b128 v[198:201], v193 offset:16384
	ds_read_b128 v[202:205], v193 offset:17408
	ds_read_b128 v[206:209], v193 offset:18432
	ds_read_b128 v[210:213], v193 offset:19456
	ds_read_b128 v[214:217], v193 offset:20480
	ds_read_b128 v[218:221], v193 offset:21504
	ds_read_b128 v[222:225], v193 offset:22528
	ds_read_b128 v[226:229], v193 offset:23552
	global_load_lds_dwordx4 v142, s[50:51]
	s_add_i32 m0, s0, 0x2000
	s_add_u32 s72, s50, 0x100000
	s_addc_u32 s73, s51, 0
	s_add_i32 s0, s62, s19
	global_load_lds_dwordx4 v146, s[50:51]
	s_mov_b32 m0, s0
	s_nop 0
	global_load_lds_dwordx4 v142, s[72:73]
	s_add_i32 m0, s0, 0x2000
	s_nop 0
	global_load_lds_dwordx4 v146, s[72:73]
	s_mov_b32 m0, s31
	s_nop 0
	global_load_lds_dwordx4 v140, s[52:53]
	s_mov_b32 m0, s35
	s_nop 0
	global_load_lds_dwordx4 v144, s[52:53]
	s_waitcnt vmcnt(8)
	s_waitcnt lgkmcnt(0)
	s_barrier
	v_mfma_f32_16x16x32_bf16 v[68:71], v[136:139], v[198:201], v[68:71]
	v_mfma_f32_16x16x32_bf16 v[68:71], v[158:161], v[202:205], v[68:71]
	v_mfma_f32_16x16x32_bf16 v[64:67], v[162:165], v[198:201], v[64:67]
	v_mfma_f32_16x16x32_bf16 v[64:67], v[166:169], v[202:205], v[64:67]
	v_mfma_f32_16x16x32_bf16 v[60:63], v[170:173], v[198:201], v[60:63]
	v_mfma_f32_16x16x32_bf16 v[60:63], v[174:177], v[202:205], v[60:63]
	v_mfma_f32_16x16x32_bf16 v[56:59], v[178:181], v[198:201], v[56:59]
	v_mfma_f32_16x16x32_bf16 v[56:59], v[194:197], v[202:205], v[56:59]
	v_mfma_f32_16x16x32_bf16 v[40:43], v[178:181], v[206:209], v[40:43]
	v_mfma_f32_16x16x32_bf16 v[40:43], v[194:197], v[210:213], v[40:43]
	v_mfma_f32_16x16x32_bf16 v[44:47], v[170:173], v[206:209], v[44:47]
	v_mfma_f32_16x16x32_bf16 v[44:47], v[174:177], v[210:213], v[44:47]
	v_mfma_f32_16x16x32_bf16 v[48:51], v[162:165], v[206:209], v[48:51]
	v_mfma_f32_16x16x32_bf16 v[48:51], v[166:169], v[210:213], v[48:51]
	v_mfma_f32_16x16x32_bf16 v[52:55], v[136:139], v[206:209], v[52:55]
	v_mfma_f32_16x16x32_bf16 v[52:55], v[158:161], v[210:213], v[52:55]
	v_mfma_f32_16x16x32_bf16 v[36:39], v[136:139], v[214:217], v[36:39]
	v_mfma_f32_16x16x32_bf16 v[36:39], v[158:161], v[218:221], v[36:39]
	v_mfma_f32_16x16x32_bf16 v[32:35], v[162:165], v[214:217], v[32:35]
	v_mfma_f32_16x16x32_bf16 v[32:35], v[166:169], v[218:221], v[32:35]
	v_mfma_f32_16x16x32_bf16 v[28:31], v[170:173], v[214:217], v[28:31]
	v_mfma_f32_16x16x32_bf16 v[28:31], v[174:177], v[218:221], v[28:31]
	v_mfma_f32_16x16x32_bf16 v[24:27], v[178:181], v[214:217], v[24:27]
	v_mfma_f32_16x16x32_bf16 v[24:27], v[194:197], v[218:221], v[24:27]
	v_mfma_f32_16x16x32_bf16 v[6:9], v[178:181], v[222:225], v[8:11]
	v_mfma_f32_16x16x32_bf16 v[6:9], v[194:197], v[226:229], v[6:9]
	v_mfma_f32_16x16x32_bf16 v[12:15], v[170:173], v[222:225], v[12:15]
	v_mfma_f32_16x16x32_bf16 v[12:15], v[174:177], v[226:229], v[12:15]
	v_mfma_f32_16x16x32_bf16 v[16:19], v[162:165], v[222:225], v[16:19]
	v_mfma_f32_16x16x32_bf16 v[16:19], v[166:169], v[226:229], v[16:19]
	v_mfma_f32_16x16x32_bf16 v[20:23], v[136:139], v[222:225], v[20:23]
	v_mfma_f32_16x16x32_bf16 v[20:23], v[158:161], v[226:229], v[20:23]
	s_barrier
	s_add_i32 s0, 0, 0x18000
	v_add_u32_e32 v5, s0, v1
	s_add_i32 s71, 0, 0x1c000
	ds_read_b128 v[136:139], v5
	ds_read_b128 v[158:161], v5 offset:1024
	ds_read_b128 v[162:165], v5 offset:2048
	ds_read_b128 v[166:169], v5 offset:3072
	v_add_u32_e32 v5, s71, v1
	ds_read_b128 v[170:173], v5
	ds_read_b128 v[174:177], v5 offset:1024
	ds_read_b128 v[178:181], v5 offset:2048
	ds_read_b128 v[194:197], v5 offset:3072
	s_add_u32 s98, s52, 0x100000
	s_addc_u32 s99, s53, 0
	s_mov_b32 m0, s45
	ds_read_b128 v[198:201], v193 offset:32768
	ds_read_b128 v[202:205], v193 offset:33792
	ds_read_b128 v[206:209], v193 offset:34816
	ds_read_b128 v[210:213], v193 offset:35840
	ds_read_b128 v[214:217], v193 offset:36864
	ds_read_b128 v[218:221], v193 offset:37888
	ds_read_b128 v[222:225], v193 offset:38912
	ds_read_b128 v[226:229], v193 offset:39936
	global_load_lds_dwordx4 v140, s[98:99]
	s_mov_b32 m0, s46
	s_nop 0
	global_load_lds_dwordx4 v144, s[98:99]
	s_waitcnt vmcnt(8)
	s_waitcnt lgkmcnt(0)
	s_barrier
	v_mfma_f32_16x16x32_bf16 v[132:135], v[136:139], v[198:201], v[132:135]
	v_mfma_f32_16x16x32_bf16 v[132:135], v[158:161], v[202:205], v[132:135]
	v_mfma_f32_16x16x32_bf16 v[128:131], v[162:165], v[198:201], v[128:131]
	v_mfma_f32_16x16x32_bf16 v[128:131], v[166:169], v[202:205], v[128:131]
	v_mfma_f32_16x16x32_bf16 v[124:127], v[170:173], v[198:201], v[124:127]
	v_mfma_f32_16x16x32_bf16 v[124:127], v[174:177], v[202:205], v[124:127]
	v_mfma_f32_16x16x32_bf16 v[120:123], v[178:181], v[198:201], v[120:123]
	v_mfma_f32_16x16x32_bf16 v[120:123], v[194:197], v[202:205], v[120:123]
	v_mfma_f32_16x16x32_bf16 v[104:107], v[178:181], v[206:209], v[104:107]
	v_mfma_f32_16x16x32_bf16 v[104:107], v[194:197], v[210:213], v[104:107]
	v_mfma_f32_16x16x32_bf16 v[108:111], v[170:173], v[206:209], v[108:111]
	v_mfma_f32_16x16x32_bf16 v[108:111], v[174:177], v[210:213], v[108:111]
	v_mfma_f32_16x16x32_bf16 v[112:115], v[162:165], v[206:209], v[112:115]
	v_mfma_f32_16x16x32_bf16 v[112:115], v[166:169], v[210:213], v[112:115]
	v_mfma_f32_16x16x32_bf16 v[116:119], v[136:139], v[206:209], v[116:119]
	v_mfma_f32_16x16x32_bf16 v[116:119], v[158:161], v[210:213], v[116:119]
	v_mfma_f32_16x16x32_bf16 v[100:103], v[136:139], v[214:217], v[100:103]
	v_mfma_f32_16x16x32_bf16 v[100:103], v[158:161], v[218:221], v[100:103]
	v_mfma_f32_16x16x32_bf16 v[96:99], v[162:165], v[214:217], v[96:99]
	v_mfma_f32_16x16x32_bf16 v[96:99], v[166:169], v[218:221], v[96:99]
	v_mfma_f32_16x16x32_bf16 v[92:95], v[170:173], v[214:217], v[92:95]
	v_mfma_f32_16x16x32_bf16 v[92:95], v[174:177], v[218:221], v[92:95]
	v_mfma_f32_16x16x32_bf16 v[88:91], v[178:181], v[214:217], v[88:91]
	v_mfma_f32_16x16x32_bf16 v[88:91], v[194:197], v[218:221], v[88:91]
	v_mfma_f32_16x16x32_bf16 v[72:75], v[178:181], v[222:225], v[72:75]
	v_mfma_f32_16x16x32_bf16 v[72:75], v[194:197], v[226:229], v[72:75]
	v_mfma_f32_16x16x32_bf16 v[76:79], v[170:173], v[222:225], v[76:79]
	v_mfma_f32_16x16x32_bf16 v[76:79], v[174:177], v[226:229], v[76:79]
	v_mfma_f32_16x16x32_bf16 v[80:83], v[162:165], v[222:225], v[80:83]
	v_mfma_f32_16x16x32_bf16 v[80:83], v[166:169], v[226:229], v[80:83]
	v_mfma_f32_16x16x32_bf16 v[84:87], v[136:139], v[222:225], v[84:87]
	v_mfma_f32_16x16x32_bf16 v[84:87], v[158:161], v[226:229], v[84:87]
	s_barrier
	s_add_i32 s0, s0, s19
	s_add_i32 m0, s0, 0xffffff80
	ds_read_b128 v[198:201], v193 offset:49152
	ds_read_b128 v[202:205], v193 offset:50176
	ds_read_b128 v[206:209], v193 offset:51200
	ds_read_b128 v[210:213], v193 offset:52224
	ds_read_b128 v[214:217], v193 offset:53248
	ds_read_b128 v[218:221], v193 offset:54272
	ds_read_b128 v[222:225], v193 offset:55296
	ds_read_b128 v[226:229], v193 offset:56320
	global_load_lds_dwordx4 v142, s[50:51] offset:128
	s_add_i32 m0, s0, 0x1f80
	s_add_i32 s0, s71, s19
	global_load_lds_dwordx4 v146, s[50:51] offset:128
	s_add_u32 s50, s50, 0x100080
	s_addc_u32 s51, s51, 0
	s_mov_b32 m0, s0
	s_nop 0
	global_load_lds_dwordx4 v142, s[50:51]
	s_add_i32 m0, s0, 0x2000
	s_nop 0
	global_load_lds_dwordx4 v146, s[50:51]
	s_add_i32 m0, s56, 0xffffff80
	s_nop 0
	global_load_lds_dwordx4 v140, s[52:53] offset:128
	s_add_i32 m0, s57, 0xffffff80
	s_nop 0
	global_load_lds_dwordx4 v144, s[52:53] offset:128
	s_waitcnt vmcnt(8)
	s_waitcnt lgkmcnt(0)
	s_barrier
	v_mfma_f32_16x16x32_bf16 v[68:71], v[136:139], v[198:201], v[68:71]
	v_mfma_f32_16x16x32_bf16 v[68:71], v[158:161], v[202:205], v[68:71]
	v_mfma_f32_16x16x32_bf16 v[64:67], v[162:165], v[198:201], v[64:67]
	v_mfma_f32_16x16x32_bf16 v[64:67], v[166:169], v[202:205], v[64:67]
	v_mfma_f32_16x16x32_bf16 v[60:63], v[170:173], v[198:201], v[60:63]
	v_mfma_f32_16x16x32_bf16 v[60:63], v[174:177], v[202:205], v[60:63]
	v_mfma_f32_16x16x32_bf16 v[56:59], v[178:181], v[198:201], v[56:59]
	v_mfma_f32_16x16x32_bf16 v[56:59], v[194:197], v[202:205], v[56:59]
	v_mfma_f32_16x16x32_bf16 v[52:55], v[136:139], v[206:209], v[52:55]
	v_mfma_f32_16x16x32_bf16 v[52:55], v[158:161], v[210:213], v[52:55]
	v_mfma_f32_16x16x32_bf16 v[48:51], v[162:165], v[206:209], v[48:51]
	v_mfma_f32_16x16x32_bf16 v[48:51], v[166:169], v[210:213], v[48:51]
	v_mfma_f32_16x16x32_bf16 v[44:47], v[170:173], v[206:209], v[44:47]
	v_mfma_f32_16x16x32_bf16 v[44:47], v[174:177], v[210:213], v[44:47]
	v_mfma_f32_16x16x32_bf16 v[40:43], v[178:181], v[206:209], v[40:43]
	v_mfma_f32_16x16x32_bf16 v[40:43], v[194:197], v[210:213], v[40:43]
	v_mfma_f32_16x16x32_bf16 v[36:39], v[136:139], v[214:217], v[36:39]
	v_mfma_f32_16x16x32_bf16 v[36:39], v[158:161], v[218:221], v[36:39]
	v_mfma_f32_16x16x32_bf16 v[32:35], v[162:165], v[214:217], v[32:35]
	v_mfma_f32_16x16x32_bf16 v[32:35], v[166:169], v[218:221], v[32:35]
	v_mfma_f32_16x16x32_bf16 v[28:31], v[170:173], v[214:217], v[28:31]
	v_mfma_f32_16x16x32_bf16 v[28:31], v[174:177], v[218:221], v[28:31]
	v_mfma_f32_16x16x32_bf16 v[24:27], v[178:181], v[214:217], v[24:27]
	v_mfma_f32_16x16x32_bf16 v[24:27], v[194:197], v[218:221], v[24:27]
	v_mfma_f32_16x16x32_bf16 v[20:23], v[136:139], v[222:225], v[20:23]
	v_mfma_f32_16x16x32_bf16 v[20:23], v[158:161], v[226:229], v[20:23]
	v_mfma_f32_16x16x32_bf16 v[16:19], v[162:165], v[222:225], v[16:19]
	v_mfma_f32_16x16x32_bf16 v[16:19], v[166:169], v[226:229], v[16:19]
	v_mfma_f32_16x16x32_bf16 v[10:13], v[170:173], v[222:225], v[12:15]
	v_mfma_f32_16x16x32_bf16 v[12:15], v[174:177], v[226:229], v[10:13]
	v_mfma_f32_16x16x32_bf16 v[6:9], v[178:181], v[222:225], v[6:9]
	v_mfma_f32_16x16x32_bf16 v[8:11], v[194:197], v[226:229], v[6:9]
	s_barrier
	s_add_i32 s70, s70, 2
	s_add_u32 s42, s42, 0x100
	s_addc_u32 s43, s43, 0
	s_add_u32 s67, s67, 0x100
	s_addc_u32 s68, s68, 0
	s_cmp_gt_u32 s70, 61
	s_cbranch_scc0 .LBB0_170
	s_and_b64 vcc, exec, s[16:17]
	s_cbranch_vccz .LBB0_173
	s_barrier

.LBB0_342:
	ds_read_b128 v[132:135], v209
	ds_read_b128 v[136:139], v209 offset:1024
	ds_read_b128 v[140:143], v209 offset:2048
	ds_read_b128 v[144:147], v209 offset:3072
	ds_read_b128 v[148:151], v210
	ds_read_b128 v[152:155], v210 offset:1024
	ds_read_b128 v[156:159], v210 offset:2048
	ds_read_b128 v[160:163], v210 offset:3072
	s_add_u32 s0, s26, 0xffd50080
	s_addc_u32 s28, s27, -1
	s_cmpk_eq_i32 s62, 0xa8
	s_cselect_b32 s31, s7, s28
	s_cselect_b32 s30, s6, s0
	s_cselect_b32 s29, s25, s61
	s_cselect_b32 s28, s24, s60
	s_add_i32 m0, s43, 0xc000
	ds_read_b128 v[164:167], v211
	ds_read_b128 v[168:171], v211 offset:1024
	ds_read_b128 v[172:175], v211 offset:2048
	ds_read_b128 v[176:179], v211 offset:3072
	ds_read_b128 v[196:199], v211 offset:4096
	ds_read_b128 v[200:203], v211 offset:5120
	ds_read_b128 v[204:207], v211 offset:6144
	ds_read_b128 v[214:217], v211 offset:7168
	global_load_lds_dwordx4 v188, s[26:27]
	s_add_i32 m0, s43, 0xe000
	s_nop 0
	global_load_lds_dwordx4 v190, s[26:27]
	s_waitcnt vmcnt(8)
	s_waitcnt lgkmcnt(0)
	s_barrier
	v_mfma_f32_16x16x32_bf16 v[128:131], v[132:135], v[164:167], v[128:131]
	v_mfma_f32_16x16x32_bf16 v[128:131], v[136:139], v[168:171], v[128:131]
	v_mfma_f32_16x16x32_bf16 v[124:127], v[140:143], v[164:167], v[124:127]
	v_mfma_f32_16x16x32_bf16 v[124:127], v[144:147], v[168:171], v[124:127]
	v_mfma_f32_16x16x32_bf16 v[120:123], v[148:151], v[164:167], v[120:123]
	v_mfma_f32_16x16x32_bf16 v[120:123], v[152:155], v[168:171], v[120:123]
	v_mfma_f32_16x16x32_bf16 v[116:119], v[156:159], v[164:167], v[116:119]
	v_mfma_f32_16x16x32_bf16 v[116:119], v[160:163], v[168:171], v[116:119]
	v_mfma_f32_16x16x32_bf16 v[100:103], v[156:159], v[172:175], v[100:103]
	v_mfma_f32_16x16x32_bf16 v[100:103], v[160:163], v[176:179], v[100:103]
	v_mfma_f32_16x16x32_bf16 v[104:107], v[148:151], v[172:175], v[104:107]
	v_mfma_f32_16x16x32_bf16 v[104:107], v[152:155], v[176:179], v[104:107]
	v_mfma_f32_16x16x32_bf16 v[108:111], v[140:143], v[172:175], v[108:111]
	v_mfma_f32_16x16x32_bf16 v[108:111], v[144:147], v[176:179], v[108:111]
	v_mfma_f32_16x16x32_bf16 v[112:115], v[132:135], v[172:175], v[112:115]
	v_mfma_f32_16x16x32_bf16 v[112:115], v[136:139], v[176:179], v[112:115]
	v_mfma_f32_16x16x32_bf16 v[96:99], v[132:135], v[196:199], v[96:99]
	v_mfma_f32_16x16x32_bf16 v[96:99], v[136:139], v[200:203], v[96:99]
	v_mfma_f32_16x16x32_bf16 v[92:95], v[140:143], v[196:199], v[92:95]
	v_mfma_f32_16x16x32_bf16 v[92:95], v[144:147], v[200:203], v[92:95]
	v_mfma_f32_16x16x32_bf16 v[88:91], v[148:151], v[196:199], v[88:91]
	v_mfma_f32_16x16x32_bf16 v[88:91], v[152:155], v[200:203], v[88:91]
	v_mfma_f32_16x16x32_bf16 v[84:87], v[156:159], v[196:199], v[84:87]
	v_mfma_f32_16x16x32_bf16 v[84:87], v[160:163], v[200:203], v[84:87]
	v_mfma_f32_16x16x32_bf16 v[68:71], v[156:159], v[204:207], v[68:71]
	v_mfma_f32_16x16x32_bf16 v[68:71], v[160:163], v[214:217], v[68:71]
	v_mfma_f32_16x16x32_bf16 v[72:75], v[148:151], v[204:207], v[72:75]
	v_mfma_f32_16x16x32_bf16 v[72:75], v[152:155], v[214:217], v[72:75]
	v_mfma_f32_16x16x32_bf16 v[76:79], v[140:143], v[204:207], v[76:79]
	v_mfma_f32_16x16x32_bf16 v[76:79], v[144:147], v[214:217], v[76:79]
	v_mfma_f32_16x16x32_bf16 v[80:83], v[132:135], v[204:207], v[80:83]
	v_mfma_f32_16x16x32_bf16 v[80:83], v[136:139], v[214:217], v[80:83]
	s_barrier
	s_add_i32 s0, s53, s42
	s_mov_b32 m0, s0
	ds_read_b128 v[164:167], v211 offset:16384
	ds_read_b128 v[168:171], v211 offset:17408
	ds_read_b128 v[172:175], v211 offset:18432
	ds_read_b128 v[176:179], v211 offset:19456
	ds_read_b128 v[196:199], v211 offset:20480
	ds_read_b128 v[200:203], v211 offset:21504
	ds_read_b128 v[204:207], v211 offset:22528
	ds_read_b128 v[214:217], v211 offset:23552
	global_load_lds_dwordx4 v182, s[28:29]
	s_add_i32 m0, s0, 0x2000
	s_add_u32 s64, s28, 0x2b0000
	s_addc_u32 s65, s29, 0
	s_add_i32 s0, s54, s42
	global_load_lds_dwordx4 v186, s[28:29]
	s_mov_b32 m0, s0
	s_nop 0
	global_load_lds_dwordx4 v182, s[64:65]
	s_add_i32 m0, s0, 0x2000
	s_nop 0
	global_load_lds_dwordx4 v186, s[64:65]
	s_mov_b32 m0, s43
	s_nop 0
	global_load_lds_dwordx4 v180, s[30:31]
	s_mov_b32 m0, s45
	s_nop 0
	global_load_lds_dwordx4 v184, s[30:31]
	s_waitcnt vmcnt(8)
	s_waitcnt lgkmcnt(0)
	s_barrier
	v_mfma_f32_16x16x32_bf16 v[64:67], v[132:135], v[164:167], v[64:67]
	v_mfma_f32_16x16x32_bf16 v[64:67], v[136:139], v[168:171], v[64:67]
	v_mfma_f32_16x16x32_bf16 v[60:63], v[140:143], v[164:167], v[60:63]
	v_mfma_f32_16x16x32_bf16 v[60:63], v[144:147], v[168:171], v[60:63]
	v_mfma_f32_16x16x32_bf16 v[56:59], v[148:151], v[164:167], v[56:59]
	v_mfma_f32_16x16x32_bf16 v[56:59], v[152:155], v[168:171], v[56:59]
	v_mfma_f32_16x16x32_bf16 v[52:55], v[156:159], v[164:167], v[52:55]
	v_mfma_f32_16x16x32_bf16 v[52:55], v[160:163], v[168:171], v[52:55]
	v_mfma_f32_16x16x32_bf16 v[36:39], v[156:159], v[172:175], v[36:39]
	v_mfma_f32_16x16x32_bf16 v[36:39], v[160:163], v[176:179], v[36:39]
	v_mfma_f32_16x16x32_bf16 v[40:43], v[148:151], v[172:175], v[40:43]
	v_mfma_f32_16x16x32_bf16 v[40:43], v[152:155], v[176:179], v[40:43]
	v_mfma_f32_16x16x32_bf16 v[44:47], v[140:143], v[172:175], v[44:47]
	v_mfma_f32_16x16x32_bf16 v[44:47], v[144:147], v[176:179], v[44:47]
	v_mfma_f32_16x16x32_bf16 v[48:51], v[132:135], v[172:175], v[48:51]
	v_mfma_f32_16x16x32_bf16 v[48:51], v[136:139], v[176:179], v[48:51]
	v_mfma_f32_16x16x32_bf16 v[32:35], v[132:135], v[196:199], v[32:35]
	v_mfma_f32_16x16x32_bf16 v[32:35], v[136:139], v[200:203], v[32:35]
	v_mfma_f32_16x16x32_bf16 v[28:31], v[140:143], v[196:199], v[28:31]
	v_mfma_f32_16x16x32_bf16 v[28:31], v[144:147], v[200:203], v[28:31]
	v_mfma_f32_16x16x32_bf16 v[24:27], v[148:151], v[196:199], v[24:27]
	v_mfma_f32_16x16x32_bf16 v[24:27], v[152:155], v[200:203], v[24:27]
	v_mfma_f32_16x16x32_bf16 v[20:23], v[156:159], v[196:199], v[20:23]
	v_mfma_f32_16x16x32_bf16 v[20:23], v[160:163], v[200:203], v[20:23]
	v_mfma_f32_16x16x32_bf16 v[4:7], v[156:159], v[204:207], v[4:7]
	v_mfma_f32_16x16x32_bf16 v[4:7], v[160:163], v[214:217], v[4:7]
	v_mfma_f32_16x16x32_bf16 v[8:11], v[148:151], v[204:207], v[8:11]
	v_mfma_f32_16x16x32_bf16 v[8:11], v[152:155], v[214:217], v[8:11]
	v_mfma_f32_16x16x32_bf16 v[12:15], v[140:143], v[204:207], v[12:15]
	v_mfma_f32_16x16x32_bf16 v[12:15], v[144:147], v[214:217], v[12:15]
	v_mfma_f32_16x16x32_bf16 v[16:19], v[132:135], v[204:207], v[16:19]
	v_mfma_f32_16x16x32_bf16 v[16:19], v[136:139], v[214:217], v[16:19]
	s_barrier
	s_add_i32 s0, 0, 0x18000
	s_add_i32 s63, 0, 0x1c000
	v_add_u32_e32 v144, s0, v3
	v_add_u32_e32 v160, s63, v3
	ds_read_b128 v[132:135], v144
	ds_read_b128 v[136:139], v144 offset:1024
	ds_read_b128 v[140:143], v144 offset:2048
	ds_read_b128 v[144:147], v144 offset:3072
	ds_read_b128 v[148:151], v160
	ds_read_b128 v[152:155], v160 offset:1024
	ds_read_b128 v[156:159], v160 offset:2048
	ds_read_b128 v[160:163], v160 offset:3072
	s_add_u32 s98, s30, 0x2b0000
	s_addc_u32 s99, s31, 0
	s_mov_b32 m0, s46
	ds_read_b128 v[164:167], v211 offset:32768
	ds_read_b128 v[168:171], v211 offset:33792
	ds_read_b128 v[172:175], v211 offset:34816
	ds_read_b128 v[176:179], v211 offset:35840
	ds_read_b128 v[196:199], v211 offset:36864
	ds_read_b128 v[200:203], v211 offset:37888
	ds_read_b128 v[204:207], v211 offset:38912
	ds_read_b128 v[214:217], v211 offset:39936
	global_load_lds_dwordx4 v180, s[98:99]
	s_mov_b32 m0, s47
	s_nop 0
	global_load_lds_dwordx4 v184, s[98:99]
	s_waitcnt vmcnt(8)
	s_waitcnt lgkmcnt(0)
	s_barrier
	v_mfma_f32_16x16x32_bf16 v[128:131], v[132:135], v[164:167], v[128:131]
	v_mfma_f32_16x16x32_bf16 v[128:131], v[136:139], v[168:171], v[128:131]
	v_mfma_f32_16x16x32_bf16 v[124:127], v[140:143], v[164:167], v[124:127]
	v_mfma_f32_16x16x32_bf16 v[124:127], v[144:147], v[168:171], v[124:127]
	v_mfma_f32_16x16x32_bf16 v[120:123], v[148:151], v[164:167], v[120:123]
	v_mfma_f32_16x16x32_bf16 v[120:123], v[152:155], v[168:171], v[120:123]
	v_mfma_f32_16x16x32_bf16 v[116:119], v[156:159], v[164:167], v[116:119]
	v_mfma_f32_16x16x32_bf16 v[116:119], v[160:163], v[168:171], v[116:119]
	v_mfma_f32_16x16x32_bf16 v[100:103], v[156:159], v[172:175], v[100:103]
	v_mfma_f32_16x16x32_bf16 v[100:103], v[160:163], v[176:179], v[100:103]
	v_mfma_f32_16x16x32_bf16 v[104:107], v[148:151], v[172:175], v[104:107]
	v_mfma_f32_16x16x32_bf16 v[104:107], v[152:155], v[176:179], v[104:107]
	v_mfma_f32_16x16x32_bf16 v[108:111], v[140:143], v[172:175], v[108:111]
	v_mfma_f32_16x16x32_bf16 v[108:111], v[144:147], v[176:179], v[108:111]
	v_mfma_f32_16x16x32_bf16 v[112:115], v[132:135], v[172:175], v[112:115]
	v_mfma_f32_16x16x32_bf16 v[112:115], v[136:139], v[176:179], v[112:115]
	v_mfma_f32_16x16x32_bf16 v[96:99], v[132:135], v[196:199], v[96:99]
	v_mfma_f32_16x16x32_bf16 v[96:99], v[136:139], v[200:203], v[96:99]
	v_mfma_f32_16x16x32_bf16 v[92:95], v[140:143], v[196:199], v[92:95]
	v_mfma_f32_16x16x32_bf16 v[92:95], v[144:147], v[200:203], v[92:95]
	v_mfma_f32_16x16x32_bf16 v[88:91], v[148:151], v[196:199], v[88:91]
	v_mfma_f32_16x16x32_bf16 v[88:91], v[152:155], v[200:203], v[88:91]
	v_mfma_f32_16x16x32_bf16 v[84:87], v[156:159], v[196:199], v[84:87]
	v_mfma_f32_16x16x32_bf16 v[84:87], v[160:163], v[200:203], v[84:87]
	v_mfma_f32_16x16x32_bf16 v[68:71], v[156:159], v[204:207], v[68:71]
	v_mfma_f32_16x16x32_bf16 v[68:71], v[160:163], v[214:217], v[68:71]
	v_mfma_f32_16x16x32_bf16 v[72:75], v[148:151], v[204:207], v[72:75]
	v_mfma_f32_16x16x32_bf16 v[72:75], v[152:155], v[214:217], v[72:75]
	v_mfma_f32_16x16x32_bf16 v[76:79], v[140:143], v[204:207], v[76:79]
	v_mfma_f32_16x16x32_bf16 v[76:79], v[144:147], v[214:217], v[76:79]
	v_mfma_f32_16x16x32_bf16 v[80:83], v[132:135], v[204:207], v[80:83]
	v_mfma_f32_16x16x32_bf16 v[80:83], v[136:139], v[214:217], v[80:83]
	s_barrier
	s_add_i32 s0, s0, s42
	s_add_i32 m0, s0, 0xffffff80
	ds_read_b128 v[164:167], v211 offset:49152
	ds_read_b128 v[168:171], v211 offset:50176
	ds_read_b128 v[172:175], v211 offset:51200
	ds_read_b128 v[176:179], v211 offset:52224
	ds_read_b128 v[196:199], v211 offset:53248
	ds_read_b128 v[200:203], v211 offset:54272
	ds_read_b128 v[204:207], v211 offset:55296
	ds_read_b128 v[214:217], v211 offset:56320
	global_load_lds_dwordx4 v182, s[28:29] offset:128
	s_add_i32 m0, s0, 0x1f80
	s_add_i32 s0, s63, s42
	global_load_lds_dwordx4 v186, s[28:29] offset:128
	s_add_u32 s28, s28, 0x2b0080
	s_addc_u32 s29, s29, 0
	s_mov_b32 m0, s0
	s_nop 0
	global_load_lds_dwordx4 v182, s[28:29]
	s_add_i32 m0, s0, 0x2000
	s_nop 0
	global_load_lds_dwordx4 v186, s[28:29]
	s_add_i32 m0, s51, 0xffffff80
	s_nop 0
	global_load_lds_dwordx4 v180, s[30:31] offset:128
	s_add_i32 m0, s52, 0xffffff80
	s_nop 0
	global_load_lds_dwordx4 v184, s[30:31] offset:128
	s_waitcnt vmcnt(8)
	s_waitcnt lgkmcnt(0)
	s_barrier
	v_mfma_f32_16x16x32_bf16 v[64:67], v[132:135], v[164:167], v[64:67]
	v_mfma_f32_16x16x32_bf16 v[64:67], v[136:139], v[168:171], v[64:67]
	v_mfma_f32_16x16x32_bf16 v[60:63], v[140:143], v[164:167], v[60:63]
	v_mfma_f32_16x16x32_bf16 v[60:63], v[144:147], v[168:171], v[60:63]
	v_mfma_f32_16x16x32_bf16 v[56:59], v[148:151], v[164:167], v[56:59]
	v_mfma_f32_16x16x32_bf16 v[56:59], v[152:155], v[168:171], v[56:59]
	v_mfma_f32_16x16x32_bf16 v[52:55], v[156:159], v[164:167], v[52:55]
	v_mfma_f32_16x16x32_bf16 v[52:55], v[160:163], v[168:171], v[52:55]
	v_mfma_f32_16x16x32_bf16 v[36:39], v[156:159], v[172:175], v[36:39]
	v_mfma_f32_16x16x32_bf16 v[36:39], v[160:163], v[176:179], v[36:39]
	v_mfma_f32_16x16x32_bf16 v[40:43], v[148:151], v[172:175], v[40:43]
	v_mfma_f32_16x16x32_bf16 v[40:43], v[152:155], v[176:179], v[40:43]
	v_mfma_f32_16x16x32_bf16 v[44:47], v[140:143], v[172:175], v[44:47]
	v_mfma_f32_16x16x32_bf16 v[44:47], v[144:147], v[176:179], v[44:47]
	v_mfma_f32_16x16x32_bf16 v[48:51], v[132:135], v[172:175], v[48:51]
	v_mfma_f32_16x16x32_bf16 v[48:51], v[136:139], v[176:179], v[48:51]
	v_mfma_f32_16x16x32_bf16 v[32:35], v[132:135], v[196:199], v[32:35]
	v_mfma_f32_16x16x32_bf16 v[32:35], v[136:139], v[200:203], v[32:35]
	v_mfma_f32_16x16x32_bf16 v[28:31], v[140:143], v[196:199], v[28:31]
	v_mfma_f32_16x16x32_bf16 v[28:31], v[144:147], v[200:203], v[28:31]
	v_mfma_f32_16x16x32_bf16 v[24:27], v[148:151], v[196:199], v[24:27]
	v_mfma_f32_16x16x32_bf16 v[24:27], v[152:155], v[200:203], v[24:27]
	v_mfma_f32_16x16x32_bf16 v[20:23], v[156:159], v[196:199], v[20:23]
	v_mfma_f32_16x16x32_bf16 v[20:23], v[160:163], v[200:203], v[20:23]
	v_mfma_f32_16x16x32_bf16 v[4:7], v[156:159], v[204:207], v[4:7]
	v_mfma_f32_16x16x32_bf16 v[4:7], v[160:163], v[214:217], v[4:7]
	v_mfma_f32_16x16x32_bf16 v[8:11], v[148:151], v[204:207], v[8:11]
	v_mfma_f32_16x16x32_bf16 v[8:11], v[152:155], v[214:217], v[8:11]
	v_mfma_f32_16x16x32_bf16 v[12:15], v[140:143], v[204:207], v[12:15]
	v_mfma_f32_16x16x32_bf16 v[12:15], v[144:147], v[214:217], v[12:15]
	v_mfma_f32_16x16x32_bf16 v[16:19], v[132:135], v[204:207], v[16:19]
	v_mfma_f32_16x16x32_bf16 v[16:19], v[136:139], v[214:217], v[16:19]
	s_barrier
	s_add_i32 s62, s62, 2
	s_add_u32 s26, s26, 0x100
	s_addc_u32 s27, s27, 0
	s_add_u32 s60, s60, 0x100
	s_addc_u32 s61, s61, 0
	s_cmpk_gt_u32 s62, 0xa9
	s_cbranch_scc0 .LBB0_342
	s_and_b64 vcc, exec, s[22:23]
	s_cbranch_vccz .LBB0_345
	s_barrier

.LBB0_429:
	ds_read_b128 v[150:153], v156
	ds_read_b128 v[162:165], v156 offset:1024
	ds_read_b128 v[166:169], v156 offset:2048
	ds_read_b128 v[170:173], v156 offset:3072
	ds_read_b128 v[174:177], v157
	ds_read_b128 v[178:181], v157 offset:1024
	ds_read_b128 v[182:185], v157 offset:2048
	ds_read_b128 v[186:189], v157 offset:3072
	s_add_u32 s0, s50, 0xfff00080
	s_addc_u32 s52, s51, -1
	s_cmp_eq_u32 s72, 60
	s_cselect_b32 s55, s27, s52
	s_cselect_b32 s54, s67, s0
	s_cselect_b32 s53, s25, s71
	s_cselect_b32 s52, s68, s70
	s_add_i32 m0, s43, 0xc000
	ds_read_b128 v[190:193], v158
	ds_read_b128 v[194:197], v158 offset:1024
	ds_read_b128 v[198:201], v158 offset:2048
	ds_read_b128 v[202:205], v158 offset:3072
	ds_read_b128 v[206:209], v158 offset:4096
	ds_read_b128 v[210:213], v158 offset:5120
	ds_read_b128 v[214:217], v158 offset:6144
	ds_read_b128 v[218:221], v158 offset:7168
	global_load_lds_dwordx4 v142, s[50:51]
	s_add_i32 m0, s43, 0xe000
	s_nop 0
	global_load_lds_dwordx4 v144, s[50:51]
	s_waitcnt vmcnt(8)
	s_waitcnt lgkmcnt(0)
	s_barrier
	v_mfma_f32_16x16x32_bf16 v[128:131], v[150:153], v[190:193], v[128:131]
	v_mfma_f32_16x16x32_bf16 v[128:131], v[162:165], v[194:197], v[128:131]
	v_mfma_f32_16x16x32_bf16 v[124:127], v[166:169], v[190:193], v[124:127]
	v_mfma_f32_16x16x32_bf16 v[124:127], v[170:173], v[194:197], v[124:127]
	v_mfma_f32_16x16x32_bf16 v[120:123], v[174:177], v[190:193], v[120:123]
	v_mfma_f32_16x16x32_bf16 v[120:123], v[178:181], v[194:197], v[120:123]
	v_mfma_f32_16x16x32_bf16 v[116:119], v[182:185], v[190:193], v[116:119]
	v_mfma_f32_16x16x32_bf16 v[116:119], v[186:189], v[194:197], v[116:119]
	v_mfma_f32_16x16x32_bf16 v[100:103], v[182:185], v[198:201], v[100:103]
	v_mfma_f32_16x16x32_bf16 v[100:103], v[186:189], v[202:205], v[100:103]
	v_mfma_f32_16x16x32_bf16 v[104:107], v[174:177], v[198:201], v[104:107]
	v_mfma_f32_16x16x32_bf16 v[104:107], v[178:181], v[202:205], v[104:107]
	v_mfma_f32_16x16x32_bf16 v[108:111], v[166:169], v[198:201], v[108:111]
	v_mfma_f32_16x16x32_bf16 v[108:111], v[170:173], v[202:205], v[108:111]
	v_mfma_f32_16x16x32_bf16 v[112:115], v[150:153], v[198:201], v[112:115]
	v_mfma_f32_16x16x32_bf16 v[112:115], v[162:165], v[202:205], v[112:115]
	v_mfma_f32_16x16x32_bf16 v[96:99], v[150:153], v[206:209], v[96:99]
	v_mfma_f32_16x16x32_bf16 v[96:99], v[162:165], v[210:213], v[96:99]
	v_mfma_f32_16x16x32_bf16 v[92:95], v[166:169], v[206:209], v[92:95]
	v_mfma_f32_16x16x32_bf16 v[92:95], v[170:173], v[210:213], v[92:95]
	v_mfma_f32_16x16x32_bf16 v[88:91], v[174:177], v[206:209], v[88:91]
	v_mfma_f32_16x16x32_bf16 v[88:91], v[178:181], v[210:213], v[88:91]
	v_mfma_f32_16x16x32_bf16 v[84:87], v[182:185], v[206:209], v[84:87]
	v_mfma_f32_16x16x32_bf16 v[84:87], v[186:189], v[210:213], v[84:87]
	v_mfma_f32_16x16x32_bf16 v[68:71], v[182:185], v[214:217], v[68:71]
	v_mfma_f32_16x16x32_bf16 v[68:71], v[186:189], v[218:221], v[68:71]
	v_mfma_f32_16x16x32_bf16 v[72:75], v[174:177], v[214:217], v[72:75]
	v_mfma_f32_16x16x32_bf16 v[72:75], v[178:181], v[218:221], v[72:75]
	v_mfma_f32_16x16x32_bf16 v[76:79], v[166:169], v[214:217], v[76:79]
	v_mfma_f32_16x16x32_bf16 v[76:79], v[170:173], v[218:221], v[76:79]
	v_mfma_f32_16x16x32_bf16 v[80:83], v[150:153], v[214:217], v[80:83]
	v_mfma_f32_16x16x32_bf16 v[80:83], v[162:165], v[218:221], v[80:83]
	s_barrier
	s_add_i32 s0, s62, s41
	s_mov_b32 m0, s0
	ds_read_b128 v[190:193], v158 offset:16384
	ds_read_b128 v[194:197], v158 offset:17408
	ds_read_b128 v[198:201], v158 offset:18432
	ds_read_b128 v[202:205], v158 offset:19456
	ds_read_b128 v[206:209], v158 offset:20480
	ds_read_b128 v[210:213], v158 offset:21504
	ds_read_b128 v[214:217], v158 offset:22528
	ds_read_b128 v[218:221], v158 offset:23552
	global_load_lds_dwordx4 v136, s[52:53]
	s_add_i32 m0, s0, 0x2000
	s_add_u32 s74, s52, 0x100000
	s_addc_u32 s75, s53, 0
	s_add_i32 s0, s63, s41
	global_load_lds_dwordx4 v140, s[52:53]
	s_mov_b32 m0, s0
	s_nop 0
	global_load_lds_dwordx4 v136, s[74:75]
	s_add_i32 m0, s0, 0x2000
	s_nop 0
	global_load_lds_dwordx4 v140, s[74:75]
	s_mov_b32 m0, s43
	s_nop 0
	global_load_lds_dwordx4 v134, s[54:55]
	s_mov_b32 m0, s48
	s_nop 0
	global_load_lds_dwordx4 v138, s[54:55]
	s_waitcnt vmcnt(8)
	s_waitcnt lgkmcnt(0)
	s_barrier
	v_mfma_f32_16x16x32_bf16 v[64:67], v[150:153], v[190:193], v[64:67]
	v_mfma_f32_16x16x32_bf16 v[64:67], v[162:165], v[194:197], v[64:67]
	v_mfma_f32_16x16x32_bf16 v[60:63], v[166:169], v[190:193], v[60:63]
	v_mfma_f32_16x16x32_bf16 v[60:63], v[170:173], v[194:197], v[60:63]
	v_mfma_f32_16x16x32_bf16 v[56:59], v[174:177], v[190:193], v[56:59]
	v_mfma_f32_16x16x32_bf16 v[56:59], v[178:181], v[194:197], v[56:59]
	v_mfma_f32_16x16x32_bf16 v[52:55], v[182:185], v[190:193], v[52:55]
	v_mfma_f32_16x16x32_bf16 v[52:55], v[186:189], v[194:197], v[52:55]
	v_mfma_f32_16x16x32_bf16 v[36:39], v[182:185], v[198:201], v[36:39]
	v_mfma_f32_16x16x32_bf16 v[36:39], v[186:189], v[202:205], v[36:39]
	v_mfma_f32_16x16x32_bf16 v[40:43], v[174:177], v[198:201], v[40:43]
	v_mfma_f32_16x16x32_bf16 v[40:43], v[178:181], v[202:205], v[40:43]
	v_mfma_f32_16x16x32_bf16 v[44:47], v[166:169], v[198:201], v[44:47]
	v_mfma_f32_16x16x32_bf16 v[44:47], v[170:173], v[202:205], v[44:47]
	v_mfma_f32_16x16x32_bf16 v[48:51], v[150:153], v[198:201], v[48:51]
	v_mfma_f32_16x16x32_bf16 v[48:51], v[162:165], v[202:205], v[48:51]
	v_mfma_f32_16x16x32_bf16 v[32:35], v[150:153], v[206:209], v[32:35]
	v_mfma_f32_16x16x32_bf16 v[32:35], v[162:165], v[210:213], v[32:35]
	v_mfma_f32_16x16x32_bf16 v[28:31], v[166:169], v[206:209], v[28:31]
	v_mfma_f32_16x16x32_bf16 v[28:31], v[170:173], v[210:213], v[28:31]
	v_mfma_f32_16x16x32_bf16 v[24:27], v[174:177], v[206:209], v[24:27]
	v_mfma_f32_16x16x32_bf16 v[24:27], v[178:181], v[210:213], v[24:27]
	v_mfma_f32_16x16x32_bf16 v[20:23], v[182:185], v[206:209], v[20:23]
	v_mfma_f32_16x16x32_bf16 v[20:23], v[186:189], v[210:213], v[20:23]
	v_mfma_f32_16x16x32_bf16 v[4:7], v[182:185], v[214:217], v[4:7]
	v_mfma_f32_16x16x32_bf16 v[4:7], v[186:189], v[218:221], v[4:7]
	v_mfma_f32_16x16x32_bf16 v[8:11], v[174:177], v[214:217], v[8:11]
	v_mfma_f32_16x16x32_bf16 v[8:11], v[178:181], v[218:221], v[8:11]
	v_mfma_f32_16x16x32_bf16 v[12:15], v[166:169], v[214:217], v[12:15]
	v_mfma_f32_16x16x32_bf16 v[12:15], v[170:173], v[218:221], v[12:15]
	v_mfma_f32_16x16x32_bf16 v[16:19], v[150:153], v[214:217], v[16:19]
	v_mfma_f32_16x16x32_bf16 v[16:19], v[162:165], v[218:221], v[16:19]
	s_barrier
	s_add_i32 s0, 0, 0x18000
	v_add_u32_e32 v161, s0, v133
	s_add_i32 s73, 0, 0x1c000
	ds_read_b128 v[150:153], v161
	ds_read_b128 v[162:165], v161 offset:1024
	ds_read_b128 v[166:169], v161 offset:2048
	ds_read_b128 v[170:173], v161 offset:3072
	v_add_u32_e32 v161, s73, v133
	ds_read_b128 v[174:177], v161
	ds_read_b128 v[178:181], v161 offset:1024
	ds_read_b128 v[182:185], v161 offset:2048
	ds_read_b128 v[186:189], v161 offset:3072
	s_add_u32 s98, s54, 0x100000
	s_addc_u32 s99, s55, 0
	s_mov_b32 m0, s49
	ds_read_b128 v[190:193], v158 offset:32768
	ds_read_b128 v[194:197], v158 offset:33792
	ds_read_b128 v[198:201], v158 offset:34816
	ds_read_b128 v[202:205], v158 offset:35840
	ds_read_b128 v[206:209], v158 offset:36864
	ds_read_b128 v[210:213], v158 offset:37888
	ds_read_b128 v[214:217], v158 offset:38912
	ds_read_b128 v[218:221], v158 offset:39936
	global_load_lds_dwordx4 v134, s[98:99]
	s_mov_b32 m0, s56
	s_nop 0
	global_load_lds_dwordx4 v138, s[98:99]
	s_waitcnt vmcnt(8)
	s_waitcnt lgkmcnt(0)
	s_barrier
	v_mfma_f32_16x16x32_bf16 v[128:131], v[150:153], v[190:193], v[128:131]
	v_mfma_f32_16x16x32_bf16 v[128:131], v[162:165], v[194:197], v[128:131]
	v_mfma_f32_16x16x32_bf16 v[124:127], v[166:169], v[190:193], v[124:127]
	v_mfma_f32_16x16x32_bf16 v[124:127], v[170:173], v[194:197], v[124:127]
	v_mfma_f32_16x16x32_bf16 v[120:123], v[174:177], v[190:193], v[120:123]
	v_mfma_f32_16x16x32_bf16 v[120:123], v[178:181], v[194:197], v[120:123]
	v_mfma_f32_16x16x32_bf16 v[116:119], v[182:185], v[190:193], v[116:119]
	v_mfma_f32_16x16x32_bf16 v[116:119], v[186:189], v[194:197], v[116:119]
	v_mfma_f32_16x16x32_bf16 v[100:103], v[182:185], v[198:201], v[100:103]
	v_mfma_f32_16x16x32_bf16 v[100:103], v[186:189], v[202:205], v[100:103]
	v_mfma_f32_16x16x32_bf16 v[104:107], v[174:177], v[198:201], v[104:107]
	v_mfma_f32_16x16x32_bf16 v[104:107], v[178:181], v[202:205], v[104:107]
	v_mfma_f32_16x16x32_bf16 v[108:111], v[166:169], v[198:201], v[108:111]
	v_mfma_f32_16x16x32_bf16 v[108:111], v[170:173], v[202:205], v[108:111]
	v_mfma_f32_16x16x32_bf16 v[112:115], v[150:153], v[198:201], v[112:115]
	v_mfma_f32_16x16x32_bf16 v[112:115], v[162:165], v[202:205], v[112:115]
	v_mfma_f32_16x16x32_bf16 v[96:99], v[150:153], v[206:209], v[96:99]
	v_mfma_f32_16x16x32_bf16 v[96:99], v[162:165], v[210:213], v[96:99]
	v_mfma_f32_16x16x32_bf16 v[92:95], v[166:169], v[206:209], v[92:95]
	v_mfma_f32_16x16x32_bf16 v[92:95], v[170:173], v[210:213], v[92:95]
	v_mfma_f32_16x16x32_bf16 v[88:91], v[174:177], v[206:209], v[88:91]
	v_mfma_f32_16x16x32_bf16 v[88:91], v[178:181], v[210:213], v[88:91]
	v_mfma_f32_16x16x32_bf16 v[84:87], v[182:185], v[206:209], v[84:87]
	v_mfma_f32_16x16x32_bf16 v[84:87], v[186:189], v[210:213], v[84:87]
	v_mfma_f32_16x16x32_bf16 v[68:71], v[182:185], v[214:217], v[68:71]
	v_mfma_f32_16x16x32_bf16 v[68:71], v[186:189], v[218:221], v[68:71]
	v_mfma_f32_16x16x32_bf16 v[72:75], v[174:177], v[214:217], v[72:75]
	v_mfma_f32_16x16x32_bf16 v[72:75], v[178:181], v[218:221], v[72:75]
	v_mfma_f32_16x16x32_bf16 v[76:79], v[166:169], v[214:217], v[76:79]
	v_mfma_f32_16x16x32_bf16 v[76:79], v[170:173], v[218:221], v[76:79]
	v_mfma_f32_16x16x32_bf16 v[80:83], v[150:153], v[214:217], v[80:83]
	v_mfma_f32_16x16x32_bf16 v[80:83], v[162:165], v[218:221], v[80:83]
	s_barrier
	s_add_i32 s0, s0, s41
	s_add_i32 m0, s0, 0xffffff80
	ds_read_b128 v[190:193], v158 offset:49152
	ds_read_b128 v[194:197], v158 offset:50176
	ds_read_b128 v[198:201], v158 offset:51200
	ds_read_b128 v[202:205], v158 offset:52224
	ds_read_b128 v[206:209], v158 offset:53248
	ds_read_b128 v[210:213], v158 offset:54272
	ds_read_b128 v[214:217], v158 offset:55296
	ds_read_b128 v[218:221], v158 offset:56320
	global_load_lds_dwordx4 v136, s[52:53] offset:128
	s_add_i32 m0, s0, 0x1f80
	s_add_i32 s0, s73, s41
	global_load_lds_dwordx4 v140, s[52:53] offset:128
	s_add_u32 s52, s52, 0x100080
	s_addc_u32 s53, s53, 0
	s_mov_b32 m0, s0
	s_nop 0
	global_load_lds_dwordx4 v136, s[52:53]
	s_add_i32 m0, s0, 0x2000
	s_nop 0
	global_load_lds_dwordx4 v140, s[52:53]
	s_add_i32 m0, s59, 0xffffff80
	s_nop 0
	global_load_lds_dwordx4 v134, s[54:55] offset:128
	s_add_i32 m0, s60, 0xffffff80
	s_nop 0
	global_load_lds_dwordx4 v138, s[54:55] offset:128
	s_waitcnt vmcnt(8)
	s_waitcnt lgkmcnt(0)
	s_barrier
	v_mfma_f32_16x16x32_bf16 v[64:67], v[150:153], v[190:193], v[64:67]
	v_mfma_f32_16x16x32_bf16 v[64:67], v[162:165], v[194:197], v[64:67]
	v_mfma_f32_16x16x32_bf16 v[60:63], v[166:169], v[190:193], v[60:63]
	v_mfma_f32_16x16x32_bf16 v[60:63], v[170:173], v[194:197], v[60:63]
	v_mfma_f32_16x16x32_bf16 v[56:59], v[174:177], v[190:193], v[56:59]
	v_mfma_f32_16x16x32_bf16 v[56:59], v[178:181], v[194:197], v[56:59]
	v_mfma_f32_16x16x32_bf16 v[52:55], v[182:185], v[190:193], v[52:55]
	v_mfma_f32_16x16x32_bf16 v[52:55], v[186:189], v[194:197], v[52:55]
	v_mfma_f32_16x16x32_bf16 v[36:39], v[182:185], v[198:201], v[36:39]
	v_mfma_f32_16x16x32_bf16 v[36:39], v[186:189], v[202:205], v[36:39]
	v_mfma_f32_16x16x32_bf16 v[40:43], v[174:177], v[198:201], v[40:43]
	v_mfma_f32_16x16x32_bf16 v[40:43], v[178:181], v[202:205], v[40:43]
	v_mfma_f32_16x16x32_bf16 v[44:47], v[166:169], v[198:201], v[44:47]
	v_mfma_f32_16x16x32_bf16 v[44:47], v[170:173], v[202:205], v[44:47]
	v_mfma_f32_16x16x32_bf16 v[48:51], v[150:153], v[198:201], v[48:51]
	v_mfma_f32_16x16x32_bf16 v[48:51], v[162:165], v[202:205], v[48:51]
	v_mfma_f32_16x16x32_bf16 v[32:35], v[150:153], v[206:209], v[32:35]
	v_mfma_f32_16x16x32_bf16 v[32:35], v[162:165], v[210:213], v[32:35]
	v_mfma_f32_16x16x32_bf16 v[28:31], v[166:169], v[206:209], v[28:31]
	v_mfma_f32_16x16x32_bf16 v[28:31], v[170:173], v[210:213], v[28:31]
	v_mfma_f32_16x16x32_bf16 v[24:27], v[174:177], v[206:209], v[24:27]
	v_mfma_f32_16x16x32_bf16 v[24:27], v[178:181], v[210:213], v[24:27]
	v_mfma_f32_16x16x32_bf16 v[20:23], v[182:185], v[206:209], v[20:23]
	v_mfma_f32_16x16x32_bf16 v[20:23], v[186:189], v[210:213], v[20:23]
	v_mfma_f32_16x16x32_bf16 v[4:7], v[182:185], v[214:217], v[4:7]
	v_mfma_f32_16x16x32_bf16 v[4:7], v[186:189], v[218:221], v[4:7]
	v_mfma_f32_16x16x32_bf16 v[8:11], v[174:177], v[214:217], v[8:11]
	v_mfma_f32_16x16x32_bf16 v[8:11], v[178:181], v[218:221], v[8:11]
	v_mfma_f32_16x16x32_bf16 v[12:15], v[166:169], v[214:217], v[12:15]
	v_mfma_f32_16x16x32_bf16 v[12:15], v[170:173], v[218:221], v[12:15]
	v_mfma_f32_16x16x32_bf16 v[16:19], v[150:153], v[214:217], v[16:19]
	v_mfma_f32_16x16x32_bf16 v[16:19], v[162:165], v[218:221], v[16:19]
	s_barrier
	s_add_i32 s72, s72, 2
	s_add_u32 s50, s50, 0x100
	s_addc_u32 s51, s51, 0
	s_add_u32 s70, s70, 0x100
	s_addc_u32 s71, s71, 0
	s_cmp_gt_u32 s72, 61
	s_cbranch_scc0 .LBB0_429
	s_and_b64 vcc, exec, s[22:23]
	s_cbranch_vccz .LBB0_432
	s_barrier

.LBB0_1032:
	v_add_u32_e32 v5, s60, v3
	ds_read_b128 v[140:143], v5
	ds_read_b128 v[144:147], v5 offset:1024
	ds_read_b128 v[148:151], v5 offset:2048
	ds_read_b128 v[152:155], v5 offset:3072
	v_add_u32_e32 v5, s61, v3
	ds_read_b128 v[156:159], v5
	ds_read_b128 v[160:163], v5 offset:1024
	ds_read_b128 v[164:167], v5 offset:2048
	ds_read_b128 v[168:171], v5 offset:3072
	s_add_u32 s42, s40, 0xfff80080
	s_addc_u32 s43, s41, -1
	s_cmp_eq_u32 s67, 28
	s_cselect_b32 s51, s5, s43
	s_cselect_b32 s50, s7, s42
	s_cselect_b32 s43, s25, s66
	s_cselect_b32 s42, s27, s65
	s_add_i32 m0, s47, 0xc000
	ds_read_b128 v[172:175], v246
	ds_read_b128 v[176:179], v246 offset:1024
	ds_read_b128 v[180:183], v246 offset:2048
	ds_read_b128 v[184:187], v246 offset:3072
	ds_read_b128 v[188:191], v246 offset:4096
	ds_read_b128 v[192:195], v246 offset:5120
	ds_read_b128 v[196:199], v246 offset:6144
	ds_read_b128 v[200:203], v246 offset:7168
	global_load_lds_dwordx4 v216, s[40:41]
	s_add_i32 m0, s47, 0xe000
	s_nop 0
	global_load_lds_dwordx4 v218, s[40:41]
	s_waitcnt vmcnt(8)
	s_waitcnt lgkmcnt(0)
	s_barrier
	v_mfma_f32_16x16x32_bf16 v[136:139], v[140:143], v[172:175], v[136:139]
	v_mfma_f32_16x16x32_bf16 v[136:139], v[144:147], v[176:179], v[136:139]
	v_mfma_f32_16x16x32_bf16 v[132:135], v[148:151], v[172:175], v[132:135]
	v_mfma_f32_16x16x32_bf16 v[132:135], v[152:155], v[176:179], v[132:135]
	v_mfma_f32_16x16x32_bf16 v[104:107], v[156:159], v[172:175], v[104:107]
	v_mfma_f32_16x16x32_bf16 v[104:107], v[160:163], v[176:179], v[104:107]
	v_mfma_f32_16x16x32_bf16 v[100:103], v[164:167], v[172:175], v[100:103]
	v_mfma_f32_16x16x32_bf16 v[100:103], v[168:171], v[176:179], v[100:103]
	v_mfma_f32_16x16x32_bf16 v[92:95], v[164:167], v[180:183], v[92:95]
	v_mfma_f32_16x16x32_bf16 v[92:95], v[168:171], v[184:187], v[92:95]
	v_mfma_f32_16x16x32_bf16 v[96:99], v[156:159], v[180:183], v[96:99]
	v_mfma_f32_16x16x32_bf16 v[96:99], v[160:163], v[184:187], v[96:99]
	v_mfma_f32_16x16x32_bf16 v[124:127], v[148:151], v[180:183], v[124:127]
	v_mfma_f32_16x16x32_bf16 v[124:127], v[152:155], v[184:187], v[124:127]
	v_mfma_f32_16x16x32_bf16 v[128:131], v[140:143], v[180:183], v[128:131]
	v_mfma_f32_16x16x32_bf16 v[128:131], v[144:147], v[184:187], v[128:131]
	v_mfma_f32_16x16x32_bf16 v[120:123], v[140:143], v[188:191], v[120:123]
	v_mfma_f32_16x16x32_bf16 v[120:123], v[144:147], v[192:195], v[120:123]
	v_mfma_f32_16x16x32_bf16 v[116:119], v[148:151], v[188:191], v[116:119]
	v_mfma_f32_16x16x32_bf16 v[116:119], v[152:155], v[192:195], v[116:119]
	v_mfma_f32_16x16x32_bf16 v[88:91], v[156:159], v[188:191], v[88:91]
	v_mfma_f32_16x16x32_bf16 v[88:91], v[160:163], v[192:195], v[88:91]
	v_mfma_f32_16x16x32_bf16 v[84:87], v[164:167], v[188:191], v[84:87]
	v_mfma_f32_16x16x32_bf16 v[84:87], v[168:171], v[192:195], v[84:87]
	v_mfma_f32_16x16x32_bf16 v[76:79], v[164:167], v[196:199], v[76:79]
	v_mfma_f32_16x16x32_bf16 v[76:79], v[168:171], v[200:203], v[76:79]
	v_mfma_f32_16x16x32_bf16 v[80:83], v[156:159], v[196:199], v[80:83]
	v_mfma_f32_16x16x32_bf16 v[80:83], v[160:163], v[200:203], v[80:83]
	v_mfma_f32_16x16x32_bf16 v[108:111], v[148:151], v[196:199], v[108:111]
	v_mfma_f32_16x16x32_bf16 v[108:111], v[152:155], v[200:203], v[108:111]
	v_mfma_f32_16x16x32_bf16 v[112:115], v[140:143], v[196:199], v[112:115]
	v_mfma_f32_16x16x32_bf16 v[112:115], v[144:147], v[200:203], v[112:115]
	s_barrier
	s_add_i32 s68, s60, s46
	s_mov_b32 m0, s68
	ds_read_b128 v[172:175], v246 offset:16384
	ds_read_b128 v[176:179], v246 offset:17408
	ds_read_b128 v[180:183], v246 offset:18432
	ds_read_b128 v[184:187], v246 offset:19456
	ds_read_b128 v[188:191], v246 offset:20480
	ds_read_b128 v[192:195], v246 offset:21504
	ds_read_b128 v[196:199], v246 offset:22528
	ds_read_b128 v[200:203], v246 offset:23552
	global_load_lds_dwordx4 v210, s[42:43]
	s_add_i32 m0, s68, 0x2000
	s_add_u32 s70, s42, 0x80000
	s_addc_u32 s71, s43, 0
	s_add_i32 s68, s61, s46
	global_load_lds_dwordx4 v214, s[42:43]
	s_mov_b32 m0, s68
	s_nop 0
	global_load_lds_dwordx4 v210, s[70:71]
	s_add_i32 m0, s68, 0x2000
	s_nop 0
	global_load_lds_dwordx4 v214, s[70:71]
	s_mov_b32 m0, s47
	s_nop 0
	global_load_lds_dwordx4 v208, s[50:51]
	s_mov_b32 m0, s48
	s_nop 0
	global_load_lds_dwordx4 v212, s[50:51]
	s_waitcnt vmcnt(8)
	s_waitcnt lgkmcnt(0)
	s_barrier
	v_mfma_f32_16x16x32_bf16 v[72:75], v[140:143], v[172:175], v[72:75]
	v_mfma_f32_16x16x32_bf16 v[72:75], v[144:147], v[176:179], v[72:75]
	v_mfma_f32_16x16x32_bf16 v[68:71], v[148:151], v[172:175], v[68:71]
	v_mfma_f32_16x16x32_bf16 v[68:71], v[152:155], v[176:179], v[68:71]
	v_mfma_f32_16x16x32_bf16 v[40:43], v[156:159], v[172:175], v[40:43]
	v_mfma_f32_16x16x32_bf16 v[40:43], v[160:163], v[176:179], v[40:43]
	v_mfma_f32_16x16x32_bf16 v[36:39], v[164:167], v[172:175], v[36:39]
	v_mfma_f32_16x16x32_bf16 v[36:39], v[168:171], v[176:179], v[36:39]
	v_mfma_f32_16x16x32_bf16 v[28:31], v[164:167], v[180:183], v[28:31]
	v_mfma_f32_16x16x32_bf16 v[28:31], v[168:171], v[184:187], v[28:31]
	v_mfma_f32_16x16x32_bf16 v[32:35], v[156:159], v[180:183], v[32:35]
	v_mfma_f32_16x16x32_bf16 v[32:35], v[160:163], v[184:187], v[32:35]
	v_mfma_f32_16x16x32_bf16 v[60:63], v[148:151], v[180:183], v[60:63]
	v_mfma_f32_16x16x32_bf16 v[60:63], v[152:155], v[184:187], v[60:63]
	v_mfma_f32_16x16x32_bf16 v[64:67], v[140:143], v[180:183], v[64:67]
	v_mfma_f32_16x16x32_bf16 v[64:67], v[144:147], v[184:187], v[64:67]
	v_mfma_f32_16x16x32_bf16 v[56:59], v[140:143], v[188:191], v[56:59]
	v_mfma_f32_16x16x32_bf16 v[56:59], v[144:147], v[192:195], v[56:59]
	v_mfma_f32_16x16x32_bf16 v[52:55], v[148:151], v[188:191], v[52:55]
	v_mfma_f32_16x16x32_bf16 v[52:55], v[152:155], v[192:195], v[52:55]
	v_mfma_f32_16x16x32_bf16 v[24:27], v[156:159], v[188:191], v[24:27]
	v_mfma_f32_16x16x32_bf16 v[24:27], v[160:163], v[192:195], v[24:27]
	v_mfma_f32_16x16x32_bf16 v[20:23], v[164:167], v[188:191], v[20:23]
	v_mfma_f32_16x16x32_bf16 v[20:23], v[168:171], v[192:195], v[20:23]
	v_mfma_f32_16x16x32_bf16 v[12:15], v[164:167], v[196:199], v[12:15]
	v_mfma_f32_16x16x32_bf16 v[12:15], v[168:171], v[200:203], v[12:15]
	v_mfma_f32_16x16x32_bf16 v[16:19], v[156:159], v[196:199], v[16:19]
	v_mfma_f32_16x16x32_bf16 v[16:19], v[160:163], v[200:203], v[16:19]
	v_mfma_f32_16x16x32_bf16 v[44:47], v[148:151], v[196:199], v[44:47]
	v_mfma_f32_16x16x32_bf16 v[44:47], v[152:155], v[200:203], v[44:47]
	v_mfma_f32_16x16x32_bf16 v[48:51], v[140:143], v[196:199], v[48:51]
	v_mfma_f32_16x16x32_bf16 v[48:51], v[144:147], v[200:203], v[48:51]
	s_barrier
	s_add_i32 s68, 0, 0x18000
	v_add_u32_e32 v5, s68, v3
	s_add_i32 s70, 0, 0x1c000
	ds_read_b128 v[140:143], v5
	ds_read_b128 v[144:147], v5 offset:1024
	ds_read_b128 v[148:151], v5 offset:2048
	ds_read_b128 v[152:155], v5 offset:3072
	v_add_u32_e32 v5, s70, v3
	ds_read_b128 v[156:159], v5
	ds_read_b128 v[160:163], v5 offset:1024
	ds_read_b128 v[164:167], v5 offset:2048
	ds_read_b128 v[168:171], v5 offset:3072
	s_add_u32 s98, s50, 0x80000
	s_addc_u32 s99, s51, 0
	s_mov_b64 s[100:101], s[50:51]
	s_mov_b32 m0, s49
	ds_read_b128 v[172:175], v246 offset:32768
	ds_read_b128 v[176:179], v246 offset:33792
	ds_read_b128 v[180:183], v246 offset:34816
	ds_read_b128 v[184:187], v246 offset:35840
	ds_read_b128 v[188:191], v246 offset:36864
	ds_read_b128 v[192:195], v246 offset:37888
	ds_read_b128 v[196:199], v246 offset:38912
	ds_read_b128 v[200:203], v246 offset:39936
	global_load_lds_dwordx4 v208, s[98:99]
	s_mov_b32 m0, s52
	s_nop 0
	global_load_lds_dwordx4 v212, s[98:99]
	s_waitcnt vmcnt(8)
	s_waitcnt lgkmcnt(0)
	s_barrier
	v_mfma_f32_16x16x32_bf16 v[136:139], v[140:143], v[172:175], v[136:139]
	v_mfma_f32_16x16x32_bf16 v[136:139], v[144:147], v[176:179], v[136:139]
	v_mfma_f32_16x16x32_bf16 v[132:135], v[148:151], v[172:175], v[132:135]
	v_mfma_f32_16x16x32_bf16 v[132:135], v[152:155], v[176:179], v[132:135]
	v_mfma_f32_16x16x32_bf16 v[104:107], v[156:159], v[172:175], v[104:107]
	v_mfma_f32_16x16x32_bf16 v[104:107], v[160:163], v[176:179], v[104:107]
	v_mfma_f32_16x16x32_bf16 v[100:103], v[164:167], v[172:175], v[100:103]
	v_mfma_f32_16x16x32_bf16 v[100:103], v[168:171], v[176:179], v[100:103]
	v_mfma_f32_16x16x32_bf16 v[92:95], v[164:167], v[180:183], v[92:95]
	v_mfma_f32_16x16x32_bf16 v[92:95], v[168:171], v[184:187], v[92:95]
	v_mfma_f32_16x16x32_bf16 v[96:99], v[156:159], v[180:183], v[96:99]
	v_mfma_f32_16x16x32_bf16 v[96:99], v[160:163], v[184:187], v[96:99]
	v_mfma_f32_16x16x32_bf16 v[124:127], v[148:151], v[180:183], v[124:127]
	v_mfma_f32_16x16x32_bf16 v[124:127], v[152:155], v[184:187], v[124:127]
	v_mfma_f32_16x16x32_bf16 v[128:131], v[140:143], v[180:183], v[128:131]
	v_mfma_f32_16x16x32_bf16 v[128:131], v[144:147], v[184:187], v[128:131]
	v_mfma_f32_16x16x32_bf16 v[120:123], v[140:143], v[188:191], v[120:123]
	v_mfma_f32_16x16x32_bf16 v[120:123], v[144:147], v[192:195], v[120:123]
	v_mfma_f32_16x16x32_bf16 v[116:119], v[148:151], v[188:191], v[116:119]
	v_mfma_f32_16x16x32_bf16 v[116:119], v[152:155], v[192:195], v[116:119]
	v_mfma_f32_16x16x32_bf16 v[88:91], v[156:159], v[188:191], v[88:91]
	v_mfma_f32_16x16x32_bf16 v[88:91], v[160:163], v[192:195], v[88:91]
	v_mfma_f32_16x16x32_bf16 v[84:87], v[164:167], v[188:191], v[84:87]
	v_mfma_f32_16x16x32_bf16 v[84:87], v[168:171], v[192:195], v[84:87]
	v_mfma_f32_16x16x32_bf16 v[76:79], v[164:167], v[196:199], v[76:79]
	v_mfma_f32_16x16x32_bf16 v[76:79], v[168:171], v[200:203], v[76:79]
	v_mfma_f32_16x16x32_bf16 v[80:83], v[156:159], v[196:199], v[80:83]
	v_mfma_f32_16x16x32_bf16 v[80:83], v[160:163], v[200:203], v[80:83]
	v_mfma_f32_16x16x32_bf16 v[108:111], v[148:151], v[196:199], v[108:111]
	v_mfma_f32_16x16x32_bf16 v[108:111], v[152:155], v[200:203], v[108:111]
	v_mfma_f32_16x16x32_bf16 v[112:115], v[140:143], v[196:199], v[112:115]
	v_mfma_f32_16x16x32_bf16 v[112:115], v[144:147], v[200:203], v[112:115]
	s_barrier
	s_add_i32 s50, s68, s46
	s_add_i32 m0, s50, 0xffffff80
	ds_read_b128 v[172:175], v246 offset:49152
	ds_read_b128 v[176:179], v246 offset:50176
	ds_read_b128 v[180:183], v246 offset:51200
	ds_read_b128 v[184:187], v246 offset:52224
	ds_read_b128 v[188:191], v246 offset:53248
	ds_read_b128 v[192:195], v246 offset:54272
	ds_read_b128 v[196:199], v246 offset:55296
	ds_read_b128 v[200:203], v246 offset:56320
	global_load_lds_dwordx4 v210, s[42:43] offset:128
	s_add_i32 m0, s50, 0x1f80
	s_add_i32 s50, s70, s46
	global_load_lds_dwordx4 v214, s[42:43] offset:128
	s_add_u32 s42, s42, 0x80080
	s_addc_u32 s43, s43, 0
	s_mov_b32 m0, s50
	s_nop 0
	global_load_lds_dwordx4 v210, s[42:43]
	s_add_i32 m0, s50, 0x2000
	s_nop 0
	global_load_lds_dwordx4 v214, s[42:43]
	s_add_i32 m0, s58, 0xffffff80
	s_nop 0
	global_load_lds_dwordx4 v208, s[100:101] offset:128
	s_add_i32 m0, s59, 0xffffff80
	s_nop 0
	global_load_lds_dwordx4 v212, s[100:101] offset:128
	s_waitcnt vmcnt(8)
	s_waitcnt lgkmcnt(0)
	s_barrier
	v_mfma_f32_16x16x32_bf16 v[72:75], v[140:143], v[172:175], v[72:75]
	v_mfma_f32_16x16x32_bf16 v[72:75], v[144:147], v[176:179], v[72:75]
	v_mfma_f32_16x16x32_bf16 v[68:71], v[148:151], v[172:175], v[68:71]
	v_mfma_f32_16x16x32_bf16 v[68:71], v[152:155], v[176:179], v[68:71]
	v_mfma_f32_16x16x32_bf16 v[40:43], v[156:159], v[172:175], v[40:43]
	v_mfma_f32_16x16x32_bf16 v[40:43], v[160:163], v[176:179], v[40:43]
	v_mfma_f32_16x16x32_bf16 v[36:39], v[164:167], v[172:175], v[36:39]
	v_mfma_f32_16x16x32_bf16 v[36:39], v[168:171], v[176:179], v[36:39]
	v_mfma_f32_16x16x32_bf16 v[28:31], v[164:167], v[180:183], v[28:31]
	v_mfma_f32_16x16x32_bf16 v[28:31], v[168:171], v[184:187], v[28:31]
	v_mfma_f32_16x16x32_bf16 v[32:35], v[156:159], v[180:183], v[32:35]
	v_mfma_f32_16x16x32_bf16 v[32:35], v[160:163], v[184:187], v[32:35]
	v_mfma_f32_16x16x32_bf16 v[60:63], v[148:151], v[180:183], v[60:63]
	v_mfma_f32_16x16x32_bf16 v[60:63], v[152:155], v[184:187], v[60:63]
	v_mfma_f32_16x16x32_bf16 v[64:67], v[140:143], v[180:183], v[64:67]
	v_mfma_f32_16x16x32_bf16 v[64:67], v[144:147], v[184:187], v[64:67]
	v_mfma_f32_16x16x32_bf16 v[56:59], v[140:143], v[188:191], v[56:59]
	v_mfma_f32_16x16x32_bf16 v[56:59], v[144:147], v[192:195], v[56:59]
	v_mfma_f32_16x16x32_bf16 v[52:55], v[148:151], v[188:191], v[52:55]
	v_mfma_f32_16x16x32_bf16 v[52:55], v[152:155], v[192:195], v[52:55]
	v_mfma_f32_16x16x32_bf16 v[24:27], v[156:159], v[188:191], v[24:27]
	v_mfma_f32_16x16x32_bf16 v[24:27], v[160:163], v[192:195], v[24:27]
	v_mfma_f32_16x16x32_bf16 v[20:23], v[164:167], v[188:191], v[20:23]
	v_mfma_f32_16x16x32_bf16 v[20:23], v[168:171], v[192:195], v[20:23]
	v_mfma_f32_16x16x32_bf16 v[12:15], v[164:167], v[196:199], v[12:15]
	v_mfma_f32_16x16x32_bf16 v[12:15], v[168:171], v[200:203], v[12:15]
	v_mfma_f32_16x16x32_bf16 v[16:19], v[156:159], v[196:199], v[16:19]
	v_mfma_f32_16x16x32_bf16 v[16:19], v[160:163], v[200:203], v[16:19]
	v_mfma_f32_16x16x32_bf16 v[44:47], v[148:151], v[196:199], v[44:47]
	v_mfma_f32_16x16x32_bf16 v[44:47], v[152:155], v[200:203], v[44:47]
	v_mfma_f32_16x16x32_bf16 v[48:51], v[140:143], v[196:199], v[48:51]
	v_mfma_f32_16x16x32_bf16 v[48:51], v[144:147], v[200:203], v[48:51]
	s_barrier
	s_add_i32 s67, s67, 2
	s_add_u32 s40, s40, 0x100
	s_addc_u32 s41, s41, 0
	s_add_u32 s65, s65, 0x100
	s_addc_u32 s66, s66, 0
	s_cmp_gt_u32 s67, 29
	s_cbranch_scc0 .LBB0_1032
	s_and_b64 vcc, exec, s[22:23]
	s_cbranch_vccz .LBB0_1035
	s_barrier

.LBB0_1203:
	ds_read_b128 v[132:135], v187
	ds_read_b128 v[136:139], v187 offset:1024
	ds_read_b128 v[140:143], v187 offset:2048
	ds_read_b128 v[144:147], v187 offset:3072
	ds_read_b128 v[148:151], v188
	ds_read_b128 v[152:155], v188 offset:1024
	ds_read_b128 v[172:175], v188 offset:2048
	ds_read_b128 v[176:179], v188 offset:3072
	s_add_u32 s0, s42, 0xfff00080
	s_addc_u32 s50, s43, -1
	s_cmp_eq_u32 s65, 60
	s_cselect_b32 s53, s25, s50
	s_cselect_b32 s52, s31, s0
	s_cselect_b32 s51, s23, s64
	s_cselect_b32 s50, s62, s63
	s_add_i32 m0, s41, 0xc000
	ds_read_b128 v[180:183], v189
	ds_read_b128 v[192:195], v189 offset:1024
	ds_read_b128 v[196:199], v189 offset:2048
	ds_read_b128 v[200:203], v189 offset:3072
	ds_read_b128 v[204:207], v189 offset:4096
	ds_read_b128 v[208:211], v189 offset:5120
	ds_read_b128 v[212:215], v189 offset:6144
	ds_read_b128 v[216:219], v189 offset:7168
	global_load_lds_dwordx4 v164, s[42:43]
	s_add_i32 m0, s41, 0xe000
	s_nop 0
	global_load_lds_dwordx4 v166, s[42:43]
	s_waitcnt vmcnt(8)
	s_waitcnt lgkmcnt(0)
	s_barrier
	v_mfma_f32_16x16x32_bf16 v[128:131], v[132:135], v[180:183], v[128:131]
	v_mfma_f32_16x16x32_bf16 v[128:131], v[136:139], v[192:195], v[128:131]
	v_mfma_f32_16x16x32_bf16 v[124:127], v[140:143], v[180:183], v[124:127]
	v_mfma_f32_16x16x32_bf16 v[124:127], v[144:147], v[192:195], v[124:127]
	v_mfma_f32_16x16x32_bf16 v[120:123], v[148:151], v[180:183], v[120:123]
	v_mfma_f32_16x16x32_bf16 v[120:123], v[152:155], v[192:195], v[120:123]
	v_mfma_f32_16x16x32_bf16 v[116:119], v[172:175], v[180:183], v[116:119]
	v_mfma_f32_16x16x32_bf16 v[116:119], v[176:179], v[192:195], v[116:119]
	v_mfma_f32_16x16x32_bf16 v[100:103], v[172:175], v[196:199], v[100:103]
	v_mfma_f32_16x16x32_bf16 v[100:103], v[176:179], v[200:203], v[100:103]
	v_mfma_f32_16x16x32_bf16 v[104:107], v[148:151], v[196:199], v[104:107]
	v_mfma_f32_16x16x32_bf16 v[104:107], v[152:155], v[200:203], v[104:107]
	v_mfma_f32_16x16x32_bf16 v[108:111], v[140:143], v[196:199], v[108:111]
	v_mfma_f32_16x16x32_bf16 v[108:111], v[144:147], v[200:203], v[108:111]
	v_mfma_f32_16x16x32_bf16 v[112:115], v[132:135], v[196:199], v[112:115]
	v_mfma_f32_16x16x32_bf16 v[112:115], v[136:139], v[200:203], v[112:115]
	v_mfma_f32_16x16x32_bf16 v[96:99], v[132:135], v[204:207], v[96:99]
	v_mfma_f32_16x16x32_bf16 v[96:99], v[136:139], v[208:211], v[96:99]
	v_mfma_f32_16x16x32_bf16 v[92:95], v[140:143], v[204:207], v[92:95]
	v_mfma_f32_16x16x32_bf16 v[92:95], v[144:147], v[208:211], v[92:95]
	v_mfma_f32_16x16x32_bf16 v[88:91], v[148:151], v[204:207], v[88:91]
	v_mfma_f32_16x16x32_bf16 v[88:91], v[152:155], v[208:211], v[88:91]
	v_mfma_f32_16x16x32_bf16 v[84:87], v[172:175], v[204:207], v[84:87]
	v_mfma_f32_16x16x32_bf16 v[84:87], v[176:179], v[208:211], v[84:87]
	v_mfma_f32_16x16x32_bf16 v[68:71], v[172:175], v[212:215], v[68:71]
	v_mfma_f32_16x16x32_bf16 v[68:71], v[176:179], v[216:219], v[68:71]
	v_mfma_f32_16x16x32_bf16 v[72:75], v[148:151], v[212:215], v[72:75]
	v_mfma_f32_16x16x32_bf16 v[72:75], v[152:155], v[216:219], v[72:75]
	v_mfma_f32_16x16x32_bf16 v[76:79], v[140:143], v[212:215], v[76:79]
	v_mfma_f32_16x16x32_bf16 v[76:79], v[144:147], v[216:219], v[76:79]
	v_mfma_f32_16x16x32_bf16 v[80:83], v[132:135], v[212:215], v[80:83]
	v_mfma_f32_16x16x32_bf16 v[80:83], v[136:139], v[216:219], v[80:83]
	s_barrier
	s_add_i32 s0, s59, s46
	s_mov_b32 m0, s0
	ds_read_b128 v[180:183], v189 offset:16384
	ds_read_b128 v[192:195], v189 offset:17408
	ds_read_b128 v[196:199], v189 offset:18432
	ds_read_b128 v[200:203], v189 offset:19456
	ds_read_b128 v[204:207], v189 offset:20480
	ds_read_b128 v[208:211], v189 offset:21504
	ds_read_b128 v[212:215], v189 offset:22528
	ds_read_b128 v[216:219], v189 offset:23552
	global_load_lds_dwordx4 v158, s[50:51]
	s_add_i32 m0, s0, 0x2000
	s_add_u32 s66, s50, 0x100000
	s_addc_u32 s67, s51, 0
	s_add_i32 s0, s60, s46
	global_load_lds_dwordx4 v162, s[50:51]
	s_mov_b32 m0, s0
	s_nop 0
	global_load_lds_dwordx4 v158, s[66:67]
	s_add_i32 m0, s0, 0x2000
	s_nop 0
	global_load_lds_dwordx4 v162, s[66:67]
	s_mov_b32 m0, s41
	s_nop 0
	global_load_lds_dwordx4 v156, s[52:53]
	s_mov_b32 m0, s47
	s_nop 0
	global_load_lds_dwordx4 v160, s[52:53]
	s_waitcnt vmcnt(8)
	s_waitcnt lgkmcnt(0)
	s_barrier
	v_mfma_f32_16x16x32_bf16 v[64:67], v[132:135], v[180:183], v[64:67]
	v_mfma_f32_16x16x32_bf16 v[64:67], v[136:139], v[192:195], v[64:67]
	v_mfma_f32_16x16x32_bf16 v[60:63], v[140:143], v[180:183], v[60:63]
	v_mfma_f32_16x16x32_bf16 v[60:63], v[144:147], v[192:195], v[60:63]
	v_mfma_f32_16x16x32_bf16 v[56:59], v[148:151], v[180:183], v[56:59]
	v_mfma_f32_16x16x32_bf16 v[56:59], v[152:155], v[192:195], v[56:59]
	v_mfma_f32_16x16x32_bf16 v[52:55], v[172:175], v[180:183], v[52:55]
	v_mfma_f32_16x16x32_bf16 v[52:55], v[176:179], v[192:195], v[52:55]
	v_mfma_f32_16x16x32_bf16 v[36:39], v[172:175], v[196:199], v[36:39]
	v_mfma_f32_16x16x32_bf16 v[36:39], v[176:179], v[200:203], v[36:39]
	v_mfma_f32_16x16x32_bf16 v[40:43], v[148:151], v[196:199], v[40:43]
	v_mfma_f32_16x16x32_bf16 v[40:43], v[152:155], v[200:203], v[40:43]
	v_mfma_f32_16x16x32_bf16 v[44:47], v[140:143], v[196:199], v[44:47]
	v_mfma_f32_16x16x32_bf16 v[44:47], v[144:147], v[200:203], v[44:47]
	v_mfma_f32_16x16x32_bf16 v[48:51], v[132:135], v[196:199], v[48:51]
	v_mfma_f32_16x16x32_bf16 v[48:51], v[136:139], v[200:203], v[48:51]
	v_mfma_f32_16x16x32_bf16 v[32:35], v[132:135], v[204:207], v[32:35]
	v_mfma_f32_16x16x32_bf16 v[32:35], v[136:139], v[208:211], v[32:35]
	v_mfma_f32_16x16x32_bf16 v[28:31], v[140:143], v[204:207], v[28:31]
	v_mfma_f32_16x16x32_bf16 v[28:31], v[144:147], v[208:211], v[28:31]
	v_mfma_f32_16x16x32_bf16 v[24:27], v[148:151], v[204:207], v[24:27]
	v_mfma_f32_16x16x32_bf16 v[24:27], v[152:155], v[208:211], v[24:27]
	v_mfma_f32_16x16x32_bf16 v[20:23], v[172:175], v[204:207], v[20:23]
	v_mfma_f32_16x16x32_bf16 v[20:23], v[176:179], v[208:211], v[20:23]
	v_mfma_f32_16x16x32_bf16 v[4:7], v[172:175], v[212:215], v[4:7]
	v_mfma_f32_16x16x32_bf16 v[4:7], v[176:179], v[216:219], v[4:7]
	v_mfma_f32_16x16x32_bf16 v[8:11], v[148:151], v[212:215], v[8:11]
	v_mfma_f32_16x16x32_bf16 v[8:11], v[152:155], v[216:219], v[8:11]
	v_mfma_f32_16x16x32_bf16 v[12:15], v[140:143], v[212:215], v[12:15]
	v_mfma_f32_16x16x32_bf16 v[12:15], v[144:147], v[216:219], v[12:15]
	v_mfma_f32_16x16x32_bf16 v[16:19], v[132:135], v[212:215], v[16:19]
	v_mfma_f32_16x16x32_bf16 v[16:19], v[136:139], v[216:219], v[16:19]
	s_barrier
	s_add_i32 s0, 0, 0x18000
	s_add_i32 s66, 0, 0x1c000
	v_add_u32_e32 v144, s0, v3
	v_add_u32_e32 v176, s66, v3
	ds_read_b128 v[132:135], v144
	ds_read_b128 v[136:139], v144 offset:1024
	ds_read_b128 v[140:143], v144 offset:2048
	ds_read_b128 v[144:147], v144 offset:3072
	ds_read_b128 v[148:151], v176
	ds_read_b128 v[152:155], v176 offset:1024
	ds_read_b128 v[172:175], v176 offset:2048
	ds_read_b128 v[176:179], v176 offset:3072
	s_add_u32 s98, s52, 0x100000
	s_addc_u32 s99, s53, 0
	s_mov_b32 m0, s48
	ds_read_b128 v[180:183], v189 offset:32768
	ds_read_b128 v[192:195], v189 offset:33792
	ds_read_b128 v[196:199], v189 offset:34816
	ds_read_b128 v[200:203], v189 offset:35840
	ds_read_b128 v[204:207], v189 offset:36864
	ds_read_b128 v[208:211], v189 offset:37888
	ds_read_b128 v[212:215], v189 offset:38912
	ds_read_b128 v[216:219], v189 offset:39936
	global_load_lds_dwordx4 v156, s[98:99]
	s_mov_b32 m0, s49
	s_nop 0
	global_load_lds_dwordx4 v160, s[98:99]
	s_waitcnt vmcnt(8)
	s_waitcnt lgkmcnt(0)
	s_barrier
	v_mfma_f32_16x16x32_bf16 v[128:131], v[132:135], v[180:183], v[128:131]
	v_mfma_f32_16x16x32_bf16 v[128:131], v[136:139], v[192:195], v[128:131]
	v_mfma_f32_16x16x32_bf16 v[124:127], v[140:143], v[180:183], v[124:127]
	v_mfma_f32_16x16x32_bf16 v[124:127], v[144:147], v[192:195], v[124:127]
	v_mfma_f32_16x16x32_bf16 v[120:123], v[148:151], v[180:183], v[120:123]
	v_mfma_f32_16x16x32_bf16 v[120:123], v[152:155], v[192:195], v[120:123]
	v_mfma_f32_16x16x32_bf16 v[116:119], v[172:175], v[180:183], v[116:119]
	v_mfma_f32_16x16x32_bf16 v[116:119], v[176:179], v[192:195], v[116:119]
	v_mfma_f32_16x16x32_bf16 v[100:103], v[172:175], v[196:199], v[100:103]
	v_mfma_f32_16x16x32_bf16 v[100:103], v[176:179], v[200:203], v[100:103]
	v_mfma_f32_16x16x32_bf16 v[104:107], v[148:151], v[196:199], v[104:107]
	v_mfma_f32_16x16x32_bf16 v[104:107], v[152:155], v[200:203], v[104:107]
	v_mfma_f32_16x16x32_bf16 v[108:111], v[140:143], v[196:199], v[108:111]
	v_mfma_f32_16x16x32_bf16 v[108:111], v[144:147], v[200:203], v[108:111]
	v_mfma_f32_16x16x32_bf16 v[112:115], v[132:135], v[196:199], v[112:115]
	v_mfma_f32_16x16x32_bf16 v[112:115], v[136:139], v[200:203], v[112:115]
	v_mfma_f32_16x16x32_bf16 v[96:99], v[132:135], v[204:207], v[96:99]
	v_mfma_f32_16x16x32_bf16 v[96:99], v[136:139], v[208:211], v[96:99]
	v_mfma_f32_16x16x32_bf16 v[92:95], v[140:143], v[204:207], v[92:95]
	v_mfma_f32_16x16x32_bf16 v[92:95], v[144:147], v[208:211], v[92:95]
	v_mfma_f32_16x16x32_bf16 v[88:91], v[148:151], v[204:207], v[88:91]
	v_mfma_f32_16x16x32_bf16 v[88:91], v[152:155], v[208:211], v[88:91]
	v_mfma_f32_16x16x32_bf16 v[84:87], v[172:175], v[204:207], v[84:87]
	v_mfma_f32_16x16x32_bf16 v[84:87], v[176:179], v[208:211], v[84:87]
	v_mfma_f32_16x16x32_bf16 v[68:71], v[172:175], v[212:215], v[68:71]
	v_mfma_f32_16x16x32_bf16 v[68:71], v[176:179], v[216:219], v[68:71]
	v_mfma_f32_16x16x32_bf16 v[72:75], v[148:151], v[212:215], v[72:75]
	v_mfma_f32_16x16x32_bf16 v[72:75], v[152:155], v[216:219], v[72:75]
	v_mfma_f32_16x16x32_bf16 v[76:79], v[140:143], v[212:215], v[76:79]
	v_mfma_f32_16x16x32_bf16 v[76:79], v[144:147], v[216:219], v[76:79]
	v_mfma_f32_16x16x32_bf16 v[80:83], v[132:135], v[212:215], v[80:83]
	v_mfma_f32_16x16x32_bf16 v[80:83], v[136:139], v[216:219], v[80:83]
	s_barrier
	s_add_i32 s0, s0, s46
	s_add_i32 m0, s0, 0xffffff80
	ds_read_b128 v[180:183], v189 offset:49152
	ds_read_b128 v[192:195], v189 offset:50176
	ds_read_b128 v[196:199], v189 offset:51200
	ds_read_b128 v[200:203], v189 offset:52224
	ds_read_b128 v[204:207], v189 offset:53248
	ds_read_b128 v[208:211], v189 offset:54272
	ds_read_b128 v[212:215], v189 offset:55296
	ds_read_b128 v[216:219], v189 offset:56320
	global_load_lds_dwordx4 v158, s[50:51] offset:128
	s_add_i32 m0, s0, 0x1f80
	s_add_i32 s0, s66, s46
	global_load_lds_dwordx4 v162, s[50:51] offset:128
	s_add_u32 s50, s50, 0x100080
	s_addc_u32 s51, s51, 0
	s_mov_b32 m0, s0
	s_nop 0
	global_load_lds_dwordx4 v158, s[50:51]
	s_add_i32 m0, s0, 0x2000
	s_nop 0
	global_load_lds_dwordx4 v162, s[50:51]
	s_add_i32 m0, s57, 0xffffff80
	s_nop 0
	global_load_lds_dwordx4 v156, s[52:53] offset:128
	s_add_i32 m0, s58, 0xffffff80
	s_nop 0
	global_load_lds_dwordx4 v160, s[52:53] offset:128
	s_waitcnt vmcnt(8)
	s_waitcnt lgkmcnt(0)
	s_barrier
	v_mfma_f32_16x16x32_bf16 v[64:67], v[132:135], v[180:183], v[64:67]
	v_mfma_f32_16x16x32_bf16 v[64:67], v[136:139], v[192:195], v[64:67]
	v_mfma_f32_16x16x32_bf16 v[60:63], v[140:143], v[180:183], v[60:63]
	v_mfma_f32_16x16x32_bf16 v[60:63], v[144:147], v[192:195], v[60:63]
	v_mfma_f32_16x16x32_bf16 v[56:59], v[148:151], v[180:183], v[56:59]
	v_mfma_f32_16x16x32_bf16 v[56:59], v[152:155], v[192:195], v[56:59]
	v_mfma_f32_16x16x32_bf16 v[52:55], v[172:175], v[180:183], v[52:55]
	v_mfma_f32_16x16x32_bf16 v[52:55], v[176:179], v[192:195], v[52:55]
	v_mfma_f32_16x16x32_bf16 v[36:39], v[172:175], v[196:199], v[36:39]
	v_mfma_f32_16x16x32_bf16 v[36:39], v[176:179], v[200:203], v[36:39]
	v_mfma_f32_16x16x32_bf16 v[40:43], v[148:151], v[196:199], v[40:43]
	v_mfma_f32_16x16x32_bf16 v[40:43], v[152:155], v[200:203], v[40:43]
	v_mfma_f32_16x16x32_bf16 v[44:47], v[140:143], v[196:199], v[44:47]
	v_mfma_f32_16x16x32_bf16 v[44:47], v[144:147], v[200:203], v[44:47]
	v_mfma_f32_16x16x32_bf16 v[48:51], v[132:135], v[196:199], v[48:51]
	v_mfma_f32_16x16x32_bf16 v[48:51], v[136:139], v[200:203], v[48:51]
	v_mfma_f32_16x16x32_bf16 v[32:35], v[132:135], v[204:207], v[32:35]
	v_mfma_f32_16x16x32_bf16 v[32:35], v[136:139], v[208:211], v[32:35]
	v_mfma_f32_16x16x32_bf16 v[28:31], v[140:143], v[204:207], v[28:31]
	v_mfma_f32_16x16x32_bf16 v[28:31], v[144:147], v[208:211], v[28:31]
	v_mfma_f32_16x16x32_bf16 v[24:27], v[148:151], v[204:207], v[24:27]
	v_mfma_f32_16x16x32_bf16 v[24:27], v[152:155], v[208:211], v[24:27]
	v_mfma_f32_16x16x32_bf16 v[20:23], v[172:175], v[204:207], v[20:23]
	v_mfma_f32_16x16x32_bf16 v[20:23], v[176:179], v[208:211], v[20:23]
	v_mfma_f32_16x16x32_bf16 v[4:7], v[172:175], v[212:215], v[4:7]
	v_mfma_f32_16x16x32_bf16 v[4:7], v[176:179], v[216:219], v[4:7]
	v_mfma_f32_16x16x32_bf16 v[8:11], v[148:151], v[212:215], v[8:11]
	v_mfma_f32_16x16x32_bf16 v[8:11], v[152:155], v[216:219], v[8:11]
	v_mfma_f32_16x16x32_bf16 v[12:15], v[140:143], v[212:215], v[12:15]
	v_mfma_f32_16x16x32_bf16 v[12:15], v[144:147], v[216:219], v[12:15]
	v_mfma_f32_16x16x32_bf16 v[16:19], v[132:135], v[212:215], v[16:19]
	v_mfma_f32_16x16x32_bf16 v[16:19], v[136:139], v[216:219], v[16:19]
	s_barrier
	s_add_i32 s65, s65, 2
	s_add_u32 s42, s42, 0x100
	s_addc_u32 s43, s43, 0
	s_add_u32 s63, s63, 0x100
	s_addc_u32 s64, s64, 0
	s_cmp_gt_u32 s65, 61
	s_cbranch_scc0 .LBB0_1203
	s_and_b64 vcc, exec, s[20:21]
	s_cbranch_vccz .LBB0_1206
	s_barrier

.LBB0_1288:
	ds_read_b128 v[154:157], v150
	ds_read_b128 v[158:161], v150 offset:1024
	ds_read_b128 v[162:165], v150 offset:2048
	ds_read_b128 v[166:169], v150 offset:3072
	ds_read_b128 v[170:173], v151
	ds_read_b128 v[174:177], v151 offset:1024
	ds_read_b128 v[178:181], v151 offset:2048
	ds_read_b128 v[182:185], v151 offset:3072
	s_add_u32 s0, s42, 0xfff00080
	s_addc_u32 s50, s43, -1
	s_cmp_eq_u32 s70, 12
	s_cselect_b32 s53, s29, s50
	s_cselect_b32 s52, s28, s0
	s_cselect_b32 s51, s5, s41
	s_cselect_b32 s50, s4, s31
	s_add_i32 m0, s17, 0xc000
	ds_read_b128 v[186:189], v152
	ds_read_b128 v[190:193], v152 offset:1024
	ds_read_b128 v[194:197], v152 offset:2048
	ds_read_b128 v[198:201], v152 offset:3072
	ds_read_b128 v[202:205], v152 offset:4096
	ds_read_b128 v[206:209], v152 offset:5120
	ds_read_b128 v[210:213], v152 offset:6144
	ds_read_b128 v[214:217], v152 offset:7168
	global_load_lds_dwordx4 v142, s[42:43]
	s_add_i32 m0, s17, 0xe000
	s_nop 0
	global_load_lds_dwordx4 v144, s[42:43]
	s_waitcnt vmcnt(8)
	s_waitcnt lgkmcnt(0)
	s_barrier
	v_mfma_f32_16x16x32_bf16 v[128:131], v[154:157], v[186:189], v[128:131]
	v_mfma_f32_16x16x32_bf16 v[128:131], v[158:161], v[190:193], v[128:131]
	v_mfma_f32_16x16x32_bf16 v[124:127], v[162:165], v[186:189], v[124:127]
	v_mfma_f32_16x16x32_bf16 v[124:127], v[166:169], v[190:193], v[124:127]
	v_mfma_f32_16x16x32_bf16 v[112:115], v[170:173], v[186:189], v[112:115]
	v_mfma_f32_16x16x32_bf16 v[112:115], v[174:177], v[190:193], v[112:115]
	v_mfma_f32_16x16x32_bf16 v[108:111], v[178:181], v[186:189], v[108:111]
	v_mfma_f32_16x16x32_bf16 v[108:111], v[182:185], v[190:193], v[108:111]
	v_mfma_f32_16x16x32_bf16 v[92:95], v[178:181], v[194:197], v[92:95]
	v_mfma_f32_16x16x32_bf16 v[92:95], v[182:185], v[198:201], v[92:95]
	v_mfma_f32_16x16x32_bf16 v[96:99], v[170:173], v[194:197], v[96:99]
	v_mfma_f32_16x16x32_bf16 v[96:99], v[174:177], v[198:201], v[96:99]
	v_mfma_f32_16x16x32_bf16 v[116:119], v[162:165], v[194:197], v[116:119]
	v_mfma_f32_16x16x32_bf16 v[116:119], v[166:169], v[198:201], v[116:119]
	v_mfma_f32_16x16x32_bf16 v[120:123], v[154:157], v[194:197], v[120:123]
	v_mfma_f32_16x16x32_bf16 v[120:123], v[158:161], v[198:201], v[120:123]
	v_mfma_f32_16x16x32_bf16 v[104:107], v[154:157], v[202:205], v[104:107]
	v_mfma_f32_16x16x32_bf16 v[104:107], v[158:161], v[206:209], v[104:107]
	v_mfma_f32_16x16x32_bf16 v[100:103], v[162:165], v[202:205], v[100:103]
	v_mfma_f32_16x16x32_bf16 v[100:103], v[166:169], v[206:209], v[100:103]
	v_mfma_f32_16x16x32_bf16 v[80:83], v[170:173], v[202:205], v[80:83]
	v_mfma_f32_16x16x32_bf16 v[80:83], v[174:177], v[206:209], v[80:83]
	v_mfma_f32_16x16x32_bf16 v[76:79], v[178:181], v[202:205], v[76:79]
	v_mfma_f32_16x16x32_bf16 v[76:79], v[182:185], v[206:209], v[76:79]
	v_mfma_f32_16x16x32_bf16 v[68:71], v[178:181], v[210:213], v[68:71]
	v_mfma_f32_16x16x32_bf16 v[68:71], v[182:185], v[214:217], v[68:71]
	v_mfma_f32_16x16x32_bf16 v[72:75], v[170:173], v[210:213], v[72:75]
	v_mfma_f32_16x16x32_bf16 v[72:75], v[174:177], v[214:217], v[72:75]
	v_mfma_f32_16x16x32_bf16 v[84:87], v[162:165], v[210:213], v[84:87]
	v_mfma_f32_16x16x32_bf16 v[84:87], v[166:169], v[214:217], v[84:87]
	v_mfma_f32_16x16x32_bf16 v[88:91], v[154:157], v[210:213], v[88:91]
	v_mfma_f32_16x16x32_bf16 v[88:91], v[158:161], v[214:217], v[88:91]
	s_barrier
	s_add_i32 s0, s60, s46
	s_mov_b32 m0, s0
	ds_read_b128 v[186:189], v152 offset:16384
	ds_read_b128 v[190:193], v152 offset:17408
	ds_read_b128 v[194:197], v152 offset:18432
	ds_read_b128 v[198:201], v152 offset:19456
	ds_read_b128 v[202:205], v152 offset:20480
	ds_read_b128 v[206:209], v152 offset:21504
	ds_read_b128 v[210:213], v152 offset:22528
	ds_read_b128 v[214:217], v152 offset:23552
	global_load_lds_dwordx4 v136, s[50:51]
	s_add_i32 m0, s0, 0x2000
	s_add_u32 s72, s50, 0x100000
	s_addc_u32 s73, s51, 0
	s_add_i32 s0, s61, s46
	global_load_lds_dwordx4 v132, s[50:51]
	s_mov_b32 m0, s0
	s_nop 0
	global_load_lds_dwordx4 v136, s[72:73]
	s_add_i32 m0, s0, 0x2000
	s_nop 0
	global_load_lds_dwordx4 v132, s[72:73]
	s_mov_b32 m0, s17
	s_nop 0
	global_load_lds_dwordx4 v138, s[52:53]
	s_mov_b32 m0, s47
	s_nop 0
	global_load_lds_dwordx4 v134, s[52:53]
	s_waitcnt vmcnt(8)
	s_waitcnt lgkmcnt(0)
	s_barrier
	v_mfma_f32_16x16x32_bf16 v[64:67], v[154:157], v[186:189], v[64:67]
	v_mfma_f32_16x16x32_bf16 v[64:67], v[158:161], v[190:193], v[64:67]
	v_mfma_f32_16x16x32_bf16 v[60:63], v[162:165], v[186:189], v[60:63]
	v_mfma_f32_16x16x32_bf16 v[60:63], v[166:169], v[190:193], v[60:63]
	v_mfma_f32_16x16x32_bf16 v[48:51], v[170:173], v[186:189], v[48:51]
	v_mfma_f32_16x16x32_bf16 v[48:51], v[174:177], v[190:193], v[48:51]
	v_mfma_f32_16x16x32_bf16 v[44:47], v[178:181], v[186:189], v[44:47]
	v_mfma_f32_16x16x32_bf16 v[44:47], v[182:185], v[190:193], v[44:47]
	v_mfma_f32_16x16x32_bf16 v[28:31], v[178:181], v[194:197], v[28:31]
	v_mfma_f32_16x16x32_bf16 v[28:31], v[182:185], v[198:201], v[28:31]
	v_mfma_f32_16x16x32_bf16 v[32:35], v[170:173], v[194:197], v[32:35]
	v_mfma_f32_16x16x32_bf16 v[32:35], v[174:177], v[198:201], v[32:35]
	v_mfma_f32_16x16x32_bf16 v[52:55], v[162:165], v[194:197], v[52:55]
	v_mfma_f32_16x16x32_bf16 v[52:55], v[166:169], v[198:201], v[52:55]
	v_mfma_f32_16x16x32_bf16 v[56:59], v[154:157], v[194:197], v[56:59]
	v_mfma_f32_16x16x32_bf16 v[56:59], v[158:161], v[198:201], v[56:59]
	v_mfma_f32_16x16x32_bf16 v[40:43], v[154:157], v[202:205], v[40:43]
	v_mfma_f32_16x16x32_bf16 v[40:43], v[158:161], v[206:209], v[40:43]
	v_mfma_f32_16x16x32_bf16 v[36:39], v[162:165], v[202:205], v[36:39]
	v_mfma_f32_16x16x32_bf16 v[36:39], v[166:169], v[206:209], v[36:39]
	v_mfma_f32_16x16x32_bf16 v[16:19], v[170:173], v[202:205], v[16:19]
	v_mfma_f32_16x16x32_bf16 v[16:19], v[174:177], v[206:209], v[16:19]
	v_mfma_f32_16x16x32_bf16 v[12:15], v[178:181], v[202:205], v[12:15]
	v_mfma_f32_16x16x32_bf16 v[12:15], v[182:185], v[206:209], v[12:15]
	v_mfma_f32_16x16x32_bf16 v[4:7], v[178:181], v[210:213], v[4:7]
	v_mfma_f32_16x16x32_bf16 v[4:7], v[182:185], v[214:217], v[4:7]
	v_mfma_f32_16x16x32_bf16 v[8:11], v[170:173], v[210:213], v[8:11]
	v_mfma_f32_16x16x32_bf16 v[8:11], v[174:177], v[214:217], v[8:11]
	v_mfma_f32_16x16x32_bf16 v[20:23], v[162:165], v[210:213], v[20:23]
	v_mfma_f32_16x16x32_bf16 v[20:23], v[166:169], v[214:217], v[20:23]
	v_mfma_f32_16x16x32_bf16 v[24:27], v[154:157], v[210:213], v[24:27]
	v_mfma_f32_16x16x32_bf16 v[24:27], v[158:161], v[214:217], v[24:27]
	s_barrier
	s_add_i32 s0, 0, 0x18000
	v_add_u32_e32 v140, s0, v3
	s_add_i32 s71, 0, 0x1c000
	ds_read_b128 v[154:157], v140
	ds_read_b128 v[158:161], v140 offset:1024
	ds_read_b128 v[162:165], v140 offset:2048
	ds_read_b128 v[166:169], v140 offset:3072
	v_add_u32_e32 v140, s71, v3
	ds_read_b128 v[170:173], v140
	ds_read_b128 v[174:177], v140 offset:1024
	ds_read_b128 v[178:181], v140 offset:2048
	ds_read_b128 v[182:185], v140 offset:3072
	s_add_u32 s98, s52, 0x100000
	s_addc_u32 s99, s53, 0
	s_mov_b32 m0, s48
	ds_read_b128 v[186:189], v152 offset:32768
	ds_read_b128 v[190:193], v152 offset:33792
	ds_read_b128 v[194:197], v152 offset:34816
	ds_read_b128 v[198:201], v152 offset:35840
	ds_read_b128 v[202:205], v152 offset:36864
	ds_read_b128 v[206:209], v152 offset:37888
	ds_read_b128 v[210:213], v152 offset:38912
	ds_read_b128 v[214:217], v152 offset:39936
	global_load_lds_dwordx4 v138, s[98:99]
	s_mov_b32 m0, s49
	s_nop 0
	global_load_lds_dwordx4 v134, s[98:99]
	s_waitcnt vmcnt(8)
	s_waitcnt lgkmcnt(0)
	s_barrier
	v_mfma_f32_16x16x32_bf16 v[128:131], v[154:157], v[186:189], v[128:131]
	v_mfma_f32_16x16x32_bf16 v[128:131], v[158:161], v[190:193], v[128:131]
	v_mfma_f32_16x16x32_bf16 v[124:127], v[162:165], v[186:189], v[124:127]
	v_mfma_f32_16x16x32_bf16 v[124:127], v[166:169], v[190:193], v[124:127]
	v_mfma_f32_16x16x32_bf16 v[112:115], v[170:173], v[186:189], v[112:115]
	v_mfma_f32_16x16x32_bf16 v[112:115], v[174:177], v[190:193], v[112:115]
	v_mfma_f32_16x16x32_bf16 v[108:111], v[178:181], v[186:189], v[108:111]
	v_mfma_f32_16x16x32_bf16 v[108:111], v[182:185], v[190:193], v[108:111]
	v_mfma_f32_16x16x32_bf16 v[92:95], v[178:181], v[194:197], v[92:95]
	v_mfma_f32_16x16x32_bf16 v[92:95], v[182:185], v[198:201], v[92:95]
	v_mfma_f32_16x16x32_bf16 v[96:99], v[170:173], v[194:197], v[96:99]
	v_mfma_f32_16x16x32_bf16 v[96:99], v[174:177], v[198:201], v[96:99]
	v_mfma_f32_16x16x32_bf16 v[116:119], v[162:165], v[194:197], v[116:119]
	v_mfma_f32_16x16x32_bf16 v[116:119], v[166:169], v[198:201], v[116:119]
	v_mfma_f32_16x16x32_bf16 v[120:123], v[154:157], v[194:197], v[120:123]
	v_mfma_f32_16x16x32_bf16 v[120:123], v[158:161], v[198:201], v[120:123]
	v_mfma_f32_16x16x32_bf16 v[104:107], v[154:157], v[202:205], v[104:107]
	v_mfma_f32_16x16x32_bf16 v[104:107], v[158:161], v[206:209], v[104:107]
	v_mfma_f32_16x16x32_bf16 v[100:103], v[162:165], v[202:205], v[100:103]
	v_mfma_f32_16x16x32_bf16 v[100:103], v[166:169], v[206:209], v[100:103]
	v_mfma_f32_16x16x32_bf16 v[80:83], v[170:173], v[202:205], v[80:83]
	v_mfma_f32_16x16x32_bf16 v[80:83], v[174:177], v[206:209], v[80:83]
	v_mfma_f32_16x16x32_bf16 v[76:79], v[178:181], v[202:205], v[76:79]
	v_mfma_f32_16x16x32_bf16 v[76:79], v[182:185], v[206:209], v[76:79]
	v_mfma_f32_16x16x32_bf16 v[68:71], v[178:181], v[210:213], v[68:71]
	v_mfma_f32_16x16x32_bf16 v[68:71], v[182:185], v[214:217], v[68:71]
	v_mfma_f32_16x16x32_bf16 v[72:75], v[170:173], v[210:213], v[72:75]
	v_mfma_f32_16x16x32_bf16 v[72:75], v[174:177], v[214:217], v[72:75]
	v_mfma_f32_16x16x32_bf16 v[84:87], v[162:165], v[210:213], v[84:87]
	v_mfma_f32_16x16x32_bf16 v[84:87], v[166:169], v[214:217], v[84:87]
	v_mfma_f32_16x16x32_bf16 v[88:91], v[154:157], v[210:213], v[88:91]
	v_mfma_f32_16x16x32_bf16 v[88:91], v[158:161], v[214:217], v[88:91]
	s_barrier
	s_add_i32 s0, s0, s46
	s_add_i32 m0, s0, 0xffffff80
	ds_read_b128 v[186:189], v152 offset:49152
	ds_read_b128 v[190:193], v152 offset:50176
	ds_read_b128 v[194:197], v152 offset:51200
	ds_read_b128 v[198:201], v152 offset:52224
	ds_read_b128 v[202:205], v152 offset:53248
	ds_read_b128 v[206:209], v152 offset:54272
	ds_read_b128 v[210:213], v152 offset:55296
	ds_read_b128 v[214:217], v152 offset:56320
	global_load_lds_dwordx4 v136, s[50:51] offset:128
	s_add_i32 m0, s0, 0x1f80
	s_add_i32 s0, s71, s46
	global_load_lds_dwordx4 v132, s[50:51] offset:128
	s_add_u32 s50, s50, 0x100080
	s_addc_u32 s51, s51, 0
	s_mov_b32 m0, s0
	s_nop 0
	global_load_lds_dwordx4 v136, s[50:51]
	s_add_i32 m0, s0, 0x2000
	s_nop 0
	global_load_lds_dwordx4 v132, s[50:51]
	s_add_i32 m0, s58, 0xffffff80
	s_nop 0
	global_load_lds_dwordx4 v138, s[52:53] offset:128
	s_add_i32 m0, s59, 0xffffff80
	s_nop 0
	global_load_lds_dwordx4 v134, s[52:53] offset:128
	s_waitcnt vmcnt(8)
	s_waitcnt lgkmcnt(0)
	s_barrier
	v_mfma_f32_16x16x32_bf16 v[64:67], v[154:157], v[186:189], v[64:67]
	v_mfma_f32_16x16x32_bf16 v[64:67], v[158:161], v[190:193], v[64:67]
	v_mfma_f32_16x16x32_bf16 v[60:63], v[162:165], v[186:189], v[60:63]
	v_mfma_f32_16x16x32_bf16 v[60:63], v[166:169], v[190:193], v[60:63]
	v_mfma_f32_16x16x32_bf16 v[48:51], v[170:173], v[186:189], v[48:51]
	v_mfma_f32_16x16x32_bf16 v[48:51], v[174:177], v[190:193], v[48:51]
	v_mfma_f32_16x16x32_bf16 v[44:47], v[178:181], v[186:189], v[44:47]
	v_mfma_f32_16x16x32_bf16 v[44:47], v[182:185], v[190:193], v[44:47]
	v_mfma_f32_16x16x32_bf16 v[28:31], v[178:181], v[194:197], v[28:31]
	v_mfma_f32_16x16x32_bf16 v[28:31], v[182:185], v[198:201], v[28:31]
	v_mfma_f32_16x16x32_bf16 v[32:35], v[170:173], v[194:197], v[32:35]
	v_mfma_f32_16x16x32_bf16 v[32:35], v[174:177], v[198:201], v[32:35]
	v_mfma_f32_16x16x32_bf16 v[52:55], v[162:165], v[194:197], v[52:55]
	v_mfma_f32_16x16x32_bf16 v[52:55], v[166:169], v[198:201], v[52:55]
	v_mfma_f32_16x16x32_bf16 v[56:59], v[154:157], v[194:197], v[56:59]
	v_mfma_f32_16x16x32_bf16 v[56:59], v[158:161], v[198:201], v[56:59]
	v_mfma_f32_16x16x32_bf16 v[40:43], v[154:157], v[202:205], v[40:43]
	v_mfma_f32_16x16x32_bf16 v[40:43], v[158:161], v[206:209], v[40:43]
	v_mfma_f32_16x16x32_bf16 v[36:39], v[162:165], v[202:205], v[36:39]
	v_mfma_f32_16x16x32_bf16 v[36:39], v[166:169], v[206:209], v[36:39]
	v_mfma_f32_16x16x32_bf16 v[16:19], v[170:173], v[202:205], v[16:19]
	v_mfma_f32_16x16x32_bf16 v[16:19], v[174:177], v[206:209], v[16:19]
	v_mfma_f32_16x16x32_bf16 v[12:15], v[178:181], v[202:205], v[12:15]
	v_mfma_f32_16x16x32_bf16 v[12:15], v[182:185], v[206:209], v[12:15]
	v_mfma_f32_16x16x32_bf16 v[4:7], v[178:181], v[210:213], v[4:7]
	v_mfma_f32_16x16x32_bf16 v[4:7], v[182:185], v[214:217], v[4:7]
	v_mfma_f32_16x16x32_bf16 v[8:11], v[170:173], v[210:213], v[8:11]
	v_mfma_f32_16x16x32_bf16 v[8:11], v[174:177], v[214:217], v[8:11]
	v_mfma_f32_16x16x32_bf16 v[20:23], v[162:165], v[210:213], v[20:23]
	v_mfma_f32_16x16x32_bf16 v[20:23], v[166:169], v[214:217], v[20:23]
	v_mfma_f32_16x16x32_bf16 v[24:27], v[154:157], v[210:213], v[24:27]
	v_mfma_f32_16x16x32_bf16 v[24:27], v[158:161], v[214:217], v[24:27]
	s_barrier
	s_add_i32 s70, s70, 2
	s_add_u32 s42, s42, 0x100
	s_addc_u32 s43, s43, 0
	s_add_u32 s31, s31, 0x100
	s_addc_u32 s41, s41, 0
	s_cmp_gt_u32 s70, 13
	s_cbranch_scc0 .LBB0_1288
	s_and_b64 vcc, exec, s[14:15]
	s_cbranch_vccz .LBB0_1291
	s_barrier

.LBB0_1415:
	ds_read_b128 v[132:135], v187
	ds_read_b128 v[136:139], v187 offset:1024
	ds_read_b128 v[140:143], v187 offset:2048
	ds_read_b128 v[144:147], v187 offset:3072
	ds_read_b128 v[148:151], v188
	ds_read_b128 v[152:155], v188 offset:1024
	ds_read_b128 v[172:175], v188 offset:2048
	ds_read_b128 v[176:179], v188 offset:3072
	s_add_u32 s0, s42, 0xfffe0080
	s_addc_u32 s50, s43, -1
	s_cmp_eq_u32 s64, 4
	s_cselect_b32 s53, s25, s50
	s_cselect_b32 s52, s31, s0
	s_cselect_b32 s51, s23, s63
	s_cselect_b32 s50, s61, s62
	s_add_i32 m0, s41, 0xc000
	ds_read_b128 v[180:183], v189
	ds_read_b128 v[192:195], v189 offset:1024
	ds_read_b128 v[196:199], v189 offset:2048
	ds_read_b128 v[200:203], v189 offset:3072
	ds_read_b128 v[204:207], v189 offset:4096
	ds_read_b128 v[208:211], v189 offset:5120
	ds_read_b128 v[212:215], v189 offset:6144
	ds_read_b128 v[216:219], v189 offset:7168
	global_load_lds_dwordx4 v164, s[42:43]
	s_add_i32 m0, s41, 0xe000
	s_nop 0
	global_load_lds_dwordx4 v166, s[42:43]
	s_waitcnt vmcnt(8)
	s_waitcnt lgkmcnt(0)
	s_barrier
	v_mfma_f32_16x16x32_bf16 v[128:131], v[132:135], v[180:183], v[128:131]
	v_mfma_f32_16x16x32_bf16 v[128:131], v[136:139], v[192:195], v[128:131]
	v_mfma_f32_16x16x32_bf16 v[124:127], v[140:143], v[180:183], v[124:127]
	v_mfma_f32_16x16x32_bf16 v[124:127], v[144:147], v[192:195], v[124:127]
	v_mfma_f32_16x16x32_bf16 v[120:123], v[148:151], v[180:183], v[120:123]
	v_mfma_f32_16x16x32_bf16 v[120:123], v[152:155], v[192:195], v[120:123]
	v_mfma_f32_16x16x32_bf16 v[116:119], v[172:175], v[180:183], v[116:119]
	v_mfma_f32_16x16x32_bf16 v[116:119], v[176:179], v[192:195], v[116:119]
	v_mfma_f32_16x16x32_bf16 v[100:103], v[172:175], v[196:199], v[100:103]
	v_mfma_f32_16x16x32_bf16 v[100:103], v[176:179], v[200:203], v[100:103]
	v_mfma_f32_16x16x32_bf16 v[104:107], v[148:151], v[196:199], v[104:107]
	v_mfma_f32_16x16x32_bf16 v[104:107], v[152:155], v[200:203], v[104:107]
	v_mfma_f32_16x16x32_bf16 v[108:111], v[140:143], v[196:199], v[108:111]
	v_mfma_f32_16x16x32_bf16 v[108:111], v[144:147], v[200:203], v[108:111]
	v_mfma_f32_16x16x32_bf16 v[112:115], v[132:135], v[196:199], v[112:115]
	v_mfma_f32_16x16x32_bf16 v[112:115], v[136:139], v[200:203], v[112:115]
	v_mfma_f32_16x16x32_bf16 v[96:99], v[132:135], v[204:207], v[96:99]
	v_mfma_f32_16x16x32_bf16 v[96:99], v[136:139], v[208:211], v[96:99]
	v_mfma_f32_16x16x32_bf16 v[92:95], v[140:143], v[204:207], v[92:95]
	v_mfma_f32_16x16x32_bf16 v[92:95], v[144:147], v[208:211], v[92:95]
	v_mfma_f32_16x16x32_bf16 v[88:91], v[148:151], v[204:207], v[88:91]
	v_mfma_f32_16x16x32_bf16 v[88:91], v[152:155], v[208:211], v[88:91]
	v_mfma_f32_16x16x32_bf16 v[84:87], v[172:175], v[204:207], v[84:87]
	v_mfma_f32_16x16x32_bf16 v[84:87], v[176:179], v[208:211], v[84:87]
	v_mfma_f32_16x16x32_bf16 v[68:71], v[172:175], v[212:215], v[68:71]
	v_mfma_f32_16x16x32_bf16 v[68:71], v[176:179], v[216:219], v[68:71]
	v_mfma_f32_16x16x32_bf16 v[72:75], v[148:151], v[212:215], v[72:75]
	v_mfma_f32_16x16x32_bf16 v[72:75], v[152:155], v[216:219], v[72:75]
	v_mfma_f32_16x16x32_bf16 v[76:79], v[140:143], v[212:215], v[76:79]
	v_mfma_f32_16x16x32_bf16 v[76:79], v[144:147], v[216:219], v[76:79]
	v_mfma_f32_16x16x32_bf16 v[80:83], v[132:135], v[212:215], v[80:83]
	v_mfma_f32_16x16x32_bf16 v[80:83], v[136:139], v[216:219], v[80:83]
	s_barrier
	s_add_i32 s0, s58, s45
	s_mov_b32 m0, s0
	ds_read_b128 v[180:183], v189 offset:16384
	ds_read_b128 v[192:195], v189 offset:17408
	ds_read_b128 v[196:199], v189 offset:18432
	ds_read_b128 v[200:203], v189 offset:19456
	ds_read_b128 v[204:207], v189 offset:20480
	ds_read_b128 v[208:211], v189 offset:21504
	ds_read_b128 v[212:215], v189 offset:22528
	ds_read_b128 v[216:219], v189 offset:23552
	global_load_lds_dwordx4 v158, s[50:51]
	s_add_i32 m0, s0, 0x2000
	s_add_u32 s66, s50, 0x20000
	s_addc_u32 s67, s51, 0
	s_add_i32 s0, s59, s45
	global_load_lds_dwordx4 v162, s[50:51]
	s_mov_b32 m0, s0
	s_nop 0
	global_load_lds_dwordx4 v158, s[66:67]
	s_add_i32 m0, s0, 0x2000
	s_nop 0
	global_load_lds_dwordx4 v162, s[66:67]
	s_mov_b32 m0, s41
	s_nop 0
	global_load_lds_dwordx4 v156, s[52:53]
	s_mov_b32 m0, s46
	s_nop 0
	global_load_lds_dwordx4 v160, s[52:53]
	s_waitcnt vmcnt(8)
	s_waitcnt lgkmcnt(0)
	s_barrier
	v_mfma_f32_16x16x32_bf16 v[64:67], v[132:135], v[180:183], v[64:67]
	v_mfma_f32_16x16x32_bf16 v[64:67], v[136:139], v[192:195], v[64:67]
	v_mfma_f32_16x16x32_bf16 v[60:63], v[140:143], v[180:183], v[60:63]
	v_mfma_f32_16x16x32_bf16 v[60:63], v[144:147], v[192:195], v[60:63]
	v_mfma_f32_16x16x32_bf16 v[56:59], v[148:151], v[180:183], v[56:59]
	v_mfma_f32_16x16x32_bf16 v[56:59], v[152:155], v[192:195], v[56:59]
	v_mfma_f32_16x16x32_bf16 v[52:55], v[172:175], v[180:183], v[52:55]
	v_mfma_f32_16x16x32_bf16 v[52:55], v[176:179], v[192:195], v[52:55]
	v_mfma_f32_16x16x32_bf16 v[36:39], v[172:175], v[196:199], v[36:39]
	v_mfma_f32_16x16x32_bf16 v[36:39], v[176:179], v[200:203], v[36:39]
	v_mfma_f32_16x16x32_bf16 v[40:43], v[148:151], v[196:199], v[40:43]
	v_mfma_f32_16x16x32_bf16 v[40:43], v[152:155], v[200:203], v[40:43]
	v_mfma_f32_16x16x32_bf16 v[44:47], v[140:143], v[196:199], v[44:47]
	v_mfma_f32_16x16x32_bf16 v[44:47], v[144:147], v[200:203], v[44:47]
	v_mfma_f32_16x16x32_bf16 v[48:51], v[132:135], v[196:199], v[48:51]
	v_mfma_f32_16x16x32_bf16 v[48:51], v[136:139], v[200:203], v[48:51]
	v_mfma_f32_16x16x32_bf16 v[32:35], v[132:135], v[204:207], v[32:35]
	v_mfma_f32_16x16x32_bf16 v[32:35], v[136:139], v[208:211], v[32:35]
	v_mfma_f32_16x16x32_bf16 v[28:31], v[140:143], v[204:207], v[28:31]
	v_mfma_f32_16x16x32_bf16 v[28:31], v[144:147], v[208:211], v[28:31]
	v_mfma_f32_16x16x32_bf16 v[24:27], v[148:151], v[204:207], v[24:27]
	v_mfma_f32_16x16x32_bf16 v[24:27], v[152:155], v[208:211], v[24:27]
	v_mfma_f32_16x16x32_bf16 v[20:23], v[172:175], v[204:207], v[20:23]
	v_mfma_f32_16x16x32_bf16 v[20:23], v[176:179], v[208:211], v[20:23]
	v_mfma_f32_16x16x32_bf16 v[4:7], v[172:175], v[212:215], v[4:7]
	v_mfma_f32_16x16x32_bf16 v[4:7], v[176:179], v[216:219], v[4:7]
	v_mfma_f32_16x16x32_bf16 v[8:11], v[148:151], v[212:215], v[8:11]
	v_mfma_f32_16x16x32_bf16 v[8:11], v[152:155], v[216:219], v[8:11]
	v_mfma_f32_16x16x32_bf16 v[12:15], v[140:143], v[212:215], v[12:15]
	v_mfma_f32_16x16x32_bf16 v[12:15], v[144:147], v[216:219], v[12:15]
	v_mfma_f32_16x16x32_bf16 v[16:19], v[132:135], v[212:215], v[16:19]
	v_mfma_f32_16x16x32_bf16 v[16:19], v[136:139], v[216:219], v[16:19]
	s_barrier
	s_add_i32 s0, 0, 0x18000
	s_add_i32 s65, 0, 0x1c000
	v_add_u32_e32 v144, s0, v3
	v_add_u32_e32 v176, s65, v3
	ds_read_b128 v[132:135], v144
	ds_read_b128 v[136:139], v144 offset:1024
	ds_read_b128 v[140:143], v144 offset:2048
	ds_read_b128 v[144:147], v144 offset:3072
	ds_read_b128 v[148:151], v176
	ds_read_b128 v[152:155], v176 offset:1024
	ds_read_b128 v[172:175], v176 offset:2048
	ds_read_b128 v[176:179], v176 offset:3072
	s_add_u32 s98, s52, 0x20000
	s_addc_u32 s99, s53, 0
	s_mov_b32 m0, s47
	ds_read_b128 v[180:183], v189 offset:32768
	ds_read_b128 v[192:195], v189 offset:33792
	ds_read_b128 v[196:199], v189 offset:34816
	ds_read_b128 v[200:203], v189 offset:35840
	ds_read_b128 v[204:207], v189 offset:36864
	ds_read_b128 v[208:211], v189 offset:37888
	ds_read_b128 v[212:215], v189 offset:38912
	ds_read_b128 v[216:219], v189 offset:39936
	global_load_lds_dwordx4 v156, s[98:99]
	s_mov_b32 m0, s48
	s_nop 0
	global_load_lds_dwordx4 v160, s[98:99]
	s_waitcnt vmcnt(8)
	s_waitcnt lgkmcnt(0)
	s_barrier
	v_mfma_f32_16x16x32_bf16 v[128:131], v[132:135], v[180:183], v[128:131]
	v_mfma_f32_16x16x32_bf16 v[128:131], v[136:139], v[192:195], v[128:131]
	v_mfma_f32_16x16x32_bf16 v[124:127], v[140:143], v[180:183], v[124:127]
	v_mfma_f32_16x16x32_bf16 v[124:127], v[144:147], v[192:195], v[124:127]
	v_mfma_f32_16x16x32_bf16 v[120:123], v[148:151], v[180:183], v[120:123]
	v_mfma_f32_16x16x32_bf16 v[120:123], v[152:155], v[192:195], v[120:123]
	v_mfma_f32_16x16x32_bf16 v[116:119], v[172:175], v[180:183], v[116:119]
	v_mfma_f32_16x16x32_bf16 v[116:119], v[176:179], v[192:195], v[116:119]
	v_mfma_f32_16x16x32_bf16 v[100:103], v[172:175], v[196:199], v[100:103]
	v_mfma_f32_16x16x32_bf16 v[100:103], v[176:179], v[200:203], v[100:103]
	v_mfma_f32_16x16x32_bf16 v[104:107], v[148:151], v[196:199], v[104:107]
	v_mfma_f32_16x16x32_bf16 v[104:107], v[152:155], v[200:203], v[104:107]
	v_mfma_f32_16x16x32_bf16 v[108:111], v[140:143], v[196:199], v[108:111]
	v_mfma_f32_16x16x32_bf16 v[108:111], v[144:147], v[200:203], v[108:111]
	v_mfma_f32_16x16x32_bf16 v[112:115], v[132:135], v[196:199], v[112:115]
	v_mfma_f32_16x16x32_bf16 v[112:115], v[136:139], v[200:203], v[112:115]
	v_mfma_f32_16x16x32_bf16 v[96:99], v[132:135], v[204:207], v[96:99]
	v_mfma_f32_16x16x32_bf16 v[96:99], v[136:139], v[208:211], v[96:99]
	v_mfma_f32_16x16x32_bf16 v[92:95], v[140:143], v[204:207], v[92:95]
	v_mfma_f32_16x16x32_bf16 v[92:95], v[144:147], v[208:211], v[92:95]
	v_mfma_f32_16x16x32_bf16 v[88:91], v[148:151], v[204:207], v[88:91]
	v_mfma_f32_16x16x32_bf16 v[88:91], v[152:155], v[208:211], v[88:91]
	v_mfma_f32_16x16x32_bf16 v[84:87], v[172:175], v[204:207], v[84:87]
	v_mfma_f32_16x16x32_bf16 v[84:87], v[176:179], v[208:211], v[84:87]
	v_mfma_f32_16x16x32_bf16 v[68:71], v[172:175], v[212:215], v[68:71]
	v_mfma_f32_16x16x32_bf16 v[68:71], v[176:179], v[216:219], v[68:71]
	v_mfma_f32_16x16x32_bf16 v[72:75], v[148:151], v[212:215], v[72:75]
	v_mfma_f32_16x16x32_bf16 v[72:75], v[152:155], v[216:219], v[72:75]
	v_mfma_f32_16x16x32_bf16 v[76:79], v[140:143], v[212:215], v[76:79]
	v_mfma_f32_16x16x32_bf16 v[76:79], v[144:147], v[216:219], v[76:79]
	v_mfma_f32_16x16x32_bf16 v[80:83], v[132:135], v[212:215], v[80:83]
	v_mfma_f32_16x16x32_bf16 v[80:83], v[136:139], v[216:219], v[80:83]
	s_barrier
	s_add_i32 s0, s0, s45
	s_add_i32 m0, s0, 0xffffff80
	ds_read_b128 v[180:183], v189 offset:49152
	ds_read_b128 v[192:195], v189 offset:50176
	ds_read_b128 v[196:199], v189 offset:51200
	ds_read_b128 v[200:203], v189 offset:52224
	ds_read_b128 v[204:207], v189 offset:53248
	ds_read_b128 v[208:211], v189 offset:54272
	ds_read_b128 v[212:215], v189 offset:55296
	ds_read_b128 v[216:219], v189 offset:56320
	global_load_lds_dwordx4 v158, s[50:51] offset:128
	s_add_i32 m0, s0, 0x1f80
	s_add_i32 s0, s65, s45
	global_load_lds_dwordx4 v162, s[50:51] offset:128
	s_add_u32 s50, s50, 0x20080
	s_addc_u32 s51, s51, 0
	s_mov_b32 m0, s0
	s_nop 0
	global_load_lds_dwordx4 v158, s[50:51]
	s_add_i32 m0, s0, 0x2000
	s_nop 0
	global_load_lds_dwordx4 v162, s[50:51]
	s_add_i32 m0, s56, 0xffffff80
	s_nop 0
	global_load_lds_dwordx4 v156, s[52:53] offset:128
	s_add_i32 m0, s57, 0xffffff80
	s_nop 0
	global_load_lds_dwordx4 v160, s[52:53] offset:128
	s_waitcnt vmcnt(8)
	s_waitcnt lgkmcnt(0)
	s_barrier
	v_mfma_f32_16x16x32_bf16 v[64:67], v[132:135], v[180:183], v[64:67]
	v_mfma_f32_16x16x32_bf16 v[64:67], v[136:139], v[192:195], v[64:67]
	v_mfma_f32_16x16x32_bf16 v[60:63], v[140:143], v[180:183], v[60:63]
	v_mfma_f32_16x16x32_bf16 v[60:63], v[144:147], v[192:195], v[60:63]
	v_mfma_f32_16x16x32_bf16 v[56:59], v[148:151], v[180:183], v[56:59]
	v_mfma_f32_16x16x32_bf16 v[56:59], v[152:155], v[192:195], v[56:59]
	v_mfma_f32_16x16x32_bf16 v[52:55], v[172:175], v[180:183], v[52:55]
	v_mfma_f32_16x16x32_bf16 v[52:55], v[176:179], v[192:195], v[52:55]
	v_mfma_f32_16x16x32_bf16 v[36:39], v[172:175], v[196:199], v[36:39]
	v_mfma_f32_16x16x32_bf16 v[36:39], v[176:179], v[200:203], v[36:39]
	v_mfma_f32_16x16x32_bf16 v[40:43], v[148:151], v[196:199], v[40:43]
	v_mfma_f32_16x16x32_bf16 v[40:43], v[152:155], v[200:203], v[40:43]
	v_mfma_f32_16x16x32_bf16 v[44:47], v[140:143], v[196:199], v[44:47]
	v_mfma_f32_16x16x32_bf16 v[44:47], v[144:147], v[200:203], v[44:47]
	v_mfma_f32_16x16x32_bf16 v[48:51], v[132:135], v[196:199], v[48:51]
	v_mfma_f32_16x16x32_bf16 v[48:51], v[136:139], v[200:203], v[48:51]
	v_mfma_f32_16x16x32_bf16 v[32:35], v[132:135], v[204:207], v[32:35]
	v_mfma_f32_16x16x32_bf16 v[32:35], v[136:139], v[208:211], v[32:35]
	v_mfma_f32_16x16x32_bf16 v[28:31], v[140:143], v[204:207], v[28:31]
	v_mfma_f32_16x16x32_bf16 v[28:31], v[144:147], v[208:211], v[28:31]
	v_mfma_f32_16x16x32_bf16 v[24:27], v[148:151], v[204:207], v[24:27]
	v_mfma_f32_16x16x32_bf16 v[24:27], v[152:155], v[208:211], v[24:27]
	v_mfma_f32_16x16x32_bf16 v[20:23], v[172:175], v[204:207], v[20:23]
	v_mfma_f32_16x16x32_bf16 v[20:23], v[176:179], v[208:211], v[20:23]
	v_mfma_f32_16x16x32_bf16 v[4:7], v[172:175], v[212:215], v[4:7]
	v_mfma_f32_16x16x32_bf16 v[4:7], v[176:179], v[216:219], v[4:7]
	v_mfma_f32_16x16x32_bf16 v[8:11], v[148:151], v[212:215], v[8:11]
	v_mfma_f32_16x16x32_bf16 v[8:11], v[152:155], v[216:219], v[8:11]
	v_mfma_f32_16x16x32_bf16 v[12:15], v[140:143], v[212:215], v[12:15]
	v_mfma_f32_16x16x32_bf16 v[12:15], v[144:147], v[216:219], v[12:15]
	v_mfma_f32_16x16x32_bf16 v[16:19], v[132:135], v[212:215], v[16:19]
	v_mfma_f32_16x16x32_bf16 v[16:19], v[136:139], v[216:219], v[16:19]
	s_barrier
	s_add_i32 s64, s64, 2
	s_add_u32 s42, s42, 0x100
	s_addc_u32 s43, s43, 0
	s_add_u32 s62, s62, 0x100
	s_addc_u32 s63, s63, 0
	s_cmp_gt_u32 s64, 5
	s_cbranch_scc0 .LBB0_1415
	s_and_b64 vcc, exec, s[16:17]
	s_cbranch_vccz .LBB0_1418
	s_barrier

.LBB0_1503:
	ds_read_b128 v[132:135], v159
	ds_read_b128 v[164:167], v159 offset:1024
	ds_read_b128 v[168:171], v159 offset:2048
	ds_read_b128 v[172:175], v159 offset:3072
	ds_read_b128 v[176:179], v160
	ds_read_b128 v[180:183], v160 offset:1024
	ds_read_b128 v[184:187], v160 offset:2048
	ds_read_b128 v[188:191], v160 offset:3072
	s_add_u32 s0, s54, 0xfff00080
	s_addc_u32 s56, s55, -1
	s_cmp_eq_u32 s75, 60
	s_cselect_b32 s59, s31, s56
	s_cselect_b32 s58, s71, s0
	s_cselect_b32 s57, s29, s74
	s_cselect_b32 s56, s72, s73
	s_add_i32 m0, s48, 0xc000
	ds_read_b128 v[192:195], v161
	ds_read_b128 v[196:199], v161 offset:1024
	ds_read_b128 v[200:203], v161 offset:2048
	ds_read_b128 v[204:207], v161 offset:3072
	ds_read_b128 v[208:211], v161 offset:4096
	ds_read_b128 v[212:215], v161 offset:5120
	ds_read_b128 v[216:219], v161 offset:6144
	ds_read_b128 v[220:223], v161 offset:7168
	global_load_lds_dwordx4 v148, s[54:55]
	s_add_i32 m0, s48, 0xe000
	s_nop 0
	global_load_lds_dwordx4 v150, s[54:55]
	s_waitcnt vmcnt(8)
	s_waitcnt lgkmcnt(0)
	s_barrier
	v_mfma_f32_16x16x32_bf16 v[136:139], v[132:135], v[192:195], v[136:139]
	v_mfma_f32_16x16x32_bf16 v[136:139], v[164:167], v[196:199], v[136:139]
	v_mfma_f32_16x16x32_bf16 v[128:131], v[168:171], v[192:195], v[128:131]
	v_mfma_f32_16x16x32_bf16 v[128:131], v[172:175], v[196:199], v[128:131]
	v_mfma_f32_16x16x32_bf16 v[124:127], v[176:179], v[192:195], v[124:127]
	v_mfma_f32_16x16x32_bf16 v[124:127], v[180:183], v[196:199], v[124:127]
	v_mfma_f32_16x16x32_bf16 v[120:123], v[184:187], v[192:195], v[120:123]
	v_mfma_f32_16x16x32_bf16 v[120:123], v[188:191], v[196:199], v[120:123]
	v_mfma_f32_16x16x32_bf16 v[104:107], v[184:187], v[200:203], v[104:107]
	v_mfma_f32_16x16x32_bf16 v[104:107], v[188:191], v[204:207], v[104:107]
	v_mfma_f32_16x16x32_bf16 v[108:111], v[176:179], v[200:203], v[108:111]
	v_mfma_f32_16x16x32_bf16 v[108:111], v[180:183], v[204:207], v[108:111]
	v_mfma_f32_16x16x32_bf16 v[112:115], v[168:171], v[200:203], v[112:115]
	v_mfma_f32_16x16x32_bf16 v[112:115], v[172:175], v[204:207], v[112:115]
	v_mfma_f32_16x16x32_bf16 v[116:119], v[132:135], v[200:203], v[116:119]
	v_mfma_f32_16x16x32_bf16 v[116:119], v[164:167], v[204:207], v[116:119]
	v_mfma_f32_16x16x32_bf16 v[100:103], v[132:135], v[208:211], v[100:103]
	v_mfma_f32_16x16x32_bf16 v[100:103], v[164:167], v[212:215], v[100:103]
	v_mfma_f32_16x16x32_bf16 v[96:99], v[168:171], v[208:211], v[96:99]
	v_mfma_f32_16x16x32_bf16 v[96:99], v[172:175], v[212:215], v[96:99]
	v_mfma_f32_16x16x32_bf16 v[92:95], v[176:179], v[208:211], v[92:95]
	v_mfma_f32_16x16x32_bf16 v[92:95], v[180:183], v[212:215], v[92:95]
	v_mfma_f32_16x16x32_bf16 v[88:91], v[184:187], v[208:211], v[88:91]
	v_mfma_f32_16x16x32_bf16 v[88:91], v[188:191], v[212:215], v[88:91]
	v_mfma_f32_16x16x32_bf16 v[72:75], v[184:187], v[216:219], v[72:75]
	v_mfma_f32_16x16x32_bf16 v[72:75], v[188:191], v[220:223], v[72:75]
	v_mfma_f32_16x16x32_bf16 v[76:79], v[176:179], v[216:219], v[76:79]
	v_mfma_f32_16x16x32_bf16 v[76:79], v[180:183], v[220:223], v[76:79]
	v_mfma_f32_16x16x32_bf16 v[80:83], v[168:171], v[216:219], v[80:83]
	v_mfma_f32_16x16x32_bf16 v[80:83], v[172:175], v[220:223], v[80:83]
	v_mfma_f32_16x16x32_bf16 v[84:87], v[132:135], v[216:219], v[84:87]
	v_mfma_f32_16x16x32_bf16 v[84:87], v[164:167], v[220:223], v[84:87]
	s_barrier
	s_add_i32 s0, s65, s47
	s_mov_b32 m0, s0
	ds_read_b128 v[192:195], v161 offset:16384
	ds_read_b128 v[196:199], v161 offset:17408
	ds_read_b128 v[200:203], v161 offset:18432
	ds_read_b128 v[204:207], v161 offset:19456
	ds_read_b128 v[208:211], v161 offset:20480
	ds_read_b128 v[212:215], v161 offset:21504
	ds_read_b128 v[216:219], v161 offset:22528
	ds_read_b128 v[220:223], v161 offset:23552
	global_load_lds_dwordx4 v142, s[56:57]
	s_add_i32 m0, s0, 0x2000
	s_add_u32 s76, s56, 0x100000
	s_addc_u32 s77, s57, 0
	s_add_i32 s0, s66, s47
	global_load_lds_dwordx4 v146, s[56:57]
	s_mov_b32 m0, s0
	s_nop 0
	global_load_lds_dwordx4 v142, s[76:77]
	s_add_i32 m0, s0, 0x2000
	s_nop 0
	global_load_lds_dwordx4 v146, s[76:77]
	s_mov_b32 m0, s48
	s_nop 0
	global_load_lds_dwordx4 v140, s[58:59]
	s_mov_b32 m0, s49
	s_nop 0
	global_load_lds_dwordx4 v144, s[58:59]
	s_waitcnt vmcnt(8)
	s_waitcnt lgkmcnt(0)
	s_barrier
	v_mfma_f32_16x16x32_bf16 v[68:71], v[132:135], v[192:195], v[68:71]
	v_mfma_f32_16x16x32_bf16 v[68:71], v[164:167], v[196:199], v[68:71]
	v_mfma_f32_16x16x32_bf16 v[64:67], v[168:171], v[192:195], v[64:67]
	v_mfma_f32_16x16x32_bf16 v[64:67], v[172:175], v[196:199], v[64:67]
	v_mfma_f32_16x16x32_bf16 v[60:63], v[176:179], v[192:195], v[60:63]
	v_mfma_f32_16x16x32_bf16 v[60:63], v[180:183], v[196:199], v[60:63]
	v_mfma_f32_16x16x32_bf16 v[56:59], v[184:187], v[192:195], v[56:59]
	v_mfma_f32_16x16x32_bf16 v[56:59], v[188:191], v[196:199], v[56:59]
	v_mfma_f32_16x16x32_bf16 v[40:43], v[184:187], v[200:203], v[40:43]
	v_mfma_f32_16x16x32_bf16 v[40:43], v[188:191], v[204:207], v[40:43]
	v_mfma_f32_16x16x32_bf16 v[44:47], v[176:179], v[200:203], v[44:47]
	v_mfma_f32_16x16x32_bf16 v[44:47], v[180:183], v[204:207], v[44:47]
	v_mfma_f32_16x16x32_bf16 v[48:51], v[168:171], v[200:203], v[48:51]
	v_mfma_f32_16x16x32_bf16 v[48:51], v[172:175], v[204:207], v[48:51]
	v_mfma_f32_16x16x32_bf16 v[52:55], v[132:135], v[200:203], v[52:55]
	v_mfma_f32_16x16x32_bf16 v[52:55], v[164:167], v[204:207], v[52:55]
	v_mfma_f32_16x16x32_bf16 v[36:39], v[132:135], v[208:211], v[36:39]
	v_mfma_f32_16x16x32_bf16 v[36:39], v[164:167], v[212:215], v[36:39]
	v_mfma_f32_16x16x32_bf16 v[32:35], v[168:171], v[208:211], v[32:35]
	v_mfma_f32_16x16x32_bf16 v[32:35], v[172:175], v[212:215], v[32:35]
	v_mfma_f32_16x16x32_bf16 v[28:31], v[176:179], v[208:211], v[28:31]
	v_mfma_f32_16x16x32_bf16 v[28:31], v[180:183], v[212:215], v[28:31]
	v_mfma_f32_16x16x32_bf16 v[24:27], v[184:187], v[208:211], v[24:27]
	v_mfma_f32_16x16x32_bf16 v[24:27], v[188:191], v[212:215], v[24:27]
	v_mfma_f32_16x16x32_bf16 v[8:11], v[184:187], v[216:219], v[8:11]
	v_mfma_f32_16x16x32_bf16 v[8:11], v[188:191], v[220:223], v[8:11]
	v_mfma_f32_16x16x32_bf16 v[12:15], v[176:179], v[216:219], v[12:15]
	v_mfma_f32_16x16x32_bf16 v[12:15], v[180:183], v[220:223], v[12:15]
	v_mfma_f32_16x16x32_bf16 v[16:19], v[168:171], v[216:219], v[16:19]
	v_mfma_f32_16x16x32_bf16 v[16:19], v[172:175], v[220:223], v[16:19]
	v_mfma_f32_16x16x32_bf16 v[20:23], v[132:135], v[216:219], v[20:23]
	v_mfma_f32_16x16x32_bf16 v[20:23], v[164:167], v[220:223], v[20:23]
	s_barrier
	s_add_i32 s0, 0, 0x18000
	s_add_i32 s76, 0, 0x1c000
	v_add_u32_e32 v172, s0, v156
	v_add_u32_e32 v188, s76, v156
	ds_read_b128 v[132:135], v172
	ds_read_b128 v[164:167], v172 offset:1024
	ds_read_b128 v[168:171], v172 offset:2048
	ds_read_b128 v[172:175], v172 offset:3072
	ds_read_b128 v[176:179], v188
	ds_read_b128 v[180:183], v188 offset:1024
	ds_read_b128 v[184:187], v188 offset:2048
	ds_read_b128 v[188:191], v188 offset:3072
	s_add_u32 s98, s58, 0x100000
	s_addc_u32 s99, s59, 0
	s_mov_b32 m0, s51
	ds_read_b128 v[192:195], v161 offset:32768
	ds_read_b128 v[196:199], v161 offset:33792
	ds_read_b128 v[200:203], v161 offset:34816
	ds_read_b128 v[204:207], v161 offset:35840
	ds_read_b128 v[208:211], v161 offset:36864
	ds_read_b128 v[212:215], v161 offset:37888
	ds_read_b128 v[216:219], v161 offset:38912
	ds_read_b128 v[220:223], v161 offset:39936
	global_load_lds_dwordx4 v140, s[98:99]
	s_mov_b32 m0, s53
	s_nop 0
	global_load_lds_dwordx4 v144, s[98:99]
	s_waitcnt vmcnt(8)
	s_waitcnt lgkmcnt(0)
	s_barrier
	v_mfma_f32_16x16x32_bf16 v[136:139], v[132:135], v[192:195], v[136:139]
	v_mfma_f32_16x16x32_bf16 v[136:139], v[164:167], v[196:199], v[136:139]
	v_mfma_f32_16x16x32_bf16 v[128:131], v[168:171], v[192:195], v[128:131]
	v_mfma_f32_16x16x32_bf16 v[128:131], v[172:175], v[196:199], v[128:131]
	v_mfma_f32_16x16x32_bf16 v[124:127], v[176:179], v[192:195], v[124:127]
	v_mfma_f32_16x16x32_bf16 v[124:127], v[180:183], v[196:199], v[124:127]
	v_mfma_f32_16x16x32_bf16 v[120:123], v[184:187], v[192:195], v[120:123]
	v_mfma_f32_16x16x32_bf16 v[120:123], v[188:191], v[196:199], v[120:123]
	v_mfma_f32_16x16x32_bf16 v[104:107], v[184:187], v[200:203], v[104:107]
	v_mfma_f32_16x16x32_bf16 v[104:107], v[188:191], v[204:207], v[104:107]
	v_mfma_f32_16x16x32_bf16 v[108:111], v[176:179], v[200:203], v[108:111]
	v_mfma_f32_16x16x32_bf16 v[108:111], v[180:183], v[204:207], v[108:111]
	v_mfma_f32_16x16x32_bf16 v[112:115], v[168:171], v[200:203], v[112:115]
	v_mfma_f32_16x16x32_bf16 v[112:115], v[172:175], v[204:207], v[112:115]
	v_mfma_f32_16x16x32_bf16 v[116:119], v[132:135], v[200:203], v[116:119]
	v_mfma_f32_16x16x32_bf16 v[116:119], v[164:167], v[204:207], v[116:119]
	v_mfma_f32_16x16x32_bf16 v[100:103], v[132:135], v[208:211], v[100:103]
	v_mfma_f32_16x16x32_bf16 v[100:103], v[164:167], v[212:215], v[100:103]
	v_mfma_f32_16x16x32_bf16 v[96:99], v[168:171], v[208:211], v[96:99]
	v_mfma_f32_16x16x32_bf16 v[96:99], v[172:175], v[212:215], v[96:99]
	v_mfma_f32_16x16x32_bf16 v[92:95], v[176:179], v[208:211], v[92:95]
	v_mfma_f32_16x16x32_bf16 v[92:95], v[180:183], v[212:215], v[92:95]
	v_mfma_f32_16x16x32_bf16 v[88:91], v[184:187], v[208:211], v[88:91]
	v_mfma_f32_16x16x32_bf16 v[88:91], v[188:191], v[212:215], v[88:91]
	v_mfma_f32_16x16x32_bf16 v[72:75], v[184:187], v[216:219], v[72:75]
	v_mfma_f32_16x16x32_bf16 v[72:75], v[188:191], v[220:223], v[72:75]
	v_mfma_f32_16x16x32_bf16 v[76:79], v[176:179], v[216:219], v[76:79]
	v_mfma_f32_16x16x32_bf16 v[76:79], v[180:183], v[220:223], v[76:79]
	v_mfma_f32_16x16x32_bf16 v[80:83], v[168:171], v[216:219], v[80:83]
	v_mfma_f32_16x16x32_bf16 v[80:83], v[172:175], v[220:223], v[80:83]
	v_mfma_f32_16x16x32_bf16 v[84:87], v[132:135], v[216:219], v[84:87]
	v_mfma_f32_16x16x32_bf16 v[84:87], v[164:167], v[220:223], v[84:87]
	s_barrier
	s_add_i32 s0, s0, s47
	s_add_i32 m0, s0, 0xffffff80
	ds_read_b128 v[192:195], v161 offset:49152
	ds_read_b128 v[196:199], v161 offset:50176
	ds_read_b128 v[200:203], v161 offset:51200
	ds_read_b128 v[204:207], v161 offset:52224
	ds_read_b128 v[208:211], v161 offset:53248
	ds_read_b128 v[212:215], v161 offset:54272
	ds_read_b128 v[216:219], v161 offset:55296
	ds_read_b128 v[220:223], v161 offset:56320
	global_load_lds_dwordx4 v142, s[56:57] offset:128
	s_add_i32 m0, s0, 0x1f80
	s_add_i32 s0, s76, s47
	global_load_lds_dwordx4 v146, s[56:57] offset:128
	s_add_u32 s56, s56, 0x100080
	s_addc_u32 s57, s57, 0
	s_mov_b32 m0, s0
	s_nop 0
	global_load_lds_dwordx4 v142, s[56:57]
	s_add_i32 m0, s0, 0x2000
	s_nop 0
	global_load_lds_dwordx4 v146, s[56:57]
	s_add_i32 m0, s62, 0xffffff80
	s_nop 0
	global_load_lds_dwordx4 v140, s[58:59] offset:128
	s_add_i32 m0, s63, 0xffffff80
	s_nop 0
	global_load_lds_dwordx4 v144, s[58:59] offset:128
	s_waitcnt vmcnt(8)
	s_waitcnt lgkmcnt(0)
	s_barrier
	v_mfma_f32_16x16x32_bf16 v[68:71], v[132:135], v[192:195], v[68:71]
	v_mfma_f32_16x16x32_bf16 v[68:71], v[164:167], v[196:199], v[68:71]
	v_mfma_f32_16x16x32_bf16 v[64:67], v[168:171], v[192:195], v[64:67]
	v_mfma_f32_16x16x32_bf16 v[64:67], v[172:175], v[196:199], v[64:67]
	v_mfma_f32_16x16x32_bf16 v[60:63], v[176:179], v[192:195], v[60:63]
	v_mfma_f32_16x16x32_bf16 v[60:63], v[180:183], v[196:199], v[60:63]
	v_mfma_f32_16x16x32_bf16 v[56:59], v[184:187], v[192:195], v[56:59]
	v_mfma_f32_16x16x32_bf16 v[56:59], v[188:191], v[196:199], v[56:59]
	v_mfma_f32_16x16x32_bf16 v[40:43], v[184:187], v[200:203], v[40:43]
	v_mfma_f32_16x16x32_bf16 v[40:43], v[188:191], v[204:207], v[40:43]
	v_mfma_f32_16x16x32_bf16 v[44:47], v[176:179], v[200:203], v[44:47]
	v_mfma_f32_16x16x32_bf16 v[44:47], v[180:183], v[204:207], v[44:47]
	v_mfma_f32_16x16x32_bf16 v[48:51], v[168:171], v[200:203], v[48:51]
	v_mfma_f32_16x16x32_bf16 v[48:51], v[172:175], v[204:207], v[48:51]
	v_mfma_f32_16x16x32_bf16 v[52:55], v[132:135], v[200:203], v[52:55]
	v_mfma_f32_16x16x32_bf16 v[52:55], v[164:167], v[204:207], v[52:55]
	v_mfma_f32_16x16x32_bf16 v[36:39], v[132:135], v[208:211], v[36:39]
	v_mfma_f32_16x16x32_bf16 v[36:39], v[164:167], v[212:215], v[36:39]
	v_mfma_f32_16x16x32_bf16 v[32:35], v[168:171], v[208:211], v[32:35]
	v_mfma_f32_16x16x32_bf16 v[32:35], v[172:175], v[212:215], v[32:35]
	v_mfma_f32_16x16x32_bf16 v[28:31], v[176:179], v[208:211], v[28:31]
	v_mfma_f32_16x16x32_bf16 v[28:31], v[180:183], v[212:215], v[28:31]
	v_mfma_f32_16x16x32_bf16 v[24:27], v[184:187], v[208:211], v[24:27]
	v_mfma_f32_16x16x32_bf16 v[24:27], v[188:191], v[212:215], v[24:27]
	v_mfma_f32_16x16x32_bf16 v[8:11], v[184:187], v[216:219], v[8:11]
	v_mfma_f32_16x16x32_bf16 v[8:11], v[188:191], v[220:223], v[8:11]
	v_mfma_f32_16x16x32_bf16 v[12:15], v[176:179], v[216:219], v[12:15]
	v_mfma_f32_16x16x32_bf16 v[12:15], v[180:183], v[220:223], v[12:15]
	v_mfma_f32_16x16x32_bf16 v[16:19], v[168:171], v[216:219], v[16:19]
	v_mfma_f32_16x16x32_bf16 v[16:19], v[172:175], v[220:223], v[16:19]
	v_mfma_f32_16x16x32_bf16 v[20:23], v[132:135], v[216:219], v[20:23]
	v_mfma_f32_16x16x32_bf16 v[20:23], v[164:167], v[220:223], v[20:23]
	s_barrier
	s_add_i32 s75, s75, 2
	s_add_u32 s54, s54, 0x100
	s_addc_u32 s55, s55, 0
	s_add_u32 s73, s73, 0x100
	s_addc_u32 s74, s74, 0
	s_cmp_gt_u32 s75, 61
	s_cbranch_scc0 .LBB0_1503
	s_and_b64 vcc, exec, s[26:27]
	s_cbranch_vccz .LBB0_1506
	s_barrier

.LBB0_1672:
	ds_read_b128 v[132:135], v193
	ds_read_b128 v[136:139], v193 offset:1024
	ds_read_b128 v[140:143], v193 offset:2048
	ds_read_b128 v[144:147], v193 offset:3072
	ds_read_b128 v[148:151], v194
	ds_read_b128 v[152:155], v194 offset:1024
	ds_read_b128 v[172:175], v194 offset:2048
	ds_read_b128 v[176:179], v194 offset:3072
	s_add_u32 s0, s30, 0xffd50080
	s_addc_u32 s42, s31, -1
	s_cmpk_eq_i32 s66, 0xa8
	s_cselect_b32 s51, s7, s42
	s_cselect_b32 s50, s6, s0
	s_cselect_b32 s43, s29, s65
	s_cselect_b32 s42, s28, s64
	s_add_i32 m0, s46, 0xc000
	ds_read_b128 v[180:183], v195
	ds_read_b128 v[198:201], v195 offset:1024
	ds_read_b128 v[202:205], v195 offset:2048
	ds_read_b128 v[206:209], v195 offset:3072
	ds_read_b128 v[210:213], v195 offset:4096
	ds_read_b128 v[214:217], v195 offset:5120
	ds_read_b128 v[218:221], v195 offset:6144
	ds_read_b128 v[222:225], v195 offset:7168
	global_load_lds_dwordx4 v164, s[30:31]
	s_add_i32 m0, s46, 0xe000
	s_nop 0
	global_load_lds_dwordx4 v166, s[30:31]
	s_waitcnt vmcnt(8)
	s_waitcnt lgkmcnt(0)
	s_barrier
	v_mfma_f32_16x16x32_bf16 v[128:131], v[132:135], v[180:183], v[128:131]
	v_mfma_f32_16x16x32_bf16 v[128:131], v[136:139], v[198:201], v[128:131]
	v_mfma_f32_16x16x32_bf16 v[124:127], v[140:143], v[180:183], v[124:127]
	v_mfma_f32_16x16x32_bf16 v[124:127], v[144:147], v[198:201], v[124:127]
	v_mfma_f32_16x16x32_bf16 v[120:123], v[148:151], v[180:183], v[120:123]
	v_mfma_f32_16x16x32_bf16 v[120:123], v[152:155], v[198:201], v[120:123]
	v_mfma_f32_16x16x32_bf16 v[116:119], v[172:175], v[180:183], v[116:119]
	v_mfma_f32_16x16x32_bf16 v[116:119], v[176:179], v[198:201], v[116:119]
	v_mfma_f32_16x16x32_bf16 v[100:103], v[172:175], v[202:205], v[100:103]
	v_mfma_f32_16x16x32_bf16 v[100:103], v[176:179], v[206:209], v[100:103]
	v_mfma_f32_16x16x32_bf16 v[104:107], v[148:151], v[202:205], v[104:107]
	v_mfma_f32_16x16x32_bf16 v[104:107], v[152:155], v[206:209], v[104:107]
	v_mfma_f32_16x16x32_bf16 v[108:111], v[140:143], v[202:205], v[108:111]
	v_mfma_f32_16x16x32_bf16 v[108:111], v[144:147], v[206:209], v[108:111]
	v_mfma_f32_16x16x32_bf16 v[112:115], v[132:135], v[202:205], v[112:115]
	v_mfma_f32_16x16x32_bf16 v[112:115], v[136:139], v[206:209], v[112:115]
	v_mfma_f32_16x16x32_bf16 v[96:99], v[132:135], v[210:213], v[96:99]
	v_mfma_f32_16x16x32_bf16 v[96:99], v[136:139], v[214:217], v[96:99]
	v_mfma_f32_16x16x32_bf16 v[92:95], v[140:143], v[210:213], v[92:95]
	v_mfma_f32_16x16x32_bf16 v[92:95], v[144:147], v[214:217], v[92:95]
	v_mfma_f32_16x16x32_bf16 v[88:91], v[148:151], v[210:213], v[88:91]
	v_mfma_f32_16x16x32_bf16 v[88:91], v[152:155], v[214:217], v[88:91]
	v_mfma_f32_16x16x32_bf16 v[84:87], v[172:175], v[210:213], v[84:87]
	v_mfma_f32_16x16x32_bf16 v[84:87], v[176:179], v[214:217], v[84:87]
	v_mfma_f32_16x16x32_bf16 v[68:71], v[172:175], v[218:221], v[68:71]
	v_mfma_f32_16x16x32_bf16 v[68:71], v[176:179], v[222:225], v[68:71]
	v_mfma_f32_16x16x32_bf16 v[72:75], v[148:151], v[218:221], v[72:75]
	v_mfma_f32_16x16x32_bf16 v[72:75], v[152:155], v[222:225], v[72:75]
	v_mfma_f32_16x16x32_bf16 v[76:79], v[140:143], v[218:221], v[76:79]
	v_mfma_f32_16x16x32_bf16 v[76:79], v[144:147], v[222:225], v[76:79]
	v_mfma_f32_16x16x32_bf16 v[80:83], v[132:135], v[218:221], v[80:83]
	v_mfma_f32_16x16x32_bf16 v[80:83], v[136:139], v[222:225], v[80:83]
	s_barrier
	s_add_i32 s0, s57, s45
	s_mov_b32 m0, s0
	ds_read_b128 v[180:183], v195 offset:16384
	ds_read_b128 v[198:201], v195 offset:17408
	ds_read_b128 v[202:205], v195 offset:18432
	ds_read_b128 v[206:209], v195 offset:19456
	ds_read_b128 v[210:213], v195 offset:20480
	ds_read_b128 v[214:217], v195 offset:21504
	ds_read_b128 v[218:221], v195 offset:22528
	ds_read_b128 v[222:225], v195 offset:23552
	global_load_lds_dwordx4 v158, s[42:43]
	s_add_i32 m0, s0, 0x2000
	s_add_u32 s70, s42, 0x2b0000
	s_addc_u32 s71, s43, 0
	s_add_i32 s0, s58, s45
	global_load_lds_dwordx4 v162, s[42:43]
	s_mov_b32 m0, s0
	s_nop 0
	global_load_lds_dwordx4 v158, s[70:71]
	s_add_i32 m0, s0, 0x2000
	s_nop 0
	global_load_lds_dwordx4 v162, s[70:71]
	s_mov_b32 m0, s46
	s_nop 0
	global_load_lds_dwordx4 v156, s[50:51]
	s_mov_b32 m0, s47
	s_nop 0
	global_load_lds_dwordx4 v160, s[50:51]
	s_waitcnt vmcnt(8)
	s_waitcnt lgkmcnt(0)
	s_barrier
	v_mfma_f32_16x16x32_bf16 v[64:67], v[132:135], v[180:183], v[64:67]
	v_mfma_f32_16x16x32_bf16 v[64:67], v[136:139], v[198:201], v[64:67]
	v_mfma_f32_16x16x32_bf16 v[60:63], v[140:143], v[180:183], v[60:63]
	v_mfma_f32_16x16x32_bf16 v[60:63], v[144:147], v[198:201], v[60:63]
	v_mfma_f32_16x16x32_bf16 v[56:59], v[148:151], v[180:183], v[56:59]
	v_mfma_f32_16x16x32_bf16 v[56:59], v[152:155], v[198:201], v[56:59]
	v_mfma_f32_16x16x32_bf16 v[52:55], v[172:175], v[180:183], v[52:55]
	v_mfma_f32_16x16x32_bf16 v[52:55], v[176:179], v[198:201], v[52:55]
	v_mfma_f32_16x16x32_bf16 v[36:39], v[172:175], v[202:205], v[36:39]
	v_mfma_f32_16x16x32_bf16 v[36:39], v[176:179], v[206:209], v[36:39]
	v_mfma_f32_16x16x32_bf16 v[40:43], v[148:151], v[202:205], v[40:43]
	v_mfma_f32_16x16x32_bf16 v[40:43], v[152:155], v[206:209], v[40:43]
	v_mfma_f32_16x16x32_bf16 v[44:47], v[140:143], v[202:205], v[44:47]
	v_mfma_f32_16x16x32_bf16 v[44:47], v[144:147], v[206:209], v[44:47]
	v_mfma_f32_16x16x32_bf16 v[48:51], v[132:135], v[202:205], v[48:51]
	v_mfma_f32_16x16x32_bf16 v[48:51], v[136:139], v[206:209], v[48:51]
	v_mfma_f32_16x16x32_bf16 v[32:35], v[132:135], v[210:213], v[32:35]
	v_mfma_f32_16x16x32_bf16 v[32:35], v[136:139], v[214:217], v[32:35]
	v_mfma_f32_16x16x32_bf16 v[28:31], v[140:143], v[210:213], v[28:31]
	v_mfma_f32_16x16x32_bf16 v[28:31], v[144:147], v[214:217], v[28:31]
	v_mfma_f32_16x16x32_bf16 v[24:27], v[148:151], v[210:213], v[24:27]
	v_mfma_f32_16x16x32_bf16 v[24:27], v[152:155], v[214:217], v[24:27]
	v_mfma_f32_16x16x32_bf16 v[20:23], v[172:175], v[210:213], v[20:23]
	v_mfma_f32_16x16x32_bf16 v[20:23], v[176:179], v[214:217], v[20:23]
	v_mfma_f32_16x16x32_bf16 v[4:7], v[172:175], v[218:221], v[4:7]
	v_mfma_f32_16x16x32_bf16 v[4:7], v[176:179], v[222:225], v[4:7]
	v_mfma_f32_16x16x32_bf16 v[8:11], v[148:151], v[218:221], v[8:11]
	v_mfma_f32_16x16x32_bf16 v[8:11], v[152:155], v[222:225], v[8:11]
	v_mfma_f32_16x16x32_bf16 v[12:15], v[140:143], v[218:221], v[12:15]
	v_mfma_f32_16x16x32_bf16 v[12:15], v[144:147], v[222:225], v[12:15]
	v_mfma_f32_16x16x32_bf16 v[16:19], v[132:135], v[218:221], v[16:19]
	v_mfma_f32_16x16x32_bf16 v[16:19], v[136:139], v[222:225], v[16:19]
	s_barrier
	s_add_i32 s0, 0, 0x18000
	s_add_i32 s67, 0, 0x1c000
	v_add_u32_e32 v144, s0, v191
	v_add_u32_e32 v176, s67, v191
	ds_read_b128 v[132:135], v144
	ds_read_b128 v[136:139], v144 offset:1024
	ds_read_b128 v[140:143], v144 offset:2048
	ds_read_b128 v[144:147], v144 offset:3072
	ds_read_b128 v[148:151], v176
	ds_read_b128 v[152:155], v176 offset:1024
	ds_read_b128 v[172:175], v176 offset:2048
	ds_read_b128 v[176:179], v176 offset:3072
	s_add_u32 s98, s50, 0x2b0000
	s_addc_u32 s99, s51, 0
	s_mov_b32 m0, s48
	ds_read_b128 v[180:183], v195 offset:32768
	ds_read_b128 v[198:201], v195 offset:33792
	ds_read_b128 v[202:205], v195 offset:34816
	ds_read_b128 v[206:209], v195 offset:35840
	ds_read_b128 v[210:213], v195 offset:36864
	ds_read_b128 v[214:217], v195 offset:37888
	ds_read_b128 v[218:221], v195 offset:38912
	ds_read_b128 v[222:225], v195 offset:39936
	global_load_lds_dwordx4 v156, s[98:99]
	s_mov_b32 m0, s49
	s_nop 0
	global_load_lds_dwordx4 v160, s[98:99]
	s_waitcnt vmcnt(8)
	s_waitcnt lgkmcnt(0)
	s_barrier
	v_mfma_f32_16x16x32_bf16 v[128:131], v[132:135], v[180:183], v[128:131]
	v_mfma_f32_16x16x32_bf16 v[128:131], v[136:139], v[198:201], v[128:131]
	v_mfma_f32_16x16x32_bf16 v[124:127], v[140:143], v[180:183], v[124:127]
	v_mfma_f32_16x16x32_bf16 v[124:127], v[144:147], v[198:201], v[124:127]
	v_mfma_f32_16x16x32_bf16 v[120:123], v[148:151], v[180:183], v[120:123]
	v_mfma_f32_16x16x32_bf16 v[120:123], v[152:155], v[198:201], v[120:123]
	v_mfma_f32_16x16x32_bf16 v[116:119], v[172:175], v[180:183], v[116:119]
	v_mfma_f32_16x16x32_bf16 v[116:119], v[176:179], v[198:201], v[116:119]
	v_mfma_f32_16x16x32_bf16 v[100:103], v[172:175], v[202:205], v[100:103]
	v_mfma_f32_16x16x32_bf16 v[100:103], v[176:179], v[206:209], v[100:103]
	v_mfma_f32_16x16x32_bf16 v[104:107], v[148:151], v[202:205], v[104:107]
	v_mfma_f32_16x16x32_bf16 v[104:107], v[152:155], v[206:209], v[104:107]
	v_mfma_f32_16x16x32_bf16 v[108:111], v[140:143], v[202:205], v[108:111]
	v_mfma_f32_16x16x32_bf16 v[108:111], v[144:147], v[206:209], v[108:111]
	v_mfma_f32_16x16x32_bf16 v[112:115], v[132:135], v[202:205], v[112:115]
	v_mfma_f32_16x16x32_bf16 v[112:115], v[136:139], v[206:209], v[112:115]
	v_mfma_f32_16x16x32_bf16 v[96:99], v[132:135], v[210:213], v[96:99]
	v_mfma_f32_16x16x32_bf16 v[96:99], v[136:139], v[214:217], v[96:99]
	v_mfma_f32_16x16x32_bf16 v[92:95], v[140:143], v[210:213], v[92:95]
	v_mfma_f32_16x16x32_bf16 v[92:95], v[144:147], v[214:217], v[92:95]
	v_mfma_f32_16x16x32_bf16 v[88:91], v[148:151], v[210:213], v[88:91]
	v_mfma_f32_16x16x32_bf16 v[88:91], v[152:155], v[214:217], v[88:91]
	v_mfma_f32_16x16x32_bf16 v[84:87], v[172:175], v[210:213], v[84:87]
	v_mfma_f32_16x16x32_bf16 v[84:87], v[176:179], v[214:217], v[84:87]
	v_mfma_f32_16x16x32_bf16 v[68:71], v[172:175], v[218:221], v[68:71]
	v_mfma_f32_16x16x32_bf16 v[68:71], v[176:179], v[222:225], v[68:71]
	v_mfma_f32_16x16x32_bf16 v[72:75], v[148:151], v[218:221], v[72:75]
	v_mfma_f32_16x16x32_bf16 v[72:75], v[152:155], v[222:225], v[72:75]
	v_mfma_f32_16x16x32_bf16 v[76:79], v[140:143], v[218:221], v[76:79]
	v_mfma_f32_16x16x32_bf16 v[76:79], v[144:147], v[222:225], v[76:79]
	v_mfma_f32_16x16x32_bf16 v[80:83], v[132:135], v[218:221], v[80:83]
	v_mfma_f32_16x16x32_bf16 v[80:83], v[136:139], v[222:225], v[80:83]
	s_barrier
	s_add_i32 s0, s0, s45
	s_add_i32 m0, s0, 0xffffff80
	ds_read_b128 v[180:183], v195 offset:49152
	ds_read_b128 v[198:201], v195 offset:50176
	ds_read_b128 v[202:205], v195 offset:51200
	ds_read_b128 v[206:209], v195 offset:52224
	ds_read_b128 v[210:213], v195 offset:53248
	ds_read_b128 v[214:217], v195 offset:54272
	ds_read_b128 v[218:221], v195 offset:55296
	ds_read_b128 v[222:225], v195 offset:56320
	global_load_lds_dwordx4 v158, s[42:43] offset:128
	s_add_i32 m0, s0, 0x1f80
	s_add_i32 s0, s67, s45
	global_load_lds_dwordx4 v162, s[42:43] offset:128
	s_add_u32 s42, s42, 0x2b0080
	s_addc_u32 s43, s43, 0
	s_mov_b32 m0, s0
	s_nop 0
	global_load_lds_dwordx4 v158, s[42:43]
	s_add_i32 m0, s0, 0x2000
	s_nop 0
	global_load_lds_dwordx4 v162, s[42:43]
	s_add_i32 m0, s55, 0xffffff80
	s_nop 0
	global_load_lds_dwordx4 v156, s[50:51] offset:128
	s_add_i32 m0, s56, 0xffffff80
	s_nop 0
	global_load_lds_dwordx4 v160, s[50:51] offset:128
	s_waitcnt vmcnt(8)
	s_waitcnt lgkmcnt(0)
	s_barrier
	v_mfma_f32_16x16x32_bf16 v[64:67], v[132:135], v[180:183], v[64:67]
	v_mfma_f32_16x16x32_bf16 v[64:67], v[136:139], v[198:201], v[64:67]
	v_mfma_f32_16x16x32_bf16 v[60:63], v[140:143], v[180:183], v[60:63]
	v_mfma_f32_16x16x32_bf16 v[60:63], v[144:147], v[198:201], v[60:63]
	v_mfma_f32_16x16x32_bf16 v[56:59], v[148:151], v[180:183], v[56:59]
	v_mfma_f32_16x16x32_bf16 v[56:59], v[152:155], v[198:201], v[56:59]
	v_mfma_f32_16x16x32_bf16 v[52:55], v[172:175], v[180:183], v[52:55]
	v_mfma_f32_16x16x32_bf16 v[52:55], v[176:179], v[198:201], v[52:55]
	v_mfma_f32_16x16x32_bf16 v[36:39], v[172:175], v[202:205], v[36:39]
	v_mfma_f32_16x16x32_bf16 v[36:39], v[176:179], v[206:209], v[36:39]
	v_mfma_f32_16x16x32_bf16 v[40:43], v[148:151], v[202:205], v[40:43]
	v_mfma_f32_16x16x32_bf16 v[40:43], v[152:155], v[206:209], v[40:43]
	v_mfma_f32_16x16x32_bf16 v[44:47], v[140:143], v[202:205], v[44:47]
	v_mfma_f32_16x16x32_bf16 v[44:47], v[144:147], v[206:209], v[44:47]
	v_mfma_f32_16x16x32_bf16 v[48:51], v[132:135], v[202:205], v[48:51]
	v_mfma_f32_16x16x32_bf16 v[48:51], v[136:139], v[206:209], v[48:51]
	v_mfma_f32_16x16x32_bf16 v[32:35], v[132:135], v[210:213], v[32:35]
	v_mfma_f32_16x16x32_bf16 v[32:35], v[136:139], v[214:217], v[32:35]
	v_mfma_f32_16x16x32_bf16 v[28:31], v[140:143], v[210:213], v[28:31]
	v_mfma_f32_16x16x32_bf16 v[28:31], v[144:147], v[214:217], v[28:31]
	v_mfma_f32_16x16x32_bf16 v[24:27], v[148:151], v[210:213], v[24:27]
	v_mfma_f32_16x16x32_bf16 v[24:27], v[152:155], v[214:217], v[24:27]
	v_mfma_f32_16x16x32_bf16 v[20:23], v[172:175], v[210:213], v[20:23]
	v_mfma_f32_16x16x32_bf16 v[20:23], v[176:179], v[214:217], v[20:23]
	v_mfma_f32_16x16x32_bf16 v[4:7], v[172:175], v[218:221], v[4:7]
	v_mfma_f32_16x16x32_bf16 v[4:7], v[176:179], v[222:225], v[4:7]
	v_mfma_f32_16x16x32_bf16 v[8:11], v[148:151], v[218:221], v[8:11]
	v_mfma_f32_16x16x32_bf16 v[8:11], v[152:155], v[222:225], v[8:11]
	v_mfma_f32_16x16x32_bf16 v[12:15], v[140:143], v[218:221], v[12:15]
	v_mfma_f32_16x16x32_bf16 v[12:15], v[144:147], v[222:225], v[12:15]
	v_mfma_f32_16x16x32_bf16 v[16:19], v[132:135], v[218:221], v[16:19]
	v_mfma_f32_16x16x32_bf16 v[16:19], v[136:139], v[222:225], v[16:19]
	s_barrier
	s_add_i32 s66, s66, 2
	s_add_u32 s30, s30, 0x100
	s_addc_u32 s31, s31, 0
	s_add_u32 s64, s64, 0x100
	s_addc_u32 s65, s65, 0
	s_cmpk_gt_u32 s66, 0xa9
	s_cbranch_scc0 .LBB0_1672
	s_and_b64 vcc, exec, s[24:25]
	s_cbranch_vccz .LBB0_1675
	s_barrier

.LBB0_1703:
	ds_read_b128 v[136:139], v196
	ds_read_b128 v[140:143], v196 offset:1024
	ds_read_b128 v[144:147], v196 offset:2048
	ds_read_b128 v[148:151], v196 offset:3072
	ds_read_b128 v[152:155], v197
	ds_read_b128 v[176:179], v197 offset:1024
	ds_read_b128 v[180:183], v197 offset:2048
	ds_read_b128 v[184:187], v197 offset:3072
	s_add_u32 s8, s6, 0x100
	s_addc_u32 s9, s7, 0
	s_add_u32 s0, s65, s6
	s_addc_u32 s40, s66, s7
	s_cmpk_eq_i32 s67, 0xa8
	s_cselect_b32 s43, s50, s40
	s_cselect_b32 s40, 0, s8
	s_cselect_b32 s42, s51, s0
	s_cselect_b32 s0, 0, s9
	s_add_u32 s40, s16, s40
	s_addc_u32 s41, s17, s0
	s_mov_b32 m0, s58
	v_lshl_add_u64 v[226:227], v[132:133], 0, s[6:7]
	ds_read_b128 v[188:191], v198
	ds_read_b128 v[192:195], v198 offset:1024
	ds_read_b128 v[202:205], v198 offset:2048
	ds_read_b128 v[206:209], v198 offset:3072
	ds_read_b128 v[210:213], v198 offset:4096
	ds_read_b128 v[214:217], v198 offset:5120
	ds_read_b128 v[218:221], v198 offset:6144
	ds_read_b128 v[222:225], v198 offset:7168
	global_load_lds_dwordx4 v[226:227], off
	v_lshl_add_u64 v[226:227], v[134:135], 0, s[6:7]
	s_mov_b32 m0, s59
	s_nop 0
	global_load_lds_dwordx4 v[226:227], off
	s_waitcnt vmcnt(8)
	s_waitcnt lgkmcnt(0)
	s_barrier
	v_mfma_f32_16x16x32_bf16 v[128:131], v[136:139], v[188:191], v[128:131]
	v_mfma_f32_16x16x32_bf16 v[128:131], v[140:143], v[192:195], v[128:131]
	v_mfma_f32_16x16x32_bf16 v[124:127], v[144:147], v[188:191], v[124:127]
	v_mfma_f32_16x16x32_bf16 v[124:127], v[148:151], v[192:195], v[124:127]
	v_mfma_f32_16x16x32_bf16 v[120:123], v[152:155], v[188:191], v[120:123]
	v_mfma_f32_16x16x32_bf16 v[120:123], v[176:179], v[192:195], v[120:123]
	v_mfma_f32_16x16x32_bf16 v[116:119], v[180:183], v[188:191], v[116:119]
	v_mfma_f32_16x16x32_bf16 v[116:119], v[184:187], v[192:195], v[116:119]
	v_mfma_f32_16x16x32_bf16 v[100:103], v[180:183], v[202:205], v[100:103]
	v_mfma_f32_16x16x32_bf16 v[100:103], v[184:187], v[206:209], v[100:103]
	v_mfma_f32_16x16x32_bf16 v[104:107], v[152:155], v[202:205], v[104:107]
	v_mfma_f32_16x16x32_bf16 v[104:107], v[176:179], v[206:209], v[104:107]
	v_mfma_f32_16x16x32_bf16 v[108:111], v[144:147], v[202:205], v[108:111]
	v_mfma_f32_16x16x32_bf16 v[108:111], v[148:151], v[206:209], v[108:111]
	v_mfma_f32_16x16x32_bf16 v[112:115], v[136:139], v[202:205], v[112:115]
	v_mfma_f32_16x16x32_bf16 v[112:115], v[140:143], v[206:209], v[112:115]
	v_mfma_f32_16x16x32_bf16 v[96:99], v[136:139], v[210:213], v[96:99]
	v_mfma_f32_16x16x32_bf16 v[96:99], v[140:143], v[214:217], v[96:99]
	v_mfma_f32_16x16x32_bf16 v[92:95], v[144:147], v[210:213], v[92:95]
	v_mfma_f32_16x16x32_bf16 v[92:95], v[148:151], v[214:217], v[92:95]
	v_mfma_f32_16x16x32_bf16 v[88:91], v[152:155], v[210:213], v[88:91]
	v_mfma_f32_16x16x32_bf16 v[88:91], v[176:179], v[214:217], v[88:91]
	v_mfma_f32_16x16x32_bf16 v[84:87], v[180:183], v[210:213], v[84:87]
	v_mfma_f32_16x16x32_bf16 v[84:87], v[184:187], v[214:217], v[84:87]
	v_mfma_f32_16x16x32_bf16 v[68:71], v[180:183], v[218:221], v[68:71]
	v_mfma_f32_16x16x32_bf16 v[68:71], v[184:187], v[222:225], v[68:71]
	v_mfma_f32_16x16x32_bf16 v[72:75], v[152:155], v[218:221], v[72:75]
	v_mfma_f32_16x16x32_bf16 v[72:75], v[176:179], v[222:225], v[72:75]
	v_mfma_f32_16x16x32_bf16 v[76:79], v[144:147], v[218:221], v[76:79]
	v_mfma_f32_16x16x32_bf16 v[76:79], v[148:151], v[222:225], v[76:79]
	v_mfma_f32_16x16x32_bf16 v[80:83], v[136:139], v[218:221], v[80:83]
	v_mfma_f32_16x16x32_bf16 v[80:83], v[140:143], v[222:225], v[80:83]
	s_barrier
	s_mov_b32 m0, s60
	v_lshl_add_u64 v[226:227], s[40:41], 0, v[158:159]
	s_add_u32 s6, s40, 0x2b0000
	ds_read_b128 v[188:191], v198 offset:16384
	ds_read_b128 v[192:195], v198 offset:17408
	ds_read_b128 v[202:205], v198 offset:18432
	ds_read_b128 v[206:209], v198 offset:19456
	ds_read_b128 v[210:213], v198 offset:20480
	ds_read_b128 v[214:217], v198 offset:21504
	ds_read_b128 v[218:221], v198 offset:22528
	ds_read_b128 v[222:225], v198 offset:23552
	global_load_lds_dwordx4 v[226:227], off
	v_lshl_add_u64 v[228:229], s[40:41], 0, v[162:163]
	s_mov_b32 m0, s61
	s_addc_u32 s7, s41, 0
	global_load_lds_dwordx4 v[228:229], off
	v_lshl_add_u64 v[230:231], s[6:7], 0, v[158:159]
	s_mov_b32 m0, s62
	v_lshl_add_u64 v[232:233], s[42:43], 0, v[160:161]
	global_load_lds_dwordx4 v[230:231], off
	v_lshl_add_u64 v[230:231], s[6:7], 0, v[162:163]
	s_mov_b32 m0, s63
	s_nop 0
	global_load_lds_dwordx4 v[230:231], off
	v_lshl_add_u64 v[230:231], s[42:43], 0, v[156:157]
	s_mov_b32 m0, s46
	s_nop 0
	global_load_lds_dwordx4 v[230:231], off
	s_mov_b32 m0, s47
	s_nop 0
	global_load_lds_dwordx4 v[232:233], off
	s_waitcnt vmcnt(8)
	s_waitcnt lgkmcnt(0)
	s_barrier
	v_mfma_f32_16x16x32_bf16 v[64:67], v[136:139], v[188:191], v[64:67]
	v_mfma_f32_16x16x32_bf16 v[64:67], v[140:143], v[192:195], v[64:67]
	v_mfma_f32_16x16x32_bf16 v[60:63], v[144:147], v[188:191], v[60:63]
	v_mfma_f32_16x16x32_bf16 v[60:63], v[148:151], v[192:195], v[60:63]
	v_mfma_f32_16x16x32_bf16 v[56:59], v[152:155], v[188:191], v[56:59]
	v_mfma_f32_16x16x32_bf16 v[56:59], v[176:179], v[192:195], v[56:59]
	v_mfma_f32_16x16x32_bf16 v[52:55], v[180:183], v[188:191], v[52:55]
	v_mfma_f32_16x16x32_bf16 v[52:55], v[184:187], v[192:195], v[52:55]
	v_mfma_f32_16x16x32_bf16 v[36:39], v[180:183], v[202:205], v[36:39]
	v_mfma_f32_16x16x32_bf16 v[36:39], v[184:187], v[206:209], v[36:39]
	v_mfma_f32_16x16x32_bf16 v[40:43], v[152:155], v[202:205], v[40:43]
	v_mfma_f32_16x16x32_bf16 v[40:43], v[176:179], v[206:209], v[40:43]
	v_mfma_f32_16x16x32_bf16 v[44:47], v[144:147], v[202:205], v[44:47]
	v_mfma_f32_16x16x32_bf16 v[44:47], v[148:151], v[206:209], v[44:47]
	v_mfma_f32_16x16x32_bf16 v[48:51], v[136:139], v[202:205], v[48:51]
	v_mfma_f32_16x16x32_bf16 v[48:51], v[140:143], v[206:209], v[48:51]
	v_mfma_f32_16x16x32_bf16 v[32:35], v[136:139], v[210:213], v[32:35]
	v_mfma_f32_16x16x32_bf16 v[32:35], v[140:143], v[214:217], v[32:35]
	v_mfma_f32_16x16x32_bf16 v[28:31], v[144:147], v[210:213], v[28:31]
	v_mfma_f32_16x16x32_bf16 v[28:31], v[148:151], v[214:217], v[28:31]
	v_mfma_f32_16x16x32_bf16 v[24:27], v[152:155], v[210:213], v[24:27]
	v_mfma_f32_16x16x32_bf16 v[24:27], v[176:179], v[214:217], v[24:27]
	v_mfma_f32_16x16x32_bf16 v[20:23], v[180:183], v[210:213], v[20:23]
	v_mfma_f32_16x16x32_bf16 v[20:23], v[184:187], v[214:217], v[20:23]
	v_mfma_f32_16x16x32_bf16 v[4:7], v[180:183], v[218:221], v[4:7]
	v_mfma_f32_16x16x32_bf16 v[4:7], v[184:187], v[222:225], v[4:7]
	v_mfma_f32_16x16x32_bf16 v[8:11], v[152:155], v[218:221], v[8:11]
	v_mfma_f32_16x16x32_bf16 v[8:11], v[176:179], v[222:225], v[8:11]
	v_mfma_f32_16x16x32_bf16 v[12:15], v[144:147], v[218:221], v[12:15]
	v_mfma_f32_16x16x32_bf16 v[12:15], v[148:151], v[222:225], v[12:15]
	v_mfma_f32_16x16x32_bf16 v[16:19], v[136:139], v[218:221], v[16:19]
	v_mfma_f32_16x16x32_bf16 v[16:19], v[140:143], v[222:225], v[16:19]
	s_barrier
	s_add_i32 s0, 0, 0x18000
	s_add_i32 s68, 0, 0x1c000
	v_add_u32_e32 v148, s0, v3
	v_add_u32_e32 v170, s68, v3
	ds_read_b128 v[136:139], v148
	ds_read_b128 v[140:143], v148 offset:1024
	ds_read_b128 v[144:147], v148 offset:2048
	ds_read_b128 v[148:151], v148 offset:3072
	ds_read_b128 v[152:155], v170
	ds_read_b128 v[176:179], v170 offset:1024
	ds_read_b128 v[180:183], v170 offset:2048
	ds_read_b128 v[184:187], v170 offset:3072
	s_add_u32 s6, s42, 0x2b0000
	s_addc_u32 s7, s43, 0
	s_mov_b32 m0, s48
	v_lshl_add_u64 v[234:235], s[6:7], 0, v[156:157]
	ds_read_b128 v[188:191], v198 offset:32768
	ds_read_b128 v[192:195], v198 offset:33792
	ds_read_b128 v[202:205], v198 offset:34816
	ds_read_b128 v[206:209], v198 offset:35840
	ds_read_b128 v[210:213], v198 offset:36864
	ds_read_b128 v[214:217], v198 offset:37888
	ds_read_b128 v[218:221], v198 offset:38912
	ds_read_b128 v[222:225], v198 offset:39936
	global_load_lds_dwordx4 v[234:235], off
	v_lshl_add_u64 v[234:235], s[6:7], 0, v[160:161]
	s_mov_b32 m0, s49
	s_nop 0
	global_load_lds_dwordx4 v[234:235], off
	s_waitcnt vmcnt(8)
	s_waitcnt lgkmcnt(0)
	s_barrier
	v_mfma_f32_16x16x32_bf16 v[128:131], v[136:139], v[188:191], v[128:131]
	v_mfma_f32_16x16x32_bf16 v[128:131], v[140:143], v[192:195], v[128:131]
	v_mfma_f32_16x16x32_bf16 v[124:127], v[144:147], v[188:191], v[124:127]
	v_mfma_f32_16x16x32_bf16 v[124:127], v[148:151], v[192:195], v[124:127]
	v_mfma_f32_16x16x32_bf16 v[120:123], v[152:155], v[188:191], v[120:123]
	v_mfma_f32_16x16x32_bf16 v[120:123], v[176:179], v[192:195], v[120:123]
	v_mfma_f32_16x16x32_bf16 v[116:119], v[180:183], v[188:191], v[116:119]
	v_mfma_f32_16x16x32_bf16 v[116:119], v[184:187], v[192:195], v[116:119]
	v_mfma_f32_16x16x32_bf16 v[100:103], v[180:183], v[202:205], v[100:103]
	v_mfma_f32_16x16x32_bf16 v[100:103], v[184:187], v[206:209], v[100:103]
	v_mfma_f32_16x16x32_bf16 v[104:107], v[152:155], v[202:205], v[104:107]
	v_mfma_f32_16x16x32_bf16 v[104:107], v[176:179], v[206:209], v[104:107]
	v_mfma_f32_16x16x32_bf16 v[108:111], v[144:147], v[202:205], v[108:111]
	v_mfma_f32_16x16x32_bf16 v[108:111], v[148:151], v[206:209], v[108:111]
	v_mfma_f32_16x16x32_bf16 v[112:115], v[136:139], v[202:205], v[112:115]
	v_mfma_f32_16x16x32_bf16 v[112:115], v[140:143], v[206:209], v[112:115]
	v_mfma_f32_16x16x32_bf16 v[96:99], v[136:139], v[210:213], v[96:99]
	v_mfma_f32_16x16x32_bf16 v[96:99], v[140:143], v[214:217], v[96:99]
	v_mfma_f32_16x16x32_bf16 v[92:95], v[144:147], v[210:213], v[92:95]
	v_mfma_f32_16x16x32_bf16 v[92:95], v[148:151], v[214:217], v[92:95]
	v_mfma_f32_16x16x32_bf16 v[88:91], v[152:155], v[210:213], v[88:91]
	v_mfma_f32_16x16x32_bf16 v[88:91], v[176:179], v[214:217], v[88:91]
	v_mfma_f32_16x16x32_bf16 v[84:87], v[180:183], v[210:213], v[84:87]
	v_mfma_f32_16x16x32_bf16 v[84:87], v[184:187], v[214:217], v[84:87]
	v_mfma_f32_16x16x32_bf16 v[68:71], v[180:183], v[218:221], v[68:71]
	v_mfma_f32_16x16x32_bf16 v[68:71], v[184:187], v[222:225], v[68:71]
	v_mfma_f32_16x16x32_bf16 v[72:75], v[152:155], v[218:221], v[72:75]
	v_mfma_f32_16x16x32_bf16 v[72:75], v[176:179], v[222:225], v[72:75]
	v_mfma_f32_16x16x32_bf16 v[76:79], v[144:147], v[218:221], v[76:79]
	v_mfma_f32_16x16x32_bf16 v[76:79], v[148:151], v[222:225], v[76:79]
	v_mfma_f32_16x16x32_bf16 v[80:83], v[136:139], v[218:221], v[80:83]
	v_mfma_f32_16x16x32_bf16 v[80:83], v[140:143], v[222:225], v[80:83]
	s_barrier
	s_add_i32 s0, s0, s45
	v_lshl_add_u64 v[226:227], v[226:227], 0, s[28:29]
	s_mov_b32 m0, s0
	ds_read_b128 v[188:191], v198 offset:49152
	ds_read_b128 v[192:195], v198 offset:50176
	ds_read_b128 v[202:205], v198 offset:51200
	ds_read_b128 v[206:209], v198 offset:52224
	ds_read_b128 v[210:213], v198 offset:53248
	ds_read_b128 v[214:217], v198 offset:54272
	ds_read_b128 v[218:221], v198 offset:55296
	ds_read_b128 v[222:225], v198 offset:56320
	global_load_lds_dwordx4 v[226:227], off
	s_add_i32 m0, s0, 0x2000
	s_add_u32 s6, s40, 0x2b0080
	v_lshl_add_u64 v[226:227], v[228:229], 0, s[28:29]
	s_addc_u32 s7, s41, 0
	s_add_i32 s0, s68, s45
	global_load_lds_dwordx4 v[226:227], off
	v_lshl_add_u64 v[226:227], s[6:7], 0, v[158:159]
	s_mov_b32 m0, s0
	s_nop 0
	global_load_lds_dwordx4 v[226:227], off
	v_lshl_add_u64 v[226:227], s[6:7], 0, v[162:163]
	s_add_i32 m0, s0, 0x2000
	s_nop 0
	global_load_lds_dwordx4 v[226:227], off
	v_lshl_add_u64 v[226:227], v[230:231], 0, s[28:29]
	s_mov_b32 m0, s54
	s_nop 0
	global_load_lds_dwordx4 v[226:227], off
	v_lshl_add_u64 v[226:227], v[232:233], 0, s[28:29]
	s_mov_b32 m0, s55
	s_nop 0
	global_load_lds_dwordx4 v[226:227], off
	s_waitcnt vmcnt(8)
	s_waitcnt lgkmcnt(0)
	s_barrier
	v_mfma_f32_16x16x32_bf16 v[64:67], v[136:139], v[188:191], v[64:67]
	v_mfma_f32_16x16x32_bf16 v[64:67], v[140:143], v[192:195], v[64:67]
	v_mfma_f32_16x16x32_bf16 v[60:63], v[144:147], v[188:191], v[60:63]
	v_mfma_f32_16x16x32_bf16 v[60:63], v[148:151], v[192:195], v[60:63]
	v_mfma_f32_16x16x32_bf16 v[56:59], v[152:155], v[188:191], v[56:59]
	v_mfma_f32_16x16x32_bf16 v[56:59], v[176:179], v[192:195], v[56:59]
	v_mfma_f32_16x16x32_bf16 v[52:55], v[180:183], v[188:191], v[52:55]
	v_mfma_f32_16x16x32_bf16 v[52:55], v[184:187], v[192:195], v[52:55]
	v_mfma_f32_16x16x32_bf16 v[36:39], v[180:183], v[202:205], v[36:39]
	v_mfma_f32_16x16x32_bf16 v[36:39], v[184:187], v[206:209], v[36:39]
	v_mfma_f32_16x16x32_bf16 v[40:43], v[152:155], v[202:205], v[40:43]
	v_mfma_f32_16x16x32_bf16 v[40:43], v[176:179], v[206:209], v[40:43]
	v_mfma_f32_16x16x32_bf16 v[44:47], v[144:147], v[202:205], v[44:47]
	v_mfma_f32_16x16x32_bf16 v[44:47], v[148:151], v[206:209], v[44:47]
	v_mfma_f32_16x16x32_bf16 v[48:51], v[136:139], v[202:205], v[48:51]
	v_mfma_f32_16x16x32_bf16 v[48:51], v[140:143], v[206:209], v[48:51]
	v_mfma_f32_16x16x32_bf16 v[32:35], v[136:139], v[210:213], v[32:35]
	v_mfma_f32_16x16x32_bf16 v[32:35], v[140:143], v[214:217], v[32:35]
	v_mfma_f32_16x16x32_bf16 v[28:31], v[144:147], v[210:213], v[28:31]
	v_mfma_f32_16x16x32_bf16 v[28:31], v[148:151], v[214:217], v[28:31]
	v_mfma_f32_16x16x32_bf16 v[24:27], v[152:155], v[210:213], v[24:27]
	v_mfma_f32_16x16x32_bf16 v[24:27], v[176:179], v[214:217], v[24:27]
	v_mfma_f32_16x16x32_bf16 v[20:23], v[180:183], v[210:213], v[20:23]
	v_mfma_f32_16x16x32_bf16 v[20:23], v[184:187], v[214:217], v[20:23]
	v_mfma_f32_16x16x32_bf16 v[4:7], v[180:183], v[218:221], v[4:7]
	v_mfma_f32_16x16x32_bf16 v[4:7], v[184:187], v[222:225], v[4:7]
	v_mfma_f32_16x16x32_bf16 v[8:11], v[152:155], v[218:221], v[8:11]
	v_mfma_f32_16x16x32_bf16 v[8:11], v[176:179], v[222:225], v[8:11]
	v_mfma_f32_16x16x32_bf16 v[12:15], v[144:147], v[218:221], v[12:15]
	v_mfma_f32_16x16x32_bf16 v[12:15], v[148:151], v[222:225], v[12:15]
	v_mfma_f32_16x16x32_bf16 v[16:19], v[136:139], v[218:221], v[16:19]
	v_mfma_f32_16x16x32_bf16 v[16:19], v[140:143], v[222:225], v[16:19]
	s_barrier
	s_add_i32 s67, s67, 2
	s_cmpk_gt_u32 s67, 0xa9
	s_mov_b64 s[6:7], s[8:9]
	s_cbranch_scc0 .LBB0_1703
	s_and_b64 vcc, exec, s[30:31]
	s_cbranch_vccz .LBB0_1706
	s_barrier
